# all 8 GEMM K-loops: next-tile global loads issued inside the MFMA gaps (v_lshl_add_u64 + scalar offsets, no vcc carries) instead of a 46-instruction block before the MFMA phase
# speedup vs baseline: 1.0490x; 1.0211x over previous
; DI unsigned swz(int row, int chunk) { return (unsigned)row * 128u + (unsigned)((chunk ^ ((row >> 1) & 7)) << 4); }
; #define MFMA32(a, b, c) __builtin_amdgcn_mfma_f32_32x32x16_bf16((a), (b), (c), 0, 0, 0)
;     ...
;         for (int kt = 0; kt < nk; ++kt) {
; #pragma unroll
;             for (int i = 0; i < 4; ++i) *(u32x4*)(lds + swz(lr + 32 * i, lc)) = ra[i];
; #pragma unroll
;             for (int i = 0; i < 8; ++i) *(u32x4*)(lds + 16384 + swz(lr + 32 * i, lc)) = rb[i];
;             __syncthreads();
;             if (kt + 1 < nk) {
; #pragma unroll
;                 for (int i = 0; i < 4; ++i) ra[i] = *(const u32x4*)((Au + (size_t)(32 * i) * lda + (kt + 1) * 64) + voA);
; #pragma unroll
;                 for (int i = 0; i < 8; ++i) rb[i] = *(const u32x4*)((Bu + (size_t)(32 * i) * ldb + (kt + 1) * 64) + voB);
;             }
;             __builtin_amdgcn_s_setprio(1);
; #pragma unroll 2
;             for (int ks = 0; ks < 4; ++ks) {
;                 bf16x8 af[2], bfr[4];
;                 const unsigned xo = (c0 ^ (unsigned)(2 * ks)) << 4;
; #pragma unroll
;                 for (int i = 0; i < 2; ++i) af[i] = *(const bf16x8*)(lds + (roA + xo) + i * 4096);
; #pragma unroll
;                 for (int j = 0; j < 4; ++j) bfr[j] = *(const bf16x8*)(lds + (roB + xo) + j * 4096);
; #pragma unroll
;                 for (int i = 0; i < 2; ++i)
; #pragma unroll
;                     for (int j = 0; j < 4; ++j) acc[i][j] = MFMA32(af[i], bfr[j], acc[i][j]);
;             }
;             __builtin_amdgcn_s_setprio(0);
;             __syncthreads();
.LBB0_141:
	s_mov_b32 s7, s5
	s_add_i32 s5, s5, 1
	s_cmp_lg_u32 s7, 15
	s_waitcnt vmcnt(9)
	ds_write_b128 v192, v[134:137]
	ds_write_b128 v192, v[130:133] offset:4096
	ds_write_b128 v192, v[138:141] offset:8192
	s_waitcnt vmcnt(7)
	ds_write_b128 v192, v[142:145] offset:12288
	ds_write_b128 v192, v[146:149] offset:16384
	s_waitcnt vmcnt(6)
	ds_write_b128 v192, v[150:153] offset:20480
	s_waitcnt vmcnt(5)
	ds_write_b128 v192, v[154:157] offset:24576
	s_waitcnt vmcnt(4)
	ds_write_b128 v192, v[158:161] offset:28672
	s_waitcnt vmcnt(3)
	ds_write_b128 v192, v[162:165] offset:32768
	s_waitcnt vmcnt(2)
	ds_write_b128 v192, v[166:169] offset:36864
	s_waitcnt vmcnt(1)
	ds_write_b128 v192, v[170:173] offset:40960
	s_waitcnt vmcnt(0)
	ds_write_b128 v192, v[174:177] offset:45056
	s_waitcnt lgkmcnt(0)
	s_barrier
	s_cbranch_scc0 .LBB0_143
	s_lshl_b32 s22, s5, 7
	s_mov_b32 s23, 0
	s_setprio 1
	v_xor_b32_e32 v0, 0, v187
	v_add_u32_e32 v195, v188, v0
	v_add_u32_e32 v0, v189, v0
	ds_read_b128 v[196:199], v195
	ds_read_b128 v[200:203], v0 offset:16384
	ds_read_b128 v[204:207], v195 offset:4096
	ds_read_b128 v[208:211], v0 offset:20480
	ds_read_b128 v[212:215], v0 offset:24576
	ds_read_b128 v[218:221], v0 offset:28672
	s_waitcnt lgkmcnt(4)
	v_mfma_f32_32x32x16_bf16 v[114:129], v[196:199], v[200:203], v[114:129]
	v_lshl_add_u64 v[222:223], v[182:183], 0, s[22:23]
	global_load_dwordx4 v[134:137], v[222:223], off
	s_add_u32 s22, s22, 0x10000
	s_mov_b32 s8, 32
	v_xor_b32_e32 v0, s8, v187
	v_add_u32_e32 v195, v188, v0
	v_add_u32_e32 v0, v189, v0
	s_waitcnt lgkmcnt(2)
	v_mfma_f32_32x32x16_bf16 v[82:97], v[196:199], v[208:211], v[82:97]
	v_lshl_add_u64 v[224:225], v[182:183], 0, s[22:23]
	global_load_dwordx4 v[130:133], v[224:225], off
	s_add_u32 s22, s22, 0x10000
	s_waitcnt lgkmcnt(1)
	v_mfma_f32_32x32x16_bf16 v[98:113], v[196:199], v[212:215], v[98:113]
	v_lshl_add_u64 v[226:227], v[182:183], 0, s[22:23]
	global_load_dwordx4 v[138:141], v[226:227], off
	s_add_u32 s22, s22, 0x10000
	s_waitcnt lgkmcnt(0)
	v_mfma_f32_32x32x16_bf16 v[66:81], v[196:199], v[218:221], v[66:81]
	v_lshl_add_u64 v[222:223], v[182:183], 0, s[22:23]
	global_load_dwordx4 v[142:145], v[222:223], off
	s_sub_u32 s22, s22, 0x30000
	v_mfma_f32_32x32x16_bf16 v[50:65], v[204:207], v[200:203], v[50:65]
	v_lshl_add_u64 v[224:225], v[184:185], 0, s[22:23]
	global_load_dwordx4 v[146:149], v[224:225], off
	s_add_u32 s22, s22, 0x10000
	v_mfma_f32_32x32x16_bf16 v[34:49], v[204:207], v[208:211], v[34:49]
	v_lshl_add_u64 v[226:227], v[184:185], 0, s[22:23]
	global_load_dwordx4 v[150:153], v[226:227], off
	s_add_u32 s22, s22, 0x10000
	v_mfma_f32_32x32x16_bf16 v[18:33], v[204:207], v[212:215], v[18:33]
	v_lshl_add_u64 v[222:223], v[184:185], 0, s[22:23]
	global_load_dwordx4 v[154:157], v[222:223], off
	s_add_u32 s22, s22, 0x10000
	v_mfma_f32_32x32x16_bf16 v[2:17], v[204:207], v[218:221], v[2:17]
	v_lshl_add_u64 v[224:225], v[184:185], 0, s[22:23]
	global_load_dwordx4 v[158:161], v[224:225], off
	s_add_u32 s22, s22, 0x10000
	ds_read_b128 v[196:199], v195
	ds_read_b128 v[200:203], v0 offset:16384
	ds_read_b128 v[204:207], v195 offset:4096
	ds_read_b128 v[208:211], v0 offset:20480
	ds_read_b128 v[212:215], v0 offset:24576
	ds_read_b128 v[218:221], v0 offset:28672
	s_waitcnt lgkmcnt(4)
	v_mfma_f32_32x32x16_bf16 v[114:129], v[196:199], v[200:203], v[114:129]
	v_lshl_add_u64 v[226:227], v[184:185], 0, s[22:23]
	global_load_dwordx4 v[162:165], v[226:227], off
	s_add_u32 s22, s22, 0x10000
	s_waitcnt lgkmcnt(2)
	v_mfma_f32_32x32x16_bf16 v[82:97], v[196:199], v[208:211], v[82:97]
	v_lshl_add_u64 v[222:223], v[184:185], 0, s[22:23]
	global_load_dwordx4 v[166:169], v[222:223], off
	s_add_u32 s22, s22, 0x10000
	s_waitcnt lgkmcnt(1)
	v_mfma_f32_32x32x16_bf16 v[98:113], v[196:199], v[212:215], v[98:113]
	v_lshl_add_u64 v[224:225], v[184:185], 0, s[22:23]
	global_load_dwordx4 v[170:173], v[224:225], off
	s_add_u32 s22, s22, 0x10000
	s_waitcnt lgkmcnt(0)
	v_mfma_f32_32x32x16_bf16 v[66:81], v[196:199], v[218:221], v[66:81]
	v_lshl_add_u64 v[226:227], v[184:185], 0, s[22:23]
	global_load_dwordx4 v[174:177], v[226:227], off
	v_mfma_f32_32x32x16_bf16 v[50:65], v[204:207], v[200:203], v[50:65]
	v_mfma_f32_32x32x16_bf16 v[34:49], v[204:207], v[208:211], v[34:49]
	v_mfma_f32_32x32x16_bf16 v[18:33], v[204:207], v[212:215], v[18:33]
	v_mfma_f32_32x32x16_bf16 v[2:17], v[204:207], v[218:221], v[2:17]
	v_xor_b32_e32 v0, 64, v187
	v_add_u32_e32 v195, v188, v0
	v_add_u32_e32 v0, v189, v0
	ds_read_b128 v[196:199], v195
	ds_read_b128 v[200:203], v0 offset:16384
	ds_read_b128 v[204:207], v195 offset:4096
	ds_read_b128 v[208:211], v0 offset:20480
	ds_read_b128 v[212:215], v0 offset:24576
	ds_read_b128 v[218:221], v0 offset:28672
	s_waitcnt lgkmcnt(4)
	v_mfma_f32_32x32x16_bf16 v[114:129], v[196:199], v[200:203], v[114:129]
	s_mov_b32 s8, 96
	v_xor_b32_e32 v0, s8, v187
	v_add_u32_e32 v195, v188, v0
	v_add_u32_e32 v0, v189, v0
	s_waitcnt lgkmcnt(2)
	v_mfma_f32_32x32x16_bf16 v[82:97], v[196:199], v[208:211], v[82:97]
	s_waitcnt lgkmcnt(1)
	v_mfma_f32_32x32x16_bf16 v[98:113], v[196:199], v[212:215], v[98:113]
	s_waitcnt lgkmcnt(0)
	v_mfma_f32_32x32x16_bf16 v[66:81], v[196:199], v[218:221], v[66:81]
	v_mfma_f32_32x32x16_bf16 v[50:65], v[204:207], v[200:203], v[50:65]
	v_mfma_f32_32x32x16_bf16 v[34:49], v[204:207], v[208:211], v[34:49]
	v_mfma_f32_32x32x16_bf16 v[18:33], v[204:207], v[212:215], v[18:33]
	v_mfma_f32_32x32x16_bf16 v[2:17], v[204:207], v[218:221], v[2:17]
	ds_read_b128 v[196:199], v195
	ds_read_b128 v[200:203], v0 offset:16384
	ds_read_b128 v[204:207], v195 offset:4096
	ds_read_b128 v[208:211], v0 offset:20480
	ds_read_b128 v[212:215], v0 offset:24576
	ds_read_b128 v[218:221], v0 offset:28672
	s_waitcnt lgkmcnt(4)
	v_mfma_f32_32x32x16_bf16 v[114:129], v[196:199], v[200:203], v[114:129]
	s_waitcnt lgkmcnt(2)
	v_mfma_f32_32x32x16_bf16 v[82:97], v[196:199], v[208:211], v[82:97]
	s_waitcnt lgkmcnt(1)
	v_mfma_f32_32x32x16_bf16 v[98:113], v[196:199], v[212:215], v[98:113]
	s_waitcnt lgkmcnt(0)
	v_mfma_f32_32x32x16_bf16 v[66:81], v[196:199], v[218:221], v[66:81]
	v_mfma_f32_32x32x16_bf16 v[50:65], v[204:207], v[200:203], v[50:65]
	v_mfma_f32_32x32x16_bf16 v[34:49], v[204:207], v[208:211], v[34:49]
	v_mfma_f32_32x32x16_bf16 v[18:33], v[204:207], v[212:215], v[18:33]
	v_mfma_f32_32x32x16_bf16 v[2:17], v[204:207], v[218:221], v[2:17]
	s_branch .Lkint_done_144

;     ...
;             __builtin_amdgcn_s_setprio(0);
;             __syncthreads();
;         }
;         int lane_e = lane; asm volatile("" : "+v"(lane_e));
;         epi.template operator()<4>(acc, tm * 128 + wm * 64, tn * 256 + wn * 128, lane_e);
;     template <int NI> DI void operator()(const f32x16 (&acc)[2][NI], int row0, int col0, int lane) const {
;         const int l31 = lane & 31, lh = lane >> 5;
;         const unsigned lo = (unsigned)(4 * lh * 1536 + l31);
;         bf16_t* base = C + (size_t)row0 * 1536 + col0;
;         const bool lat = row0 < NLAT;
;         const int tlane = (row0 & 8191) + 4 * lh;
;         if (col0 >= 1024) {
.Lkint_done_144:
	s_setprio 0
	s_cmp_eq_u32 s5, 16
	s_barrier
	s_cbranch_scc0 .LBB0_141
	s_waitcnt vmcnt(11)
	v_mov_b32_e32 v134, v186
	s_waitcnt vmcnt(9)
	v_add_u32_e32 v139, s4, v190
	v_ashrrev_i32_e32 v133, 5, v134
	v_or_b32_e32 v132, s6, v191
	v_lshlrev_b32_e32 v138, 2, v133
	v_and_b32_e32 v130, 0x1fc0, v139
	v_and_b32_e32 v0, 31, v134
	v_cmp_gt_i32_e64 s[4:5], s70, v139
	v_add_u32_e32 v136, v138, v130
	v_cmp_gt_i32_e32 vcc, s78, v132
	s_and_saveexec_b64 s[6:7], vcc
	s_xor_b64 s[34:35], exec, s[6:7]
	s_cbranch_execnz .LBB0_148
	s_andn2_saveexec_b64 s[34:35], s[34:35]
	s_cbranch_execz .LBB0_139
	s_branch .LBB0_341

; DI unsigned swz(int row, int chunk) { return (unsigned)row * 128u + (unsigned)((chunk ^ ((row >> 1) & 7)) << 4); }
; #define MFMA32(a, b, c) __builtin_amdgcn_mfma_f32_32x32x16_bf16((a), (b), (c), 0, 0, 0)
;     ...
;         for (int kt = 0; kt < nk; ++kt) {
; #pragma unroll
;             for (int i = 0; i < 4; ++i) *(u32x4*)(lds + swz(lr + 32 * i, lc)) = ra[i];
; #pragma unroll
;             for (int i = 0; i < 8; ++i) *(u32x4*)(lds + 16384 + swz(lr + 32 * i, lc)) = rb[i];
;             __syncthreads();
;             if (kt + 1 < nk) {
; #pragma unroll
;                 for (int i = 0; i < 4; ++i) ra[i] = *(const u32x4*)((Au + (size_t)(32 * i) * lda + (kt + 1) * 64) + voA);
; #pragma unroll
;                 for (int i = 0; i < 8; ++i) rb[i] = *(const u32x4*)((Bu + (size_t)(32 * i) * ldb + (kt + 1) * 64) + voB);
;             }
;             __builtin_amdgcn_s_setprio(1);
; #pragma unroll 2
;             for (int ks = 0; ks < 4; ++ks) {
;                 bf16x8 af[2], bfr[4];
;                 const unsigned xo = (c0 ^ (unsigned)(2 * ks)) << 4;
; #pragma unroll
;                 for (int i = 0; i < 2; ++i) af[i] = *(const bf16x8*)(lds + (roA + xo) + i * 4096);
; #pragma unroll
;                 for (int j = 0; j < 4; ++j) bfr[j] = *(const bf16x8*)(lds + (roB + xo) + j * 4096);
; #pragma unroll
;                 for (int i = 0; i < 2; ++i)
; #pragma unroll
;                     for (int j = 0; j < 4; ++j) acc[i][j] = MFMA32(af[i], bfr[j], acc[i][j]);
;             }
;             __builtin_amdgcn_s_setprio(0);
;             __syncthreads();
.LBB0_644:
	s_mov_b32 s4, s7
	s_add_i32 s7, s7, 1
	s_cmp_lt_u32 s4, 15
	s_waitcnt vmcnt(0)
	ds_write_b128 v224, v[130:133]
	ds_write_b128 v224, v[138:141] offset:4096
	ds_write_b128 v224, v[170:173] offset:8192
	ds_write_b128 v224, v[134:137] offset:12288
	ds_write_b128 v224, v[174:177] offset:16384
	ds_write_b128 v224, v[166:169] offset:20480
	ds_write_b128 v224, v[162:165] offset:24576
	ds_write_b128 v224, v[158:161] offset:28672
	ds_write_b128 v224, v[154:157] offset:32768
	ds_write_b128 v224, v[150:153] offset:36864
	ds_write_b128 v224, v[146:149] offset:40960
	ds_write_b128 v224, v[142:145] offset:45056
	s_waitcnt lgkmcnt(0)
	s_barrier
	s_cbranch_scc0 .LBB0_646
	s_lshl_b32 s10, s7, 7
	s_mov_b32 s11, 0
	s_setprio 1
	v_xor_b32_e32 v1, 0, v219
	v_add_u32_e32 v206, v220, v1
	v_add_u32_e32 v1, v221, v1
	ds_read_b128 v[186:189], v206
	ds_read_b128 v[190:193], v1 offset:16384
	ds_read_b128 v[194:197], v1 offset:20480
	ds_read_b128 v[198:201], v1 offset:24576
	ds_read_b128 v[202:205], v1 offset:28672
	s_waitcnt lgkmcnt(3)
	v_mfma_f32_32x32x16_bf16 v[114:129], v[186:189], v[190:193], v[114:129]
	v_lshl_add_u64 v[226:227], v[182:183], 0, s[10:11]
	global_load_dwordx4 v[130:133], v[226:227], off
	s_add_u32 s10, s10, 0x10000
	s_mov_b32 s9, 32
	v_xor_b32_e32 v1, s9, v219
	s_waitcnt lgkmcnt(2)
	v_mfma_f32_32x32x16_bf16 v[82:97], v[186:189], v[194:197], v[82:97]
	v_lshl_add_u64 v[228:229], v[182:183], 0, s[10:11]
	global_load_dwordx4 v[138:141], v[228:229], off
	s_add_u32 s10, s10, 0x10000
	s_waitcnt lgkmcnt(1)
	v_mfma_f32_32x32x16_bf16 v[50:65], v[186:189], v[198:201], v[50:65]
	v_lshl_add_u64 v[230:231], v[182:183], 0, s[10:11]
	global_load_dwordx4 v[170:173], v[230:231], off
	s_add_u32 s10, s10, 0x10000
	s_waitcnt lgkmcnt(0)
	v_mfma_f32_32x32x16_bf16 v[18:33], v[186:189], v[202:205], v[18:33]
	v_lshl_add_u64 v[226:227], v[182:183], 0, s[10:11]
	global_load_dwordx4 v[134:137], v[226:227], off
	s_sub_u32 s10, s10, 0x30000
	ds_read_b128 v[186:189], v206 offset:4096
	v_add_u32_e32 v206, v220, v1
	v_add_u32_e32 v1, v221, v1
	s_waitcnt lgkmcnt(0)
	v_mfma_f32_32x32x16_bf16 v[98:113], v[186:189], v[190:193], v[98:113]
	v_lshl_add_u64 v[228:229], v[184:185], 0, s[10:11]
	global_load_dwordx4 v[174:177], v[228:229], off
	s_add_u32 s10, s10, 0x10000
	v_mfma_f32_32x32x16_bf16 v[66:81], v[186:189], v[194:197], v[66:81]
	v_lshl_add_u64 v[230:231], v[184:185], 0, s[10:11]
	global_load_dwordx4 v[166:169], v[230:231], off
	s_add_u32 s10, s10, 0x10000
	v_mfma_f32_32x32x16_bf16 v[34:49], v[186:189], v[198:201], v[34:49]
	v_lshl_add_u64 v[226:227], v[184:185], 0, s[10:11]
	global_load_dwordx4 v[162:165], v[226:227], off
	s_add_u32 s10, s10, 0x10000
	v_mfma_f32_32x32x16_bf16 v[2:17], v[186:189], v[202:205], v[2:17]
	v_lshl_add_u64 v[228:229], v[184:185], 0, s[10:11]
	global_load_dwordx4 v[158:161], v[228:229], off
	s_add_u32 s10, s10, 0x10000
	ds_read_b128 v[186:189], v206
	ds_read_b128 v[190:193], v1 offset:16384
	ds_read_b128 v[194:197], v1 offset:20480
	ds_read_b128 v[198:201], v1 offset:24576
	ds_read_b128 v[202:205], v1 offset:28672
	s_waitcnt lgkmcnt(3)
	v_mfma_f32_32x32x16_bf16 v[114:129], v[186:189], v[190:193], v[114:129]
	v_lshl_add_u64 v[230:231], v[184:185], 0, s[10:11]
	global_load_dwordx4 v[154:157], v[230:231], off
	s_add_u32 s10, s10, 0x10000
	s_waitcnt lgkmcnt(2)
	v_mfma_f32_32x32x16_bf16 v[82:97], v[186:189], v[194:197], v[82:97]
	v_lshl_add_u64 v[226:227], v[184:185], 0, s[10:11]
	global_load_dwordx4 v[150:153], v[226:227], off
	s_add_u32 s10, s10, 0x10000
	s_waitcnt lgkmcnt(1)
	v_mfma_f32_32x32x16_bf16 v[50:65], v[186:189], v[198:201], v[50:65]
	v_lshl_add_u64 v[228:229], v[184:185], 0, s[10:11]
	global_load_dwordx4 v[146:149], v[228:229], off
	s_add_u32 s10, s10, 0x10000
	s_waitcnt lgkmcnt(0)
	v_mfma_f32_32x32x16_bf16 v[18:33], v[186:189], v[202:205], v[18:33]
	v_lshl_add_u64 v[230:231], v[184:185], 0, s[10:11]
	global_load_dwordx4 v[142:145], v[230:231], off
	ds_read_b128 v[186:189], v206 offset:4096
	s_waitcnt lgkmcnt(0)
	v_mfma_f32_32x32x16_bf16 v[98:113], v[186:189], v[190:193], v[98:113]
	v_mfma_f32_32x32x16_bf16 v[66:81], v[186:189], v[194:197], v[66:81]
	v_mfma_f32_32x32x16_bf16 v[34:49], v[186:189], v[198:201], v[34:49]
	v_mfma_f32_32x32x16_bf16 v[2:17], v[186:189], v[202:205], v[2:17]
	v_xor_b32_e32 v1, 64, v219
	v_add_u32_e32 v206, v220, v1
	v_add_u32_e32 v1, v221, v1
	ds_read_b128 v[186:189], v206
	ds_read_b128 v[190:193], v1 offset:16384
	ds_read_b128 v[194:197], v1 offset:20480
	ds_read_b128 v[198:201], v1 offset:24576
	ds_read_b128 v[202:205], v1 offset:28672
	s_waitcnt lgkmcnt(3)
	v_mfma_f32_32x32x16_bf16 v[114:129], v[186:189], v[190:193], v[114:129]
	s_mov_b32 s9, 96
	v_xor_b32_e32 v1, s9, v219
	s_waitcnt lgkmcnt(2)
	v_mfma_f32_32x32x16_bf16 v[82:97], v[186:189], v[194:197], v[82:97]
	s_waitcnt lgkmcnt(1)
	v_mfma_f32_32x32x16_bf16 v[50:65], v[186:189], v[198:201], v[50:65]
	s_waitcnt lgkmcnt(0)
	v_mfma_f32_32x32x16_bf16 v[18:33], v[186:189], v[202:205], v[18:33]
	ds_read_b128 v[186:189], v206 offset:4096
	v_add_u32_e32 v206, v220, v1
	v_add_u32_e32 v1, v221, v1
	s_waitcnt lgkmcnt(0)
	v_mfma_f32_32x32x16_bf16 v[98:113], v[186:189], v[190:193], v[98:113]
	v_mfma_f32_32x32x16_bf16 v[66:81], v[186:189], v[194:197], v[66:81]
	v_mfma_f32_32x32x16_bf16 v[34:49], v[186:189], v[198:201], v[34:49]
	v_mfma_f32_32x32x16_bf16 v[2:17], v[186:189], v[202:205], v[2:17]
	ds_read_b128 v[186:189], v206
	ds_read_b128 v[190:193], v1 offset:16384
	ds_read_b128 v[194:197], v1 offset:20480
	ds_read_b128 v[198:201], v1 offset:24576
	ds_read_b128 v[202:205], v1 offset:28672
	s_waitcnt lgkmcnt(3)
	v_mfma_f32_32x32x16_bf16 v[114:129], v[186:189], v[190:193], v[114:129]
	s_waitcnt lgkmcnt(2)
	v_mfma_f32_32x32x16_bf16 v[82:97], v[186:189], v[194:197], v[82:97]
	s_waitcnt lgkmcnt(1)
	v_mfma_f32_32x32x16_bf16 v[50:65], v[186:189], v[198:201], v[50:65]
	s_waitcnt lgkmcnt(0)
	v_mfma_f32_32x32x16_bf16 v[18:33], v[186:189], v[202:205], v[18:33]
	ds_read_b128 v[186:189], v206 offset:4096
	s_waitcnt lgkmcnt(0)
	v_mfma_f32_32x32x16_bf16 v[98:113], v[186:189], v[190:193], v[98:113]
	v_mfma_f32_32x32x16_bf16 v[66:81], v[186:189], v[194:197], v[66:81]
	v_mfma_f32_32x32x16_bf16 v[34:49], v[186:189], v[198:201], v[34:49]
	v_mfma_f32_32x32x16_bf16 v[2:17], v[186:189], v[202:205], v[2:17]
	s_branch .Lkint_done_647

; DI int cu(int r) { return (r & 3) + 8 * (r >> 2); }
;     template <int NI> DI void operator()(const f32x16 (&acc)[2][NI], int row0, int col0, int lane) const {
;         const bool lat = row0 < NLAT;
;         const float* src = (lat ? srcL + (size_t)row0 * DM : srcC + (size_t)(row0 - NLAT) * DM) + col0;
;         float* dst = (lat ? dstL + (size_t)row0 * DM : dstC + (size_t)(row0 - NLAT) * DM) + col0;
;         const float* g = mod + ((lat ? (row0 >> 13) : 8) * 6 + gate_idx) * 1024 + col0;
;         const unsigned l31 = lane & 31, lo = (unsigned)(4 * (lane >> 5) * DM) + l31;
; #pragma unroll
;         for (int ni = 0; ni < NI; ++ni) {
;             const float gv = (g + 32 * ni)[l31];
;             float sv[32];
; #pragma unroll
;             for (int q = 0; q < 32; ++q) sv[q] = __builtin_nontemporal_load(&(src + (32 * (q >> 4) + cu(q & 15)) * DM + 32 * ni)[lo]);
; #pragma unroll
;             for (int q = 0; q < 32; ++q) (dst + (32 * (q >> 4) + cu(q & 15)) * DM + 32 * ni)[lo] = sv[q] + gv * acc[q >> 4][ni][q & 15];
.Lkint_done_647:
	s_setprio 0
	s_cmp_eq_u32 s7, 16
	s_barrier
	s_cbranch_scc0 .LBB0_644
	s_waitcnt vmcnt(10)
	v_add_u32_e32 v138, s6, v222
	v_add_u32_e32 v131, 0xffff0000, v138
	v_ashrrev_i32_e32 v132, 31, v138
	v_cmp_gt_i32_e32 vcc, s16, v138
	s_waitcnt vmcnt(8)
	v_mov_b32_e32 v134, s69
	v_mov_b32_e32 v136, s49
	v_cndmask_b32_e32 v133, 0, v132, vcc
	v_cndmask_b32_e32 v132, v131, v138, vcc
	v_mov_b32_e32 v131, s73
	v_cndmask_b32_e32 v135, v131, v134, vcc
	v_mov_b32_e32 v131, s72
	v_mov_b32_e32 v134, s68
	v_cndmask_b32_e32 v134, v131, v134, vcc
	v_mov_b32_e32 v131, s27
	v_or_b32_e32 v130, s8, v223
	v_cndmask_b32_e32 v137, v131, v136, vcc
	v_mov_b32_e32 v131, s26
	v_mov_b32_e32 v136, s48
	v_lshlrev_b64 v[132:133], 12, v[132:133]
	v_cndmask_b32_e32 v136, v131, v136, vcc
	v_ashrrev_i32_e32 v131, 31, v130
	v_lshl_add_u64 v[134:135], v[134:135], 0, v[132:133]
	v_lshl_add_u64 v[132:133], v[136:137], 0, v[132:133]
	v_lshlrev_b64 v[130:131], 2, v[130:131]
	v_lshl_add_u64 v[136:137], v[132:133], 0, v[130:131]
	v_min_i32_e32 v132, 0x10000, v138
	v_ashrrev_i32_e32 v132, 13, v132
	v_mul_i32_i24_e32 v132, 0x1800, v132
	v_mov_b32_e32 v1, v218
	v_ashrrev_i32_e32 v133, 31, v132
	v_lshl_add_u64 v[132:133], v[132:133], 2, s[12:13]
	v_lshl_add_u64 v[134:135], v[134:135], 0, v[130:131]
	v_lshl_add_u64 v[130:131], v[132:133], 0, v[130:131]
	v_and_b32_e32 v132, 31, v1
	v_lshlrev_b32_e32 v1, 7, v1
	s_movk_i32 s4, 0xf000
	v_and_or_b32 v138, v1, s4, v132
	v_lshlrev_b32_e32 v132, 2, v132
	v_mov_b32_e32 v133, v0
	v_mov_b32_e32 v139, v0
	v_lshl_add_u64 v[140:141], v[130:131], 0, v[132:133]
	v_lshlrev_b64 v[130:131], 2, v[138:139]
	v_lshl_add_u64 v[134:135], v[134:135], 0, v[130:131]
	v_lshl_add_u64 v[130:131], v[136:137], 0, v[130:131]
	v_add_co_u32_e32 v136, vcc, s17, v140
	s_mov_b64 s[6:7], 0x2000
	s_nop 0
	v_addc_co_u32_e32 v137, vcc, 0, v141, vcc
	global_load_dword v1, v[136:137], off
	global_load_dword v186, v[134:135], off nt
	v_add_co_u32_e32 v136, vcc, s28, v134
	v_lshl_add_u64 v[132:133], v[140:141], 0, s[6:7]
	s_nop 0
	v_addc_co_u32_e32 v137, vcc, 0, v135, vcc
	v_add_co_u32_e32 v138, vcc, s17, v134
	s_add_i32 s97, s97, s81
	s_nop 0
	v_addc_co_u32_e32 v139, vcc, 0, v135, vcc
	v_add_co_u32_e32 v140, vcc, s29, v134
	s_cmpk_gt_i32 s97, 0x107
	s_nop 0
	v_addc_co_u32_e32 v141, vcc, 0, v135, vcc
	s_waitcnt vmcnt(2)
	v_add_co_u32_e32 v142, vcc, s31, v134
	s_waitcnt vmcnt(0)
	v_fmac_f32_e32 v186, v114, v1
	v_addc_co_u32_e32 v143, vcc, 0, v135, vcc
	v_add_co_u32_e32 v144, vcc, s35, v134
	s_nop 1
	v_addc_co_u32_e32 v145, vcc, 0, v135, vcc
	v_add_co_u32_e32 v146, vcc, s46, v134
	s_nop 1
	v_addc_co_u32_e32 v147, vcc, 0, v135, vcc
	v_add_co_u32_e32 v148, vcc, s30, v134
	global_load_dword v187, v[138:139], off offset:-4096 nt
	global_load_dword v188, v[138:139], off nt
	global_load_dword v189, v[142:143], off offset:-4096 nt
	global_load_dword v190, v[142:143], off nt
	global_load_dword v191, v[144:145], off offset:-4096 nt
	global_load_dword v192, v[144:145], off nt
	global_load_dword v193, v[146:147], off offset:-4096 nt
	global_load_dword v194, v[140:141], off nt
	v_addc_co_u32_e32 v149, vcc, 0, v135, vcc
	v_add_co_u32_e32 v150, vcc, s34, v134
	s_waitcnt vmcnt(7)
	v_fmac_f32_e32 v187, v115, v1
	v_addc_co_u32_e32 v151, vcc, 0, v135, vcc
	v_add_co_u32_e32 v152, vcc, s16, v134
	s_waitcnt vmcnt(6)
	v_fmac_f32_e32 v188, v116, v1
	v_addc_co_u32_e32 v153, vcc, 0, v135, vcc
	v_add_co_u32_e32 v154, vcc, s47, v134
	s_waitcnt vmcnt(0)
	v_fmac_f32_e32 v194, v117, v1
	v_addc_co_u32_e32 v155, vcc, 0, v135, vcc
	v_add_co_u32_e32 v156, vcc, s62, v134
	v_fmac_f32_e32 v189, v118, v1
	s_nop 0
	v_addc_co_u32_e32 v157, vcc, 0, v135, vcc
	v_add_co_u32_e32 v158, vcc, s63, v134
	v_fmac_f32_e32 v190, v119, v1
	s_nop 0
	v_addc_co_u32_e32 v159, vcc, 0, v135, vcc
	v_add_co_u32_e32 v160, vcc, s70, v134
	v_fmac_f32_e32 v191, v120, v1
	s_nop 0
	v_addc_co_u32_e32 v161, vcc, 0, v135, vcc
	v_add_co_u32_e32 v162, vcc, s71, v134
	v_fmac_f32_e32 v192, v121, v1
	s_nop 0
	v_addc_co_u32_e32 v163, vcc, 0, v135, vcc
	v_add_co_u32_e32 v164, vcc, s74, v134
	v_fmac_f32_e32 v193, v122, v1
	s_nop 0
	v_addc_co_u32_e32 v165, vcc, 0, v135, vcc
	v_add_co_u32_e32 v166, vcc, s75, v134
	s_nop 1
	v_addc_co_u32_e32 v167, vcc, 0, v135, vcc
	global_load_dword v195, v[146:147], off nt
	global_load_dword v196, v[156:157], off offset:-4096 nt
	global_load_dword v197, v[156:157], off nt
	global_load_dword v198, v[160:161], off offset:-4096 nt
	global_load_dword v199, v[160:161], off nt
	global_load_dword v200, v[164:165], off offset:-4096 nt
	global_load_dword v201, v[164:165], off nt
	global_load_dword v202, v[166:167], off offset:-4096 nt
	v_add_co_u32_e32 v168, vcc, s79, v134
	s_waitcnt vmcnt(7)
	v_fmac_f32_e32 v195, v123, v1
	v_addc_co_u32_e32 v169, vcc, 0, v135, vcc
	v_add_co_u32_e32 v170, vcc, s87, v134
	s_waitcnt vmcnt(6)
	v_fmac_f32_e32 v196, v124, v1
	v_addc_co_u32_e32 v171, vcc, 0, v135, vcc
	v_add_co_u32_e32 v172, vcc, s89, v134
	s_waitcnt vmcnt(5)
	v_fmac_f32_e32 v197, v125, v1
	v_addc_co_u32_e32 v173, vcc, 0, v135, vcc
	v_add_co_u32_e32 v174, vcc, s90, v134
	s_waitcnt vmcnt(4)
	v_fmac_f32_e32 v198, v126, v1
	v_addc_co_u32_e32 v175, vcc, 0, v135, vcc
	global_load_dword v203, v[166:167], off nt
	global_load_dword v204, v[168:169], off offset:-4096 nt
	global_load_dword v205, v[168:169], off nt
	global_load_dword v206, v[170:171], off offset:-4096 nt
	global_load_dword v207, v[170:171], off nt
	global_load_dword v208, v[172:173], off offset:-4096 nt
	global_load_dword v209, v[172:173], off nt
	global_load_dword v210, v[174:175], off offset:-4096 nt
	v_add_co_u32_e32 v176, vcc, s92, v134
	s_waitcnt vmcnt(11)
; DI int cu(int r) { return (r & 3) + 8 * (r >> 2); }
;     template <int NI> DI void operator()(const f32x16 (&acc)[2][NI], int row0, int col0, int lane) const {
;     ...
;         for (int ni = 0; ni < NI; ++ni) {
;             const float gv = (g + 32 * ni)[l31];
;             float sv[32];
; #pragma unroll
;             for (int q = 0; q < 32; ++q) sv[q] = __builtin_nontemporal_load(&(src + (32 * (q >> 4) + cu(q & 15)) * DM + 32 * ni)[lo]);
; #pragma unroll
;             for (int q = 0; q < 32; ++q) (dst + (32 * (q >> 4) + cu(q & 15)) * DM + 32 * ni)[lo] = sv[q] + gv * acc[q >> 4][ni][q & 15];
;             asm volatile("" ::: "memory");
	v_fmac_f32_e32 v199, v127, v1
	v_addc_co_u32_e32 v177, vcc, 0, v135, vcc
	v_add_co_u32_e32 v182, vcc, s94, v134
	s_waitcnt vmcnt(10)
	v_fmac_f32_e32 v200, v128, v1
	v_addc_co_u32_e32 v183, vcc, 0, v135, vcc
	v_add_co_u32_e32 v184, vcc, s96, v134
	s_waitcnt vmcnt(9)
	v_fmac_f32_e32 v201, v129, v1
	v_addc_co_u32_e32 v185, vcc, 0, v135, vcc
	global_load_dword v211, v[174:175], off nt
	global_load_dword v212, v[176:177], off offset:-4096 nt
	global_load_dword v213, v[176:177], off nt
	global_load_dword v214, v[182:183], off offset:-4096 nt
	global_load_dword v215, v[182:183], off nt
	global_load_dword v225, v[184:185], off offset:-4096 nt
	global_load_dword v226, v[184:185], off nt
	v_add_co_u32_e32 v114, vcc, s17, v130
	global_store_dword v[130:131], v186, off
	s_nop 0
	v_addc_co_u32_e32 v115, vcc, 0, v131, vcc
	v_add_co_u32_e32 v116, vcc, s29, v130
	global_store_dword v[114:115], v187, off offset:-4096
	s_nop 0
	v_addc_co_u32_e32 v117, vcc, 0, v131, vcc
	v_add_co_u32_e32 v186, vcc, s31, v130
	s_waitcnt vmcnt(17)
	v_fmac_f32_e32 v202, v98, v1
	v_addc_co_u32_e32 v187, vcc, 0, v131, vcc
	v_add_co_u32_e32 v118, vcc, s35, v130
	global_store_dword v[116:117], v194, off
	s_nop 0
	v_addc_co_u32_e32 v119, vcc, 0, v131, vcc
	v_add_co_u32_e32 v120, vcc, s46, v130
	global_store_dword v[114:115], v188, off
	s_nop 0
	v_addc_co_u32_e32 v121, vcc, 0, v131, vcc
	v_add_co_u32_e32 v122, vcc, s62, v130
	global_store_dword v[186:187], v189, off offset:-4096
	s_nop 0
	v_addc_co_u32_e32 v123, vcc, 0, v131, vcc
	v_add_co_u32_e32 v124, vcc, s70, v130
	global_store_dword v[186:187], v190, off
	s_nop 0
	v_addc_co_u32_e32 v125, vcc, 0, v131, vcc
	v_add_co_u32_e32 v126, vcc, s74, v130
	global_store_dword v[118:119], v191, off offset:-4096
	s_nop 0
	v_addc_co_u32_e32 v127, vcc, 0, v131, vcc
	v_add_co_u32_e32 v128, vcc, s75, v130
	global_store_dword v[118:119], v192, off
	s_nop 0
	v_addc_co_u32_e32 v129, vcc, 0, v131, vcc
	v_add_co_u32_e32 v98, vcc, s79, v130
	global_store_dword v[120:121], v193, off offset:-4096
	global_store_dword v[120:121], v195, off
	global_store_dword v[122:123], v196, off offset:-4096
	global_store_dword v[122:123], v197, off
	global_store_dword v[124:125], v198, off offset:-4096
	global_store_dword v[124:125], v199, off
	global_store_dword v[126:127], v200, off offset:-4096
	global_store_dword v[126:127], v201, off
	global_store_dword v[128:129], v202, off offset:-4096
	s_waitcnt vmcnt(31)
	v_fmac_f32_e32 v203, v99, v1
	v_addc_co_u32_e32 v99, vcc, 0, v131, vcc
	s_waitcnt vmcnt(30)
	v_fmac_f32_e32 v204, v100, v1
	v_add_co_u32_e32 v100, vcc, s87, v130
	s_waitcnt vmcnt(29)
	v_fmac_f32_e32 v205, v101, v1
	v_addc_co_u32_e32 v101, vcc, 0, v131, vcc
	s_waitcnt vmcnt(28)
	v_fmac_f32_e32 v206, v102, v1
	v_add_co_u32_e32 v102, vcc, s89, v130
	s_waitcnt vmcnt(27)
	v_fmac_f32_e32 v207, v103, v1
	v_addc_co_u32_e32 v103, vcc, 0, v131, vcc
	s_waitcnt vmcnt(26)
	v_fmac_f32_e32 v208, v104, v1
	v_add_co_u32_e32 v104, vcc, s90, v130
	s_waitcnt vmcnt(25)
	v_fmac_f32_e32 v209, v105, v1
	v_addc_co_u32_e32 v105, vcc, 0, v131, vcc
	s_waitcnt vmcnt(24)
	v_fmac_f32_e32 v210, v106, v1
	v_add_co_u32_e32 v106, vcc, s92, v130
	s_waitcnt vmcnt(23)
	v_fmac_f32_e32 v211, v107, v1
	v_addc_co_u32_e32 v107, vcc, 0, v131, vcc
	s_waitcnt vmcnt(22)
	v_fmac_f32_e32 v212, v108, v1
	v_add_co_u32_e32 v108, vcc, s94, v130
	s_waitcnt vmcnt(21)
	v_fmac_f32_e32 v213, v109, v1
	v_addc_co_u32_e32 v109, vcc, 0, v131, vcc
	s_waitcnt vmcnt(20)
	v_fmac_f32_e32 v214, v110, v1
	v_add_co_u32_e32 v110, vcc, s96, v130
	s_waitcnt vmcnt(19)
	v_fmac_f32_e32 v215, v111, v1
	v_addc_co_u32_e32 v111, vcc, 0, v131, vcc
	s_waitcnt vmcnt(18)
	v_fmac_f32_e32 v225, v112, v1
	s_waitcnt vmcnt(17)
	v_fmac_f32_e32 v226, v113, v1
	v_add_co_u32_e32 v194, vcc, s15, v134
	global_store_dword v[128:129], v203, off
	global_store_dword v[98:99], v204, off offset:-4096
	global_store_dword v[98:99], v205, off
	global_store_dword v[100:101], v206, off offset:-4096
	global_store_dword v[100:101], v207, off
	global_store_dword v[102:103], v208, off offset:-4096
	global_store_dword v[102:103], v209, off
	global_store_dword v[104:105], v210, off offset:-4096
	global_store_dword v[104:105], v211, off
	global_store_dword v[106:107], v212, off offset:-4096
	global_store_dword v[106:107], v213, off
	global_store_dword v[108:109], v214, off offset:-4096
	global_store_dword v[108:109], v215, off
	global_store_dword v[110:111], v225, off offset:-4096
	global_store_dword v[110:111], v226, off
	v_addc_co_u32_e32 v195, vcc, 0, v135, vcc
	v_add_co_u32_e32 v196, vcc, s78, v134
	global_load_dword v1, v[132:133], off offset:128
	global_load_dword v210, v[134:135], off offset:128 nt
	global_load_dword v211, v[136:137], off offset:128 nt
	global_load_dword v212, v[138:139], off offset:128 nt
	global_load_dword v213, v[140:141], off offset:128 nt
	global_load_dword v214, v[148:149], off offset:128 nt
	global_load_dword v215, v[142:143], off offset:128 nt
	global_load_dword v225, v[150:151], off offset:128 nt
	global_load_dword v226, v[144:145], off offset:128 nt
	global_load_dword v227, v[152:153], off offset:128 nt
	global_load_dword v228, v[146:147], off offset:128 nt
	global_load_dword v229, v[154:155], off offset:128 nt
	global_load_dword v230, v[156:157], off offset:128 nt
	global_load_dword v231, v[158:159], off offset:128 nt
	global_load_dword v232, v[160:161], off offset:128 nt
	global_load_dword v233, v[162:163], off offset:128 nt
	global_load_dword v234, v[164:165], off offset:128 nt
	v_addc_co_u32_e32 v197, vcc, 0, v135, vcc
	v_add_co_u32_e32 v198, vcc, s86, v134
	s_waitcnt vmcnt(15)
; DI int cu(int r) { return (r & 3) + 8 * (r >> 2); }
;     template <int NI> DI void operator()(const f32x16 (&acc)[2][NI], int row0, int col0, int lane) const {
;     ...
;         for (int ni = 0; ni < NI; ++ni) {
;             const float gv = (g + 32 * ni)[l31];
;             float sv[32];
; #pragma unroll
;             for (int q = 0; q < 32; ++q) sv[q] = __builtin_nontemporal_load(&(src + (32 * (q >> 4) + cu(q & 15)) * DM + 32 * ni)[lo]);
; #pragma unroll
;             for (int q = 0; q < 32; ++q) (dst + (32 * (q >> 4) + cu(q & 15)) * DM + 32 * ni)[lo] = sv[q] + gv * acc[q >> 4][ni][q & 15];
;             asm volatile("" ::: "memory");
	v_fmac_f32_e32 v210, v82, v1
	v_addc_co_u32_e32 v199, vcc, 0, v135, vcc
	v_add_co_u32_e32 v200, vcc, s88, v134
	global_load_dword v235, v[166:167], off offset:128 nt
	global_load_dword v236, v[168:169], off offset:128 nt
	global_load_dword v237, v[194:195], off offset:128 nt
	global_load_dword v238, v[196:197], off offset:128 nt
	global_load_dword v239, v[198:199], off offset:128 nt
	v_addc_co_u32_e32 v201, vcc, 0, v135, vcc
	v_add_co_u32_e32 v202, vcc, s14, v134
	s_waitcnt vmcnt(18)
	v_fmac_f32_e32 v212, v84, v1
	v_addc_co_u32_e32 v203, vcc, 0, v135, vcc
	v_add_co_u32_e32 v204, vcc, s91, v134
	s_waitcnt vmcnt(17)
	v_fmac_f32_e32 v213, v85, v1
	v_addc_co_u32_e32 v205, vcc, 0, v135, vcc
	v_add_co_u32_e32 v206, vcc, s93, v134
	v_fmac_f32_e32 v211, v83, v1
	s_nop 0
	v_addc_co_u32_e32 v207, vcc, 0, v135, vcc
	v_add_co_u32_e32 v208, vcc, s95, v134
	s_waitcnt vmcnt(10)
	v_fmac_f32_e32 v229, v92, v1
	v_addc_co_u32_e32 v209, vcc, 0, v135, vcc
	global_load_dword v240, v[170:171], off offset:128 nt
	global_load_dword v241, v[172:173], off offset:128 nt
	global_load_dword v242, v[200:201], off offset:128 nt
	global_load_dword v243, v[202:203], off offset:128 nt
	global_load_dword v244, v[204:205], off offset:128 nt
	global_load_dword v245, v[206:207], off offset:128 nt
	global_load_dword v246, v[208:209], off offset:128 nt
	global_load_dword v247, v[174:175], off offset:128 nt
	global_load_dword v248, v[176:177], off offset:128 nt
	global_load_dword v249, v[182:183], off offset:128 nt
	global_load_dword v250, v[184:185], off offset:128 nt
	v_add_co_u32_e32 v192, vcc, s28, v130
	s_waitcnt vmcnt(20)
	v_fmac_f32_e32 v230, v93, v1
	v_addc_co_u32_e32 v193, vcc, 0, v131, vcc
	v_add_co_u32_e32 v190, vcc, s30, v130
	s_waitcnt vmcnt(19)
	v_fmac_f32_e32 v231, v94, v1
	v_addc_co_u32_e32 v191, vcc, 0, v131, vcc
	v_add_co_u32_e32 v188, vcc, s34, v130
	s_waitcnt vmcnt(18)
	v_fmac_f32_e32 v232, v95, v1
	v_addc_co_u32_e32 v189, vcc, 0, v131, vcc
	v_add_co_u32_e32 v112, vcc, s16, v130
	s_waitcnt vmcnt(17)
	v_fmac_f32_e32 v233, v96, v1
	v_addc_co_u32_e32 v113, vcc, 0, v131, vcc
	v_add_co_u32_e32 v84, vcc, s47, v130
	s_waitcnt vmcnt(16)
	v_fmac_f32_e32 v234, v97, v1
	v_addc_co_u32_e32 v85, vcc, 0, v131, vcc
	v_add_co_u32_e32 v82, vcc, s63, v130
	global_store_dword v[130:131], v210, off offset:128
	s_nop 0
	v_addc_co_u32_e32 v83, vcc, 0, v131, vcc
	v_add_co_u32_e32 v92, vcc, s71, v130
	global_store_dword v[192:193], v211, off offset:128
	global_store_dword v[114:115], v212, off offset:128
	v_addc_co_u32_e32 v93, vcc, 0, v131, vcc
	v_add_co_u32_e32 v94, vcc, s15, v130
	v_fmac_f32_e32 v214, v86, v1
	s_nop 0
	v_addc_co_u32_e32 v95, vcc, 0, v131, vcc
	v_add_co_u32_e32 v96, vcc, s78, v130
	global_store_dword v[116:117], v213, off offset:128
	global_store_dword v[190:191], v214, off offset:128
	v_addc_co_u32_e32 v97, vcc, 0, v131, vcc
	v_add_co_u32_e32 v210, vcc, s86, v130
	v_fmac_f32_e32 v215, v87, v1
	s_nop 0
	v_addc_co_u32_e32 v211, vcc, 0, v131, vcc
	v_add_co_u32_e32 v212, vcc, s88, v130
	v_fmac_f32_e32 v225, v88, v1
	s_nop 0
	v_addc_co_u32_e32 v213, vcc, 0, v131, vcc
	v_add_co_u32_e32 v214, vcc, s14, v130
	global_store_dword v[186:187], v215, off offset:128
	global_store_dword v[188:189], v225, off offset:128
	v_addc_co_u32_e32 v215, vcc, 0, v131, vcc
	v_fmac_f32_e32 v227, v90, v1
	v_add_co_u32_e32 v90, vcc, s91, v130
	v_fmac_f32_e32 v228, v91, v1
	s_nop 0
	v_addc_co_u32_e32 v91, vcc, 0, v131, vcc
	v_add_co_u32_e32 v86, vcc, s93, v130
	v_fmac_f32_e32 v226, v89, v1
	s_nop 0
	v_addc_co_u32_e32 v87, vcc, 0, v131, vcc
	v_add_co_u32_e32 v88, vcc, s95, v130
	s_waitcnt vmcnt(20)
	v_fmac_f32_e32 v237, v66, v1
	v_addc_co_u32_e32 v89, vcc, 0, v131, vcc
	v_fmac_f32_e32 v235, v67, v1
	s_waitcnt vmcnt(19)
	v_fmac_f32_e32 v238, v68, v1
	v_fmac_f32_e32 v236, v69, v1
	s_waitcnt vmcnt(18)
	v_fmac_f32_e32 v239, v70, v1
	s_waitcnt vmcnt(17)
	v_fmac_f32_e32 v240, v71, v1
	s_waitcnt vmcnt(15)
	v_fmac_f32_e32 v242, v72, v1
	v_fmac_f32_e32 v241, v73, v1
	s_waitcnt vmcnt(14)
	v_fmac_f32_e32 v243, v74, v1
	s_waitcnt vmcnt(10)
	v_fmac_f32_e32 v247, v75, v1
	v_fmac_f32_e32 v244, v76, v1
	s_waitcnt vmcnt(9)
	v_fmac_f32_e32 v248, v77, v1
	v_fmac_f32_e32 v245, v78, v1
	s_waitcnt vmcnt(8)
	v_fmac_f32_e32 v249, v79, v1
	v_fmac_f32_e32 v246, v80, v1
	s_waitcnt vmcnt(7)
; DI int cu(int r) { return (r & 3) + 8 * (r >> 2); }
;     template <int NI> DI void operator()(const f32x16 (&acc)[2][NI], int row0, int col0, int lane) const {
;     ...
;         for (int ni = 0; ni < NI; ++ni) {
;             const float gv = (g + 32 * ni)[l31];
;             float sv[32];
; #pragma unroll
;             for (int q = 0; q < 32; ++q) sv[q] = __builtin_nontemporal_load(&(src + (32 * (q >> 4) + cu(q & 15)) * DM + 32 * ni)[lo]);
; #pragma unroll
;             for (int q = 0; q < 32; ++q) (dst + (32 * (q >> 4) + cu(q & 15)) * DM + 32 * ni)[lo] = sv[q] + gv * acc[q >> 4][ni][q & 15];
;             asm volatile("" ::: "memory");
	v_fmac_f32_e32 v250, v81, v1
	global_store_dword v[118:119], v226, off offset:128
	global_store_dword v[112:113], v227, off offset:128
	global_store_dword v[120:121], v228, off offset:128
	global_store_dword v[84:85], v229, off offset:128
	global_store_dword v[122:123], v230, off offset:128
	global_store_dword v[82:83], v231, off offset:128
	global_store_dword v[124:125], v232, off offset:128
	global_store_dword v[92:93], v233, off offset:128
	global_store_dword v[126:127], v234, off offset:128
	global_store_dword v[94:95], v237, off offset:128
	global_store_dword v[128:129], v235, off offset:128
	global_store_dword v[96:97], v238, off offset:128
	global_store_dword v[98:99], v236, off offset:128
	global_store_dword v[210:211], v239, off offset:128
	global_store_dword v[100:101], v240, off offset:128
	global_store_dword v[212:213], v242, off offset:128
	global_store_dword v[102:103], v241, off offset:128
	global_store_dword v[214:215], v243, off offset:128
	global_store_dword v[104:105], v247, off offset:128
	global_store_dword v[90:91], v244, off offset:128
	global_store_dword v[106:107], v248, off offset:128
	global_store_dword v[86:87], v245, off offset:128
	global_store_dword v[108:109], v249, off offset:128
	global_store_dword v[88:89], v246, off offset:128
	global_store_dword v[110:111], v250, off offset:128
	global_load_dword v1, v[132:133], off offset:256
	global_load_dword v66, v[134:135], off offset:256 nt
	global_load_dword v67, v[136:137], off offset:256 nt
	global_load_dword v68, v[138:139], off offset:256 nt
	global_load_dword v69, v[140:141], off offset:256 nt
	global_load_dword v70, v[148:149], off offset:256 nt
	global_load_dword v71, v[142:143], off offset:256 nt
	global_load_dword v72, v[150:151], off offset:256 nt
	global_load_dword v73, v[144:145], off offset:256 nt
	global_load_dword v74, v[152:153], off offset:256 nt
	global_load_dword v75, v[146:147], off offset:256 nt
	global_load_dword v76, v[154:155], off offset:256 nt
	global_load_dword v77, v[156:157], off offset:256 nt
	global_load_dword v78, v[158:159], off offset:256 nt
	global_load_dword v79, v[160:161], off offset:256 nt
	global_load_dword v80, v[162:163], off offset:256 nt
	global_load_dword v81, v[164:165], off offset:256 nt
	global_load_dword v225, v[194:195], off offset:256 nt
	global_load_dword v226, v[166:167], off offset:256 nt
	global_load_dword v227, v[196:197], off offset:256 nt
	global_load_dword v228, v[168:169], off offset:256 nt
	global_load_dword v229, v[198:199], off offset:256 nt
	global_load_dword v230, v[170:171], off offset:256 nt
	global_load_dword v231, v[200:201], off offset:256 nt
	global_load_dword v232, v[172:173], off offset:256 nt
	global_load_dword v233, v[202:203], off offset:256 nt
	global_load_dword v234, v[174:175], off offset:256 nt
	global_load_dword v235, v[204:205], off offset:256 nt
	global_load_dword v236, v[176:177], off offset:256 nt
	global_load_dword v237, v[206:207], off offset:256 nt
	global_load_dword v238, v[182:183], off offset:256 nt
	global_load_dword v239, v[208:209], off offset:256 nt
	s_waitcnt vmcnt(30)
	v_fmac_f32_e32 v66, v50, v1
	global_load_dword v50, v[184:185], off offset:256 nt
	s_waitcnt vmcnt(30)
	v_fmac_f32_e32 v67, v51, v1
	s_waitcnt vmcnt(29)
	v_fmac_f32_e32 v68, v52, v1
	s_waitcnt vmcnt(28)
	v_fmac_f32_e32 v69, v53, v1
	s_waitcnt vmcnt(27)
	v_fmac_f32_e32 v70, v54, v1
	s_waitcnt vmcnt(26)
	v_fmac_f32_e32 v71, v55, v1
	s_waitcnt vmcnt(25)
	v_fmac_f32_e32 v72, v56, v1
	s_waitcnt vmcnt(24)
	v_fmac_f32_e32 v73, v57, v1
	s_waitcnt vmcnt(23)
	v_fmac_f32_e32 v74, v58, v1
	s_waitcnt vmcnt(22)
	v_fmac_f32_e32 v75, v59, v1
	s_waitcnt vmcnt(21)
	v_fmac_f32_e32 v76, v60, v1
	s_waitcnt vmcnt(20)
	v_fmac_f32_e32 v77, v61, v1
	s_waitcnt vmcnt(19)
	v_fmac_f32_e32 v78, v62, v1
	s_waitcnt vmcnt(18)
	v_fmac_f32_e32 v79, v63, v1
	s_waitcnt vmcnt(17)
	v_fmac_f32_e32 v80, v64, v1
	s_waitcnt vmcnt(16)
	v_fmac_f32_e32 v81, v65, v1
	s_waitcnt vmcnt(15)
	v_fmac_f32_e32 v225, v34, v1
	s_waitcnt vmcnt(14)
	v_fmac_f32_e32 v226, v35, v1
	s_waitcnt vmcnt(13)
	v_fmac_f32_e32 v227, v36, v1
	s_waitcnt vmcnt(12)
	v_fmac_f32_e32 v228, v37, v1
	s_waitcnt vmcnt(11)
	v_fmac_f32_e32 v229, v38, v1
	s_waitcnt vmcnt(10)
	v_fmac_f32_e32 v230, v39, v1
	s_waitcnt vmcnt(9)
	v_fmac_f32_e32 v231, v40, v1
	s_waitcnt vmcnt(8)
	v_fmac_f32_e32 v232, v41, v1
	s_waitcnt vmcnt(7)
	v_fmac_f32_e32 v233, v42, v1
	s_waitcnt vmcnt(6)
	v_fmac_f32_e32 v234, v43, v1
	s_waitcnt vmcnt(5)
	v_fmac_f32_e32 v235, v44, v1
	s_waitcnt vmcnt(4)
	v_fmac_f32_e32 v236, v45, v1
	s_waitcnt vmcnt(3)
	v_fmac_f32_e32 v237, v46, v1
	s_waitcnt vmcnt(2)
	v_fmac_f32_e32 v238, v47, v1
	s_waitcnt vmcnt(1)
	v_fmac_f32_e32 v239, v48, v1
	global_store_dword v[130:131], v66, off offset:256
	global_store_dword v[192:193], v67, off offset:256
	global_store_dword v[114:115], v68, off offset:256
	global_store_dword v[116:117], v69, off offset:256
	global_store_dword v[190:191], v70, off offset:256
	global_store_dword v[186:187], v71, off offset:256
	global_store_dword v[188:189], v72, off offset:256
	global_store_dword v[118:119], v73, off offset:256
	global_store_dword v[112:113], v74, off offset:256
	global_store_dword v[120:121], v75, off offset:256
	global_store_dword v[84:85], v76, off offset:256
	global_store_dword v[122:123], v77, off offset:256
	global_store_dword v[82:83], v78, off offset:256
	global_store_dword v[124:125], v79, off offset:256
	global_store_dword v[92:93], v80, off offset:256
	global_store_dword v[126:127], v81, off offset:256
	global_store_dword v[94:95], v225, off offset:256
	global_store_dword v[128:129], v226, off offset:256
	global_store_dword v[96:97], v227, off offset:256
	global_store_dword v[98:99], v228, off offset:256
	global_store_dword v[210:211], v229, off offset:256
	global_store_dword v[100:101], v230, off offset:256
	global_store_dword v[212:213], v231, off offset:256
	global_store_dword v[102:103], v232, off offset:256
	global_store_dword v[214:215], v233, off offset:256
	global_store_dword v[104:105], v234, off offset:256
	global_store_dword v[90:91], v235, off offset:256
	global_store_dword v[106:107], v236, off offset:256
	global_store_dword v[86:87], v237, off offset:256
	global_store_dword v[108:109], v238, off offset:256
	global_store_dword v[88:89], v239, off offset:256
	s_waitcnt vmcnt(31)
; DI int cu(int r) { return (r & 3) + 8 * (r >> 2); }
;     template <int NI> DI void operator()(const f32x16 (&acc)[2][NI], int row0, int col0, int lane) const {
;     ...
;         for (int ni = 0; ni < NI; ++ni) {
;             const float gv = (g + 32 * ni)[l31];
;             float sv[32];
; #pragma unroll
;             for (int q = 0; q < 32; ++q) sv[q] = __builtin_nontemporal_load(&(src + (32 * (q >> 4) + cu(q & 15)) * DM + 32 * ni)[lo]);
; #pragma unroll
;             for (int q = 0; q < 32; ++q) (dst + (32 * (q >> 4) + cu(q & 15)) * DM + 32 * ni)[lo] = sv[q] + gv * acc[q >> 4][ni][q & 15];
;             asm volatile("" ::: "memory");
;         }
	v_fmac_f32_e32 v50, v49, v1
	global_store_dword v[110:111], v50, off offset:256
	global_load_dword v1, v[132:133], off offset:384
	global_load_dword v34, v[134:135], off offset:384 nt
	global_load_dword v35, v[136:137], off offset:384 nt
	global_load_dword v36, v[138:139], off offset:384 nt
	global_load_dword v37, v[140:141], off offset:384 nt
	global_load_dword v38, v[148:149], off offset:384 nt
	global_load_dword v39, v[142:143], off offset:384 nt
	global_load_dword v40, v[150:151], off offset:384 nt
	global_load_dword v41, v[144:145], off offset:384 nt
	global_load_dword v42, v[152:153], off offset:384 nt
	global_load_dword v43, v[146:147], off offset:384 nt
	global_load_dword v44, v[154:155], off offset:384 nt
	global_load_dword v45, v[156:157], off offset:384 nt
	global_load_dword v46, v[158:159], off offset:384 nt
	global_load_dword v47, v[160:161], off offset:384 nt
	global_load_dword v48, v[162:163], off offset:384 nt
	global_load_dword v49, v[164:165], off offset:384 nt
	global_load_dword v50, v[194:195], off offset:384 nt
	global_load_dword v51, v[166:167], off offset:384 nt
	global_load_dword v52, v[196:197], off offset:384 nt
	global_load_dword v53, v[168:169], off offset:384 nt
	global_load_dword v54, v[198:199], off offset:384 nt
	global_load_dword v55, v[170:171], off offset:384 nt
	global_load_dword v56, v[200:201], off offset:384 nt
	global_load_dword v57, v[172:173], off offset:384 nt
	global_load_dword v58, v[202:203], off offset:384 nt
	global_load_dword v59, v[174:175], off offset:384 nt
	global_load_dword v60, v[204:205], off offset:384 nt
	global_load_dword v61, v[176:177], off offset:384 nt
	global_load_dword v62, v[206:207], off offset:384 nt
	global_load_dword v63, v[182:183], off offset:384 nt
	global_load_dword v64, v[208:209], off offset:384 nt
	global_load_dword v65, v[184:185], off offset:384 nt
	s_waitcnt vmcnt(31)
	v_fmac_f32_e32 v34, v18, v1
	s_waitcnt vmcnt(30)
	v_fmac_f32_e32 v35, v19, v1
	s_waitcnt vmcnt(29)
	v_fmac_f32_e32 v36, v20, v1
	s_waitcnt vmcnt(28)
	v_fmac_f32_e32 v37, v21, v1
	s_waitcnt vmcnt(27)
	v_fmac_f32_e32 v38, v22, v1
	s_waitcnt vmcnt(26)
	v_fmac_f32_e32 v39, v23, v1
	s_waitcnt vmcnt(25)
	v_fmac_f32_e32 v40, v24, v1
	s_waitcnt vmcnt(24)
	v_fmac_f32_e32 v41, v25, v1
	s_waitcnt vmcnt(23)
	v_fmac_f32_e32 v42, v26, v1
	s_waitcnt vmcnt(22)
	v_fmac_f32_e32 v43, v27, v1
	s_waitcnt vmcnt(21)
	v_fmac_f32_e32 v44, v28, v1
	s_waitcnt vmcnt(20)
	v_fmac_f32_e32 v45, v29, v1
	s_waitcnt vmcnt(19)
	v_fmac_f32_e32 v46, v30, v1
	s_waitcnt vmcnt(18)
	v_fmac_f32_e32 v47, v31, v1
	s_waitcnt vmcnt(17)
	v_fmac_f32_e32 v48, v32, v1
	s_waitcnt vmcnt(16)
	v_fmac_f32_e32 v49, v33, v1
	s_waitcnt vmcnt(15)
	v_fmac_f32_e32 v50, v2, v1
	s_waitcnt vmcnt(14)
	v_fmac_f32_e32 v51, v3, v1
	s_waitcnt vmcnt(13)
	v_fmac_f32_e32 v52, v4, v1
	s_waitcnt vmcnt(12)
	v_fmac_f32_e32 v53, v5, v1
	s_waitcnt vmcnt(11)
	v_fmac_f32_e32 v54, v6, v1
	s_waitcnt vmcnt(10)
	v_fmac_f32_e32 v55, v7, v1
	s_waitcnt vmcnt(9)
	v_fmac_f32_e32 v56, v8, v1
	s_waitcnt vmcnt(8)
	v_fmac_f32_e32 v57, v9, v1
	s_waitcnt vmcnt(7)
	v_fmac_f32_e32 v58, v10, v1
	s_waitcnt vmcnt(6)
	v_fmac_f32_e32 v59, v11, v1
	s_waitcnt vmcnt(5)
	v_fmac_f32_e32 v60, v12, v1
	s_waitcnt vmcnt(4)
	v_fmac_f32_e32 v61, v13, v1
	s_waitcnt vmcnt(3)
	v_fmac_f32_e32 v62, v14, v1
	s_waitcnt vmcnt(2)
	v_fmac_f32_e32 v63, v15, v1
	s_waitcnt vmcnt(1)
	v_fmac_f32_e32 v64, v16, v1
	s_waitcnt vmcnt(0)
	v_fmac_f32_e32 v65, v17, v1
	global_store_dword v[130:131], v34, off offset:384
	global_store_dword v[192:193], v35, off offset:384
	global_store_dword v[114:115], v36, off offset:384
	global_store_dword v[116:117], v37, off offset:384
	global_store_dword v[190:191], v38, off offset:384
	global_store_dword v[186:187], v39, off offset:384
	global_store_dword v[188:189], v40, off offset:384
	global_store_dword v[118:119], v41, off offset:384
	global_store_dword v[112:113], v42, off offset:384
	global_store_dword v[120:121], v43, off offset:384
	global_store_dword v[84:85], v44, off offset:384
	global_store_dword v[122:123], v45, off offset:384
	global_store_dword v[82:83], v46, off offset:384
	global_store_dword v[124:125], v47, off offset:384
	global_store_dword v[92:93], v48, off offset:384
	global_store_dword v[126:127], v49, off offset:384
	global_store_dword v[94:95], v50, off offset:384
	global_store_dword v[128:129], v51, off offset:384
	global_store_dword v[96:97], v52, off offset:384
	global_store_dword v[98:99], v53, off offset:384
	global_store_dword v[210:211], v54, off offset:384
	global_store_dword v[100:101], v55, off offset:384
	global_store_dword v[212:213], v56, off offset:384
	global_store_dword v[102:103], v57, off offset:384
	global_store_dword v[214:215], v58, off offset:384
	global_store_dword v[104:105], v59, off offset:384
	global_store_dword v[90:91], v60, off offset:384
	global_store_dword v[106:107], v61, off offset:384
	global_store_dword v[86:87], v62, off offset:384
	global_store_dword v[108:109], v63, off offset:384
	global_store_dword v[88:89], v64, off offset:384
	global_store_dword v[110:111], v65, off offset:384
	s_cbranch_scc0 .LBB0_643

; DI unsigned swz(int row, int chunk) { return (unsigned)row * 128u + (unsigned)((chunk ^ ((row >> 1) & 7)) << 4); }
; #define MFMA32(a, b, c) __builtin_amdgcn_mfma_f32_32x32x16_bf16((a), (b), (c), 0, 0, 0)
;     ...
;         for (int kt = 0; kt < nk; ++kt) {
; #pragma unroll
;             for (int i = 0; i < 4; ++i) *(u32x4*)(lds + swz(lr + 32 * i, lc)) = ra[i];
; #pragma unroll
;             for (int i = 0; i < 8; ++i) *(u32x4*)(lds + 16384 + swz(lr + 32 * i, lc)) = rb[i];
;             __syncthreads();
;             if (kt + 1 < nk) {
; #pragma unroll
;                 for (int i = 0; i < 4; ++i) ra[i] = *(const u32x4*)((Au + (size_t)(32 * i) * lda + (kt + 1) * 64) + voA);
; #pragma unroll
;                 for (int i = 0; i < 8; ++i) rb[i] = *(const u32x4*)((Bu + (size_t)(32 * i) * ldb + (kt + 1) * 64) + voB);
;             }
;             __builtin_amdgcn_s_setprio(1);
; #pragma unroll 2
;             for (int ks = 0; ks < 4; ++ks) {
;                 bf16x8 af[2], bfr[4];
;                 const unsigned xo = (c0 ^ (unsigned)(2 * ks)) << 4;
; #pragma unroll
;                 for (int i = 0; i < 2; ++i) af[i] = *(const bf16x8*)(lds + (roA + xo) + i * 4096);
; #pragma unroll
;                 for (int j = 0; j < 4; ++j) bfr[j] = *(const bf16x8*)(lds + (roB + xo) + j * 4096);
; #pragma unroll
;                 for (int i = 0; i < 2; ++i)
; #pragma unroll
;                     for (int j = 0; j < 4; ++j) acc[i][j] = MFMA32(af[i], bfr[j], acc[i][j]);
;             }
;             __builtin_amdgcn_s_setprio(0);
;             __syncthreads();
.LBB0_734:
	s_mov_b32 s4, s7
	s_add_i32 s7, s7, 1
	s_cmp_lg_u32 s4, 15
	s_waitcnt vmcnt(9)
	ds_write_b128 v206, v[148:151]
	ds_write_b128 v206, v[144:147] offset:4096
	ds_write_b128 v206, v[152:155] offset:8192
	s_waitcnt vmcnt(7)
	ds_write_b128 v206, v[156:159] offset:12288
	ds_write_b128 v206, v[160:163] offset:16384
	s_waitcnt vmcnt(6)
	ds_write_b128 v206, v[164:167] offset:20480
	s_waitcnt vmcnt(5)
	ds_write_b128 v206, v[168:171] offset:24576
	s_waitcnt vmcnt(4)
	ds_write_b128 v206, v[172:175] offset:28672
	s_waitcnt vmcnt(3)
	ds_write_b128 v206, v[176:179] offset:32768
	s_waitcnt vmcnt(2)
	ds_write_b128 v206, v[180:183] offset:36864
	s_waitcnt vmcnt(1)
	ds_write_b128 v206, v[184:187] offset:40960
	s_waitcnt vmcnt(0)
	ds_write_b128 v206, v[188:191] offset:45056
	s_waitcnt lgkmcnt(0)
	s_barrier
	s_cbranch_scc0 .LBB0_736
	s_lshl_b32 s10, s7, 7
	s_mov_b32 s11, 0
	s_setprio 1
	v_xor_b32_e32 v1, 0, v201
	v_add_u32_e32 v10, v202, v1
	v_add_u32_e32 v1, v203, v1
	ds_read_b128 v[2:5], v10
	ds_read_b128 v[6:9], v1 offset:16384
	ds_read_b128 v[10:13], v10 offset:4096
	ds_read_b128 v[208:211], v1 offset:20480
	ds_read_b128 v[212:215], v1 offset:24576
	ds_read_b128 v[218:221], v1 offset:28672
	s_waitcnt lgkmcnt(4)
	v_mfma_f32_32x32x16_bf16 v[128:143], v[2:5], v[6:9], v[128:143]
	v_lshl_add_u64 v[222:223], v[196:197], 0, s[10:11]
	global_load_dwordx4 v[148:151], v[222:223], off
	s_add_u32 s10, s10, 0x10000
	s_mov_b32 s9, 32
	v_xor_b32_e32 v1, s9, v201
	v_add_u32_e32 v14, v202, v1
	v_add_u32_e32 v1, v203, v1
	s_waitcnt lgkmcnt(2)
	v_mfma_f32_32x32x16_bf16 v[112:127], v[2:5], v[208:211], v[112:127]
	v_lshl_add_u64 v[224:225], v[196:197], 0, s[10:11]
	global_load_dwordx4 v[144:147], v[224:225], off
	s_add_u32 s10, s10, 0x10000
	s_waitcnt lgkmcnt(1)
	v_mfma_f32_32x32x16_bf16 v[48:63], v[2:5], v[212:215], v[48:63]
	v_lshl_add_u64 v[226:227], v[196:197], 0, s[10:11]
	global_load_dwordx4 v[152:155], v[226:227], off
	s_add_u32 s10, s10, 0x10000
	s_waitcnt lgkmcnt(0)
	v_mfma_f32_32x32x16_bf16 v[64:79], v[2:5], v[218:221], v[64:79]
	v_lshl_add_u64 v[222:223], v[196:197], 0, s[10:11]
	global_load_dwordx4 v[156:159], v[222:223], off
	s_sub_u32 s10, s10, 0x30000
	v_mfma_f32_32x32x16_bf16 v[80:95], v[10:13], v[6:9], v[80:95]
	v_lshl_add_u64 v[224:225], v[198:199], 0, s[10:11]
	global_load_dwordx4 v[160:163], v[224:225], off
	s_add_u32 s10, s10, 0x10000
	v_mfma_f32_32x32x16_bf16 v[96:111], v[10:13], v[208:211], v[96:111]
	v_lshl_add_u64 v[226:227], v[198:199], 0, s[10:11]
	global_load_dwordx4 v[164:167], v[226:227], off
	s_add_u32 s10, s10, 0x10000
	v_mfma_f32_32x32x16_bf16 v[16:31], v[10:13], v[212:215], v[16:31]
	v_lshl_add_u64 v[222:223], v[198:199], 0, s[10:11]
	global_load_dwordx4 v[168:171], v[222:223], off
	s_add_u32 s10, s10, 0x10000
	v_mfma_f32_32x32x16_bf16 v[32:47], v[10:13], v[218:221], v[32:47]
	v_lshl_add_u64 v[224:225], v[198:199], 0, s[10:11]
	global_load_dwordx4 v[172:175], v[224:225], off
	s_add_u32 s10, s10, 0x10000
	ds_read_b128 v[2:5], v14
	ds_read_b128 v[6:9], v1 offset:16384
	ds_read_b128 v[10:13], v14 offset:4096
	ds_read_b128 v[208:211], v1 offset:20480
	ds_read_b128 v[212:215], v1 offset:24576
	ds_read_b128 v[218:221], v1 offset:28672
	s_waitcnt lgkmcnt(4)
	v_mfma_f32_32x32x16_bf16 v[128:143], v[2:5], v[6:9], v[128:143]
	v_lshl_add_u64 v[226:227], v[198:199], 0, s[10:11]
	global_load_dwordx4 v[176:179], v[226:227], off
	s_add_u32 s10, s10, 0x10000
	s_waitcnt lgkmcnt(2)
	v_mfma_f32_32x32x16_bf16 v[112:127], v[2:5], v[208:211], v[112:127]
	v_lshl_add_u64 v[222:223], v[198:199], 0, s[10:11]
	global_load_dwordx4 v[180:183], v[222:223], off
	s_add_u32 s10, s10, 0x10000
	s_waitcnt lgkmcnt(1)
	v_mfma_f32_32x32x16_bf16 v[48:63], v[2:5], v[212:215], v[48:63]
	v_lshl_add_u64 v[224:225], v[198:199], 0, s[10:11]
	global_load_dwordx4 v[184:187], v[224:225], off
	s_add_u32 s10, s10, 0x10000
	s_waitcnt lgkmcnt(0)
	v_mfma_f32_32x32x16_bf16 v[64:79], v[2:5], v[218:221], v[64:79]
	v_lshl_add_u64 v[226:227], v[198:199], 0, s[10:11]
	global_load_dwordx4 v[188:191], v[226:227], off
	v_mfma_f32_32x32x16_bf16 v[80:95], v[10:13], v[6:9], v[80:95]
	v_mfma_f32_32x32x16_bf16 v[96:111], v[10:13], v[208:211], v[96:111]
	v_mfma_f32_32x32x16_bf16 v[16:31], v[10:13], v[212:215], v[16:31]
	v_mfma_f32_32x32x16_bf16 v[32:47], v[10:13], v[218:221], v[32:47]
	v_xor_b32_e32 v1, 64, v201
	v_add_u32_e32 v10, v202, v1
	v_add_u32_e32 v1, v203, v1
	ds_read_b128 v[2:5], v10
	ds_read_b128 v[6:9], v1 offset:16384
	ds_read_b128 v[10:13], v10 offset:4096
	ds_read_b128 v[208:211], v1 offset:20480
	ds_read_b128 v[212:215], v1 offset:24576
	ds_read_b128 v[218:221], v1 offset:28672
	s_waitcnt lgkmcnt(4)
	v_mfma_f32_32x32x16_bf16 v[128:143], v[2:5], v[6:9], v[128:143]
	s_mov_b32 s9, 96
	v_xor_b32_e32 v1, s9, v201
	v_add_u32_e32 v14, v202, v1
	v_add_u32_e32 v1, v203, v1
	s_waitcnt lgkmcnt(2)
	v_mfma_f32_32x32x16_bf16 v[112:127], v[2:5], v[208:211], v[112:127]
	s_waitcnt lgkmcnt(1)
	v_mfma_f32_32x32x16_bf16 v[48:63], v[2:5], v[212:215], v[48:63]
	s_waitcnt lgkmcnt(0)
	v_mfma_f32_32x32x16_bf16 v[64:79], v[2:5], v[218:221], v[64:79]
	v_mfma_f32_32x32x16_bf16 v[80:95], v[10:13], v[6:9], v[80:95]
	v_mfma_f32_32x32x16_bf16 v[96:111], v[10:13], v[208:211], v[96:111]
	v_mfma_f32_32x32x16_bf16 v[16:31], v[10:13], v[212:215], v[16:31]
	v_mfma_f32_32x32x16_bf16 v[32:47], v[10:13], v[218:221], v[32:47]
	ds_read_b128 v[2:5], v14
	ds_read_b128 v[6:9], v1 offset:16384
	ds_read_b128 v[10:13], v14 offset:4096
	ds_read_b128 v[208:211], v1 offset:20480
	ds_read_b128 v[212:215], v1 offset:24576
	ds_read_b128 v[218:221], v1 offset:28672
	s_waitcnt lgkmcnt(4)
	v_mfma_f32_32x32x16_bf16 v[128:143], v[2:5], v[6:9], v[128:143]
	s_waitcnt lgkmcnt(2)
	v_mfma_f32_32x32x16_bf16 v[112:127], v[2:5], v[208:211], v[112:127]
	s_waitcnt lgkmcnt(1)
	v_mfma_f32_32x32x16_bf16 v[48:63], v[2:5], v[212:215], v[48:63]
	s_waitcnt lgkmcnt(0)
	v_mfma_f32_32x32x16_bf16 v[64:79], v[2:5], v[218:221], v[64:79]
	v_mfma_f32_32x32x16_bf16 v[80:95], v[10:13], v[6:9], v[80:95]
	v_mfma_f32_32x32x16_bf16 v[96:111], v[10:13], v[208:211], v[96:111]
	v_mfma_f32_32x32x16_bf16 v[16:31], v[10:13], v[212:215], v[16:31]
	v_mfma_f32_32x32x16_bf16 v[32:47], v[10:13], v[218:221], v[32:47]
	s_branch .Lkint_done_737

; DI float sigmoidf_(float x) { return __builtin_amdgcn_rcpf(1.0f + __builtin_amdgcn_exp2f(-1.4426950408889634f * x)); }
; DI int cu(int r) { return (r & 3) + 8 * (r >> 2); }
;     template <int NI> DI void operator()(const f32x16 (&acc)[2][NI], int row0, int col0, int lane) const {
;         const unsigned lo = (unsigned)(4 * (lane >> 5) * FFH + (lane & 31));
;         bf16_t* base = Hd + (size_t)row0 * FFH + (col0 >> 1);
; #pragma unroll
;         for (int pr = 0; pr < NI / 2; ++pr)
; #pragma unroll
;             for (int mi = 0; mi < 2; ++mi)
; #pragma unroll
;                 for (int r = 0; r < 16; ++r) { const float g = acc[mi][2 * pr][r], u = acc[mi][2 * pr + 1][r]; __builtin_nontemporal_store(f2bf(g * sigmoidf_(g) * u), &(base + (32 * mi + cu(r)) * FFH + 32 * pr)[lo]); }
.Lkint_done_737:
	s_setprio 0
	s_cmp_eq_u32 s7, 16
	s_barrier
	s_cbranch_scc0 .LBB0_734
	v_mov_b32_e32 v1, v200
	v_or_b32_e32 v6, s8, v205
	v_lshrrev_b32_e32 v2, 3, v1
	v_and_b32_e32 v2, 0xfffffc, v2
	v_mul_u32_u24_e32 v2, 0xb00, v2
	v_and_or_b32 v2, v1, 31, v2
	v_mul_f32_e32 v1, 0xbfb8aa3b, v128
	v_exp_f32_e32 v1, v1
	v_add_u32_e32 v3, s6, v204
	v_mov_b64_e32 v[4:5], s[82:83]
	v_ashrrev_i32_e32 v6, 1, v6
	v_mad_i64_i32 v[4:5], s[6:7], v3, s17, v[4:5]
	v_ashrrev_i32_e32 v7, 31, v6
	v_mul_f32_e32 v3, 0xbfb8aa3b, v129
	v_lshl_add_u64 v[4:5], v[6:7], 1, v[4:5]
	v_exp_f32_e32 v6, v3
	v_add_f32_e32 v1, 1.0, v1
	v_rcp_f32_e32 v1, v1
	v_mov_b32_e32 v3, v0
	v_lshl_add_u64 v[2:3], v[2:3], 1, v[4:5]
	v_add_f32_e32 v4, 1.0, v6
	v_rcp_f32_e32 v4, v4
	v_mul_f32_e32 v1, v128, v1
	v_mul_f32_e32 v1, v112, v1
	v_cvt_pk_bf16_f32 v1, v1, s0
	global_store_short v[2:3], v1, off nt
	v_mul_f32_e32 v1, v129, v4
	v_mul_f32_e32 v4, 0xbfb8aa3b, v130
	v_exp_f32_e32 v6, v4
	v_mul_f32_e32 v1, v113, v1
	v_add_co_u32_e32 v4, vcc, s28, v2
	v_add_f32_e32 v6, 1.0, v6
	v_rcp_f32_e32 v6, v6
	v_cvt_pk_bf16_f32 v1, v1, s0
	v_addc_co_u32_e32 v5, vcc, 0, v3, vcc
	v_mul_f32_e32 v6, v130, v6
	global_store_short v[4:5], v1, off offset:1536 nt
	v_mul_f32_e32 v1, 0xbfb8aa3b, v131
	v_mul_f32_e32 v6, v114, v6
	v_exp_f32_e32 v1, v1
	v_cvt_pk_bf16_f32 v8, v6, s0
	v_add_co_u32_e32 v6, vcc, s29, v2
	v_add_f32_e32 v1, 1.0, v1
	s_nop 0
	v_addc_co_u32_e32 v7, vcc, 0, v3, vcc
	global_store_short v[6:7], v8, off offset:3072 nt
	v_mul_f32_e32 v8, 0xbfb8aa3b, v132
	v_exp_f32_e32 v10, v8
	v_rcp_f32_e32 v1, v1
	v_add_co_u32_e32 v8, vcc, s30, v2
	v_add_f32_e32 v10, 1.0, v10
	v_rcp_f32_e32 v10, v10
	v_mul_f32_e32 v1, v131, v1
	v_mul_f32_e32 v1, v115, v1
	v_cvt_pk_bf16_f32 v1, v1, s0
	v_addc_co_u32_e32 v9, vcc, 0, v3, vcc
	global_store_short v[8:9], v1, off offset:512 nt
	v_mul_f32_e32 v1, 0xbfb8aa3b, v133
	v_mul_f32_e32 v10, v132, v10
	v_exp_f32_e32 v1, v1
	v_mul_f32_e32 v10, v116, v10
	v_cvt_pk_bf16_f32 v12, v10, s0
	v_add_co_u32_e32 v10, vcc, s31, v2
	v_add_f32_e32 v1, 1.0, v1
	s_nop 0
	v_addc_co_u32_e32 v11, vcc, 0, v3, vcc
	global_store_short v[10:11], v12, off nt
	v_mul_f32_e32 v12, 0xbfb8aa3b, v134
	v_exp_f32_e32 v14, v12
	v_rcp_f32_e32 v1, v1
	v_add_co_u32_e32 v12, vcc, s34, v2
	v_add_f32_e32 v14, 1.0, v14
	v_mul_f32_e32 v1, v133, v1
	v_rcp_f32_e32 v14, v14
	v_mul_f32_e32 v1, v117, v1
	v_cvt_pk_bf16_f32 v1, v1, s0
	v_addc_co_u32_e32 v13, vcc, 0, v3, vcc
	global_store_short v[12:13], v1, off offset:1536 nt
	v_mul_f32_e32 v1, 0xbfb8aa3b, v135
	v_exp_f32_e32 v1, v1
	v_mul_f32_e32 v14, v134, v14
	v_mul_f32_e32 v14, v118, v14
	v_cvt_pk_bf16_f32 v112, v14, s0
	v_add_co_u32_e32 v14, vcc, s35, v2
	v_add_f32_e32 v1, 1.0, v1
	s_nop 0
	v_addc_co_u32_e32 v15, vcc, 0, v3, vcc
	global_store_short v[14:15], v112, off offset:3072 nt
	v_mul_f32_e32 v112, 0xbfb8aa3b, v136
	v_rcp_f32_e32 v1, v1
	v_exp_f32_e32 v114, v112
	v_add_co_u32_e32 v112, vcc, s46, v2
	v_mul_f32_e32 v1, v135, v1
	v_add_f32_e32 v114, 1.0, v114
	v_mul_f32_e32 v1, v119, v1
	v_rcp_f32_e32 v114, v114
	v_cvt_pk_bf16_f32 v1, v1, s0
	v_addc_co_u32_e32 v113, vcc, 0, v3, vcc
	global_store_short v[112:113], v1, off offset:512 nt
	v_mul_f32_e32 v1, 0xbfb8aa3b, v137
	v_exp_f32_e32 v1, v1
	v_mul_f32_e32 v114, v136, v114
	v_mul_f32_e32 v114, v120, v114
	v_cvt_pk_bf16_f32 v116, v114, s0
	v_add_co_u32_e32 v114, vcc, s47, v2
	v_add_f32_e32 v1, 1.0, v1
	s_nop 0
	v_addc_co_u32_e32 v115, vcc, 0, v3, vcc
	v_rcp_f32_e32 v1, v1
	global_store_short v[114:115], v116, off nt
	v_mul_f32_e32 v116, 0xbfb8aa3b, v138
	v_exp_f32_e32 v118, v116
	v_mul_f32_e32 v1, v137, v1
	v_mul_f32_e32 v1, v121, v1
	v_add_co_u32_e32 v116, vcc, s62, v2
	v_add_f32_e32 v118, 1.0, v118
	v_cvt_pk_bf16_f32 v1, v1, s0
	v_addc_co_u32_e32 v117, vcc, 0, v3, vcc
	v_rcp_f32_e32 v118, v118
	global_store_short v[116:117], v1, off offset:1536 nt
	v_mul_f32_e32 v1, 0xbfb8aa3b, v139
	v_exp_f32_e32 v1, v1
	v_mul_f32_e32 v118, v138, v118
	v_mul_f32_e32 v118, v122, v118
	v_cvt_pk_bf16_f32 v120, v118, s0
	v_add_f32_e32 v1, 1.0, v1
	v_add_co_u32_e32 v118, vcc, s63, v2
	v_rcp_f32_e32 v1, v1
	s_nop 0
	v_addc_co_u32_e32 v119, vcc, 0, v3, vcc
	global_store_short v[118:119], v120, off offset:3072 nt
	v_mul_f32_e32 v120, 0xbfb8aa3b, v140
	v_exp_f32_e32 v122, v120
	v_mul_f32_e32 v1, v139, v1
	v_mul_f32_e32 v1, v123, v1
	v_add_co_u32_e32 v120, vcc, s68, v2
	v_cvt_pk_bf16_f32 v1, v1, s0
	s_nop 0
	v_addc_co_u32_e32 v121, vcc, 0, v3, vcc
	v_add_f32_e32 v122, 1.0, v122
	v_rcp_f32_e32 v122, v122
	global_store_short v[120:121], v1, off offset:512 nt
	v_mul_f32_e32 v1, 0xbfb8aa3b, v141
	v_exp_f32_e32 v1, v1
	v_mul_f32_e32 v122, v140, v122
	v_mul_f32_e32 v122, v124, v122
	v_cvt_pk_bf16_f32 v124, v122, s0
	v_add_f32_e32 v1, 1.0, v1
	v_rcp_f32_e32 v1, v1
	v_add_co_u32_e32 v122, vcc, s69, v2
	s_add_i32 s96, s96, s81
	s_nop 0
	v_addc_co_u32_e32 v123, vcc, 0, v3, vcc
	global_store_short v[122:123], v124, off nt
	v_mul_f32_e32 v124, 0xbfb8aa3b, v142
	v_exp_f32_e32 v128, v124
	v_mul_f32_e32 v1, v141, v1
	v_mul_f32_e32 v1, v125, v1
	v_add_co_u32_e32 v124, vcc, s70, v2
	v_cvt_pk_bf16_f32 v1, v1, s0
	s_nop 0
	v_addc_co_u32_e32 v125, vcc, 0, v3, vcc
	v_add_f32_e32 v128, 1.0, v128
	global_store_short v[124:125], v1, off offset:1536 nt
	v_mul_f32_e32 v1, 0xbfb8aa3b, v143
	v_rcp_f32_e32 v128, v128
	v_exp_f32_e32 v1, v1
	s_cmpk_gt_i32 s96, 0x5ab
	v_mul_f32_e32 v128, v142, v128
	v_add_f32_e32 v1, 1.0, v1
	v_mul_f32_e32 v126, v126, v128
	v_rcp_f32_e32 v1, v1
	v_add_co_u32_e32 v128, vcc, s71, v2
	v_cvt_pk_bf16_f32 v126, v126, s0
	s_nop 0
	v_addc_co_u32_e32 v129, vcc, 0, v3, vcc
	global_store_short v[128:129], v126, off offset:3072 nt
; DI float sigmoidf_(float x) { return __builtin_amdgcn_rcpf(1.0f + __builtin_amdgcn_exp2f(-1.4426950408889634f * x)); }
; DI int cu(int r) { return (r & 3) + 8 * (r >> 2); }
;     template <int NI> DI void operator()(const f32x16 (&acc)[2][NI], int row0, int col0, int lane) const {
;     ...
;         for (int pr = 0; pr < NI / 2; ++pr)
; #pragma unroll
;             for (int mi = 0; mi < 2; ++mi)
; #pragma unroll
;                 for (int r = 0; r < 16; ++r) { const float g = acc[mi][2 * pr][r], u = acc[mi][2 * pr + 1][r]; __builtin_nontemporal_store(f2bf(g * sigmoidf_(g) * u), &(base + (32 * mi + cu(r)) * FFH + 32 * pr)[lo]); }
	v_mul_f32_e32 v126, 0xbfb8aa3b, v80
	v_exp_f32_e32 v130, v126
	v_mul_f32_e32 v1, v143, v1
	v_mul_f32_e32 v1, v127, v1
	v_add_co_u32_e32 v126, vcc, s72, v2
	v_cvt_pk_bf16_f32 v1, v1, s0
	s_nop 0
	v_addc_co_u32_e32 v127, vcc, 0, v3, vcc
	v_add_f32_e32 v130, 1.0, v130
	global_store_short v[126:127], v1, off offset:512 nt
	v_mul_f32_e32 v1, 0xbfb8aa3b, v81
	v_rcp_f32_e32 v130, v130
	v_exp_f32_e32 v1, v1
	v_mul_f32_e32 v80, v80, v130
	v_add_f32_e32 v1, 1.0, v1
	v_mul_f32_e32 v80, v96, v80
	v_rcp_f32_e32 v1, v1
	v_add_co_u32_e32 v130, vcc, s73, v2
	v_cvt_pk_bf16_f32 v80, v80, s0
	s_nop 0
	v_addc_co_u32_e32 v131, vcc, 0, v3, vcc
	global_store_short v[130:131], v80, off nt
	v_mul_f32_e32 v80, 0xbfb8aa3b, v82
	v_exp_f32_e32 v96, v80
	v_mul_f32_e32 v1, v81, v1
	v_mul_f32_e32 v1, v97, v1
	v_add_co_u32_e32 v80, vcc, s74, v2
	v_cvt_pk_bf16_f32 v1, v1, s0
	s_nop 0
	v_addc_co_u32_e32 v81, vcc, 0, v3, vcc
	v_add_f32_e32 v96, 1.0, v96
	global_store_short v[80:81], v1, off offset:1536 nt
	v_mul_f32_e32 v1, 0xbfb8aa3b, v83
	v_rcp_f32_e32 v96, v96
	v_exp_f32_e32 v1, v1
	v_mul_f32_e32 v82, v82, v96
	v_add_f32_e32 v1, 1.0, v1
	v_mul_f32_e32 v82, v98, v82
	v_rcp_f32_e32 v1, v1
	v_add_co_u32_e32 v96, vcc, s75, v2
	v_cvt_pk_bf16_f32 v82, v82, s0
	s_nop 0
	v_addc_co_u32_e32 v97, vcc, 0, v3, vcc
	global_store_short v[96:97], v82, off offset:3072 nt
	v_mul_f32_e32 v82, 0xbfb8aa3b, v84
	v_exp_f32_e32 v98, v82
	v_mul_f32_e32 v1, v83, v1
	v_mul_f32_e32 v1, v99, v1
	v_add_co_u32_e32 v82, vcc, s16, v2
	v_cvt_pk_bf16_f32 v1, v1, s0
	s_nop 0
	v_addc_co_u32_e32 v83, vcc, 0, v3, vcc
	v_add_f32_e32 v98, 1.0, v98
	global_store_short v[82:83], v1, off offset:512 nt
	v_mul_f32_e32 v1, 0xbfb8aa3b, v85
	v_rcp_f32_e32 v98, v98
	v_exp_f32_e32 v1, v1
	v_mul_f32_e32 v84, v84, v98
	v_add_f32_e32 v1, 1.0, v1
	v_mul_f32_e32 v84, v100, v84
	v_rcp_f32_e32 v1, v1
	v_add_co_u32_e32 v98, vcc, s78, v2
	v_cvt_pk_bf16_f32 v84, v84, s0
	s_nop 0
	v_addc_co_u32_e32 v99, vcc, 0, v3, vcc
	global_store_short v[98:99], v84, off nt
	v_mul_f32_e32 v84, 0xbfb8aa3b, v86
	v_exp_f32_e32 v100, v84
	v_mul_f32_e32 v1, v85, v1
	v_mul_f32_e32 v1, v101, v1
	v_add_co_u32_e32 v84, vcc, s79, v2
	v_cvt_pk_bf16_f32 v1, v1, s0
	s_nop 0
	v_addc_co_u32_e32 v85, vcc, 0, v3, vcc
	v_add_f32_e32 v100, 1.0, v100
	global_store_short v[84:85], v1, off offset:1536 nt
	v_mul_f32_e32 v1, 0xbfb8aa3b, v87
	v_rcp_f32_e32 v100, v100
	v_exp_f32_e32 v1, v1
	v_mul_f32_e32 v86, v86, v100
	v_add_f32_e32 v1, 1.0, v1
	v_mul_f32_e32 v86, v102, v86
	v_rcp_f32_e32 v1, v1
	v_add_co_u32_e32 v100, vcc, s86, v2
	v_cvt_pk_bf16_f32 v86, v86, s0
	s_nop 0
	v_addc_co_u32_e32 v101, vcc, 0, v3, vcc
	global_store_short v[100:101], v86, off offset:3072 nt
	v_mul_f32_e32 v86, 0xbfb8aa3b, v88
	v_exp_f32_e32 v102, v86
	v_mul_f32_e32 v1, v87, v1
	v_mul_f32_e32 v1, v103, v1
	v_add_co_u32_e32 v86, vcc, s87, v2
	v_cvt_pk_bf16_f32 v1, v1, s0
	s_nop 0
	v_addc_co_u32_e32 v87, vcc, 0, v3, vcc
	v_add_f32_e32 v102, 1.0, v102
	global_store_short v[86:87], v1, off offset:512 nt
	v_mul_f32_e32 v1, 0xbfb8aa3b, v89
	v_rcp_f32_e32 v102, v102
	v_exp_f32_e32 v1, v1
	v_mul_f32_e32 v88, v88, v102
	v_add_f32_e32 v1, 1.0, v1
	v_mul_f32_e32 v88, v104, v88
	v_rcp_f32_e32 v1, v1
	v_add_co_u32_e32 v102, vcc, s88, v2
	v_cvt_pk_bf16_f32 v88, v88, s0
	s_nop 0
	v_addc_co_u32_e32 v103, vcc, 0, v3, vcc
	global_store_short v[102:103], v88, off nt
	v_mul_f32_e32 v88, 0xbfb8aa3b, v90
	v_exp_f32_e32 v104, v88
	v_mul_f32_e32 v1, v89, v1
	v_mul_f32_e32 v1, v105, v1
	v_add_co_u32_e32 v88, vcc, s89, v2
	v_cvt_pk_bf16_f32 v1, v1, s0
	s_nop 0
	v_addc_co_u32_e32 v89, vcc, 0, v3, vcc
	v_add_f32_e32 v104, 1.0, v104
	global_store_short v[88:89], v1, off offset:1536 nt
	v_mul_f32_e32 v1, 0xbfb8aa3b, v91
	v_rcp_f32_e32 v104, v104
	v_exp_f32_e32 v1, v1
	v_mul_f32_e32 v90, v90, v104
	v_add_f32_e32 v1, 1.0, v1
	v_mul_f32_e32 v90, v106, v90
	v_rcp_f32_e32 v1, v1
	v_add_co_u32_e32 v104, vcc, s90, v2
	v_cvt_pk_bf16_f32 v90, v90, s0
	s_nop 0
	v_addc_co_u32_e32 v105, vcc, 0, v3, vcc
	global_store_short v[104:105], v90, off offset:3072 nt
	v_mul_f32_e32 v90, 0xbfb8aa3b, v92
	v_exp_f32_e32 v106, v90
	v_mul_f32_e32 v1, v91, v1
	v_mul_f32_e32 v1, v107, v1
	v_add_co_u32_e32 v90, vcc, s91, v2
	v_cvt_pk_bf16_f32 v1, v1, s0
	s_nop 0
	v_addc_co_u32_e32 v91, vcc, 0, v3, vcc
	v_add_f32_e32 v106, 1.0, v106
	global_store_short v[90:91], v1, off offset:512 nt
	v_mul_f32_e32 v1, 0xbfb8aa3b, v93
	v_rcp_f32_e32 v106, v106
	v_exp_f32_e32 v1, v1
	v_mul_f32_e32 v92, v92, v106
	v_add_f32_e32 v1, 1.0, v1
	v_mul_f32_e32 v92, v108, v92
	v_rcp_f32_e32 v1, v1
	v_add_co_u32_e32 v106, vcc, s92, v2
	v_cvt_pk_bf16_f32 v92, v92, s0
	s_nop 0
	v_addc_co_u32_e32 v107, vcc, 0, v3, vcc
	global_store_short v[106:107], v92, off nt
	v_mul_f32_e32 v92, 0xbfb8aa3b, v94
	v_exp_f32_e32 v108, v92
	v_mul_f32_e32 v1, v93, v1
	v_mul_f32_e32 v1, v109, v1
	v_add_co_u32_e32 v92, vcc, s93, v2
	v_cvt_pk_bf16_f32 v1, v1, s0
	s_nop 0
	v_addc_co_u32_e32 v93, vcc, 0, v3, vcc
	v_add_f32_e32 v108, 1.0, v108
	global_store_short v[92:93], v1, off offset:1536 nt
	v_mul_f32_e32 v1, 0xbfb8aa3b, v95
	v_rcp_f32_e32 v108, v108
	v_exp_f32_e32 v1, v1
	v_mul_f32_e32 v94, v94, v108
	v_add_f32_e32 v1, 1.0, v1
	v_mul_f32_e32 v94, v110, v94
	v_rcp_f32_e32 v1, v1
	v_add_co_u32_e32 v108, vcc, s94, v2
	v_cvt_pk_bf16_f32 v94, v94, s0
	s_nop 0
	v_addc_co_u32_e32 v109, vcc, 0, v3, vcc
	global_store_short v[108:109], v94, off offset:3072 nt
	v_mul_f32_e32 v94, 0xbfb8aa3b, v48
	v_exp_f32_e32 v110, v94
	v_mul_f32_e32 v1, v95, v1
	v_mul_f32_e32 v1, v111, v1
	v_add_co_u32_e32 v94, vcc, s95, v2
	v_cvt_pk_bf16_f32 v1, v1, s0
	s_nop 0
	v_addc_co_u32_e32 v95, vcc, 0, v3, vcc
	v_add_f32_e32 v110, 1.0, v110
; DI float sigmoidf_(float x) { return __builtin_amdgcn_rcpf(1.0f + __builtin_amdgcn_exp2f(-1.4426950408889634f * x)); }
; DI int cu(int r) { return (r & 3) + 8 * (r >> 2); }
;     template <int NI> DI void operator()(const f32x16 (&acc)[2][NI], int row0, int col0, int lane) const {
;     ...
;         for (int pr = 0; pr < NI / 2; ++pr)
; #pragma unroll
;             for (int mi = 0; mi < 2; ++mi)
; #pragma unroll
;                 for (int r = 0; r < 16; ++r) { const float g = acc[mi][2 * pr][r], u = acc[mi][2 * pr + 1][r]; __builtin_nontemporal_store(f2bf(g * sigmoidf_(g) * u), &(base + (32 * mi + cu(r)) * FFH + 32 * pr)[lo]); }
	global_store_short v[94:95], v1, off offset:512 nt
	v_mul_f32_e32 v1, 0xbfb8aa3b, v49
	v_rcp_f32_e32 v110, v110
	v_exp_f32_e32 v1, v1
	v_mul_f32_e32 v48, v48, v110
	v_add_f32_e32 v1, 1.0, v1
	v_mul_f32_e32 v48, v64, v48
	v_rcp_f32_e32 v1, v1
	v_cvt_pk_bf16_f32 v48, v48, s0
	global_store_short v[2:3], v48, off offset:64 nt
	v_mul_f32_e32 v2, 0xbfb8aa3b, v50
	v_exp_f32_e32 v2, v2
	v_mul_f32_e32 v1, v49, v1
	v_mul_f32_e32 v1, v65, v1
	v_cvt_pk_bf16_f32 v1, v1, s0
	v_add_f32_e32 v2, 1.0, v2
	global_store_short v[4:5], v1, off offset:1600 nt
	v_mul_f32_e32 v1, 0xbfb8aa3b, v51
	v_rcp_f32_e32 v2, v2
	v_exp_f32_e32 v1, v1
	v_mul_f32_e32 v3, 0xbfb8aa3b, v30
	v_exp_f32_e32 v3, v3
	v_mul_f32_e32 v2, v50, v2
	v_add_f32_e32 v1, 1.0, v1
	v_mul_f32_e32 v2, v66, v2
	v_rcp_f32_e32 v1, v1
	v_cvt_pk_bf16_f32 v2, v2, s0
	global_store_short v[6:7], v2, off offset:3136 nt
	v_mul_f32_e32 v2, 0xbfb8aa3b, v52
	v_exp_f32_e32 v2, v2
	v_mul_f32_e32 v1, v51, v1
	v_mul_f32_e32 v1, v67, v1
	v_cvt_pk_bf16_f32 v1, v1, s0
	v_add_f32_e32 v2, 1.0, v2
	global_store_short v[8:9], v1, off offset:576 nt
	v_mul_f32_e32 v1, 0xbfb8aa3b, v53
	v_rcp_f32_e32 v2, v2
	v_exp_f32_e32 v1, v1
	v_mul_f32_e32 v2, v52, v2
	v_add_f32_e32 v1, 1.0, v1
	v_mul_f32_e32 v2, v68, v2
	v_rcp_f32_e32 v1, v1
	v_cvt_pk_bf16_f32 v2, v2, s0
	global_store_short v[10:11], v2, off offset:64 nt
	v_mul_f32_e32 v2, 0xbfb8aa3b, v54
	v_exp_f32_e32 v2, v2
	v_mul_f32_e32 v1, v53, v1
	v_mul_f32_e32 v1, v69, v1
	v_cvt_pk_bf16_f32 v1, v1, s0
	v_add_f32_e32 v2, 1.0, v2
	global_store_short v[12:13], v1, off offset:1600 nt
	v_mul_f32_e32 v1, 0xbfb8aa3b, v55
	v_rcp_f32_e32 v2, v2
	v_exp_f32_e32 v1, v1
	v_mul_f32_e32 v2, v54, v2
	v_add_f32_e32 v1, 1.0, v1
	v_mul_f32_e32 v2, v70, v2
	v_rcp_f32_e32 v1, v1
	v_cvt_pk_bf16_f32 v2, v2, s0
	global_store_short v[14:15], v2, off offset:3136 nt
	v_mul_f32_e32 v2, 0xbfb8aa3b, v56
	v_exp_f32_e32 v2, v2
	v_mul_f32_e32 v1, v55, v1
	v_mul_f32_e32 v1, v71, v1
	v_cvt_pk_bf16_f32 v1, v1, s0
	v_add_f32_e32 v2, 1.0, v2
	global_store_short v[112:113], v1, off offset:576 nt
	v_mul_f32_e32 v1, 0xbfb8aa3b, v57
	v_rcp_f32_e32 v2, v2
	v_exp_f32_e32 v1, v1
	v_mul_f32_e32 v2, v56, v2
	v_add_f32_e32 v1, 1.0, v1
	v_mul_f32_e32 v2, v72, v2
	v_rcp_f32_e32 v1, v1
	v_cvt_pk_bf16_f32 v2, v2, s0
	global_store_short v[114:115], v2, off offset:64 nt
	v_mul_f32_e32 v2, 0xbfb8aa3b, v58
	v_exp_f32_e32 v2, v2
	v_mul_f32_e32 v1, v57, v1
	v_mul_f32_e32 v1, v73, v1
	v_cvt_pk_bf16_f32 v1, v1, s0
	v_add_f32_e32 v2, 1.0, v2
	global_store_short v[116:117], v1, off offset:1600 nt
	v_mul_f32_e32 v1, 0xbfb8aa3b, v59
	v_rcp_f32_e32 v2, v2
	v_exp_f32_e32 v1, v1
	v_mul_f32_e32 v2, v58, v2
	v_add_f32_e32 v1, 1.0, v1
	v_mul_f32_e32 v2, v74, v2
	v_rcp_f32_e32 v1, v1
	v_cvt_pk_bf16_f32 v2, v2, s0
	global_store_short v[118:119], v2, off offset:3136 nt
	v_mul_f32_e32 v2, 0xbfb8aa3b, v60
	v_exp_f32_e32 v2, v2
	v_mul_f32_e32 v1, v59, v1
	v_mul_f32_e32 v1, v75, v1
	v_cvt_pk_bf16_f32 v1, v1, s0
	v_add_f32_e32 v2, 1.0, v2
	global_store_short v[120:121], v1, off offset:576 nt
	v_mul_f32_e32 v1, 0xbfb8aa3b, v61
	v_rcp_f32_e32 v2, v2
	v_exp_f32_e32 v1, v1
	v_mul_f32_e32 v2, v60, v2
	v_add_f32_e32 v1, 1.0, v1
	v_mul_f32_e32 v2, v76, v2
	v_rcp_f32_e32 v1, v1
	v_cvt_pk_bf16_f32 v2, v2, s0
	global_store_short v[122:123], v2, off offset:64 nt
	v_mul_f32_e32 v2, 0xbfb8aa3b, v62
	v_exp_f32_e32 v2, v2
	v_mul_f32_e32 v1, v61, v1
	v_mul_f32_e32 v1, v77, v1
	v_cvt_pk_bf16_f32 v1, v1, s0
	v_add_f32_e32 v2, 1.0, v2
	global_store_short v[124:125], v1, off offset:1600 nt
	v_mul_f32_e32 v1, 0xbfb8aa3b, v63
	v_rcp_f32_e32 v2, v2
	v_exp_f32_e32 v1, v1
	v_mul_f32_e32 v2, v62, v2
	v_add_f32_e32 v1, 1.0, v1
	v_mul_f32_e32 v2, v78, v2
	v_rcp_f32_e32 v1, v1
	v_cvt_pk_bf16_f32 v2, v2, s0
	global_store_short v[128:129], v2, off offset:3136 nt
	v_mul_f32_e32 v2, 0xbfb8aa3b, v16
	v_exp_f32_e32 v2, v2
	v_mul_f32_e32 v1, v63, v1
	v_mul_f32_e32 v1, v79, v1
; DI float sigmoidf_(float x) { return __builtin_amdgcn_rcpf(1.0f + __builtin_amdgcn_exp2f(-1.4426950408889634f * x)); }
; DI int cu(int r) { return (r & 3) + 8 * (r >> 2); }
;     template <int NI> DI void operator()(const f32x16 (&acc)[2][NI], int row0, int col0, int lane) const {
;     ...
;         for (int pr = 0; pr < NI / 2; ++pr)
; #pragma unroll
;             for (int mi = 0; mi < 2; ++mi)
; #pragma unroll
;                 for (int r = 0; r < 16; ++r) { const float g = acc[mi][2 * pr][r], u = acc[mi][2 * pr + 1][r]; __builtin_nontemporal_store(f2bf(g * sigmoidf_(g) * u), &(base + (32 * mi + cu(r)) * FFH + 32 * pr)[lo]); }
	v_cvt_pk_bf16_f32 v1, v1, s0
	v_add_f32_e32 v2, 1.0, v2
	global_store_short v[126:127], v1, off offset:576 nt
	v_mul_f32_e32 v1, 0xbfb8aa3b, v17
	v_rcp_f32_e32 v2, v2
	v_exp_f32_e32 v1, v1
	v_mul_f32_e32 v2, v16, v2
	v_add_f32_e32 v1, 1.0, v1
	v_mul_f32_e32 v2, v32, v2
	v_rcp_f32_e32 v1, v1
	v_cvt_pk_bf16_f32 v2, v2, s0
	global_store_short v[130:131], v2, off offset:64 nt
	v_mul_f32_e32 v2, 0xbfb8aa3b, v18
	v_exp_f32_e32 v2, v2
	v_mul_f32_e32 v1, v17, v1
	v_mul_f32_e32 v1, v33, v1
	v_cvt_pk_bf16_f32 v1, v1, s0
	v_add_f32_e32 v2, 1.0, v2
	global_store_short v[80:81], v1, off offset:1600 nt
	v_mul_f32_e32 v1, 0xbfb8aa3b, v19
	v_rcp_f32_e32 v2, v2
	v_exp_f32_e32 v1, v1
	v_mul_f32_e32 v2, v18, v2
	v_add_f32_e32 v1, 1.0, v1
	v_mul_f32_e32 v2, v34, v2
	v_rcp_f32_e32 v1, v1
	v_cvt_pk_bf16_f32 v2, v2, s0
	global_store_short v[96:97], v2, off offset:3136 nt
	v_mul_f32_e32 v2, 0xbfb8aa3b, v20
	v_exp_f32_e32 v2, v2
	v_mul_f32_e32 v1, v19, v1
	v_mul_f32_e32 v1, v35, v1
	v_cvt_pk_bf16_f32 v1, v1, s0
	v_add_f32_e32 v2, 1.0, v2
	global_store_short v[82:83], v1, off offset:576 nt
	v_mul_f32_e32 v1, 0xbfb8aa3b, v21
	v_rcp_f32_e32 v2, v2
	v_exp_f32_e32 v1, v1
	v_mul_f32_e32 v2, v20, v2
	v_add_f32_e32 v1, 1.0, v1
	v_mul_f32_e32 v2, v36, v2
	v_rcp_f32_e32 v1, v1
	v_cvt_pk_bf16_f32 v2, v2, s0
	global_store_short v[98:99], v2, off offset:64 nt
	v_mul_f32_e32 v2, 0xbfb8aa3b, v22
	v_exp_f32_e32 v2, v2
	v_mul_f32_e32 v1, v21, v1
	v_mul_f32_e32 v1, v37, v1
	v_cvt_pk_bf16_f32 v1, v1, s0
	v_add_f32_e32 v2, 1.0, v2
	global_store_short v[84:85], v1, off offset:1600 nt
	v_mul_f32_e32 v1, 0xbfb8aa3b, v23
	v_rcp_f32_e32 v2, v2
	v_exp_f32_e32 v1, v1
	v_mul_f32_e32 v2, v22, v2
	v_add_f32_e32 v1, 1.0, v1
	v_mul_f32_e32 v2, v38, v2
	v_rcp_f32_e32 v1, v1
	v_cvt_pk_bf16_f32 v2, v2, s0
	global_store_short v[100:101], v2, off offset:3136 nt
	v_mul_f32_e32 v2, 0xbfb8aa3b, v24
	v_exp_f32_e32 v2, v2
	v_mul_f32_e32 v1, v23, v1
	v_mul_f32_e32 v1, v39, v1
	v_cvt_pk_bf16_f32 v1, v1, s0
	v_add_f32_e32 v2, 1.0, v2
	global_store_short v[86:87], v1, off offset:576 nt
	v_mul_f32_e32 v1, 0xbfb8aa3b, v25
	v_rcp_f32_e32 v2, v2
	v_exp_f32_e32 v1, v1
	v_mul_f32_e32 v2, v24, v2
	v_add_f32_e32 v1, 1.0, v1
	v_mul_f32_e32 v2, v40, v2
	v_rcp_f32_e32 v1, v1
	v_cvt_pk_bf16_f32 v2, v2, s0
	global_store_short v[102:103], v2, off offset:64 nt
	v_mul_f32_e32 v2, 0xbfb8aa3b, v26
	v_exp_f32_e32 v2, v2
	v_mul_f32_e32 v1, v25, v1
	v_mul_f32_e32 v1, v41, v1
	v_cvt_pk_bf16_f32 v1, v1, s0
	v_add_f32_e32 v2, 1.0, v2
	global_store_short v[88:89], v1, off offset:1600 nt
	v_mul_f32_e32 v1, 0xbfb8aa3b, v27
	v_rcp_f32_e32 v2, v2
	v_exp_f32_e32 v1, v1
	v_mul_f32_e32 v2, v26, v2
	v_add_f32_e32 v1, 1.0, v1
	v_mul_f32_e32 v2, v42, v2
	v_rcp_f32_e32 v1, v1
	v_cvt_pk_bf16_f32 v2, v2, s0
	global_store_short v[104:105], v2, off offset:3136 nt
	v_mul_f32_e32 v2, 0xbfb8aa3b, v28
	v_exp_f32_e32 v2, v2
	v_mul_f32_e32 v1, v27, v1
	v_mul_f32_e32 v1, v43, v1
	v_cvt_pk_bf16_f32 v1, v1, s0
	v_add_f32_e32 v2, 1.0, v2
	global_store_short v[90:91], v1, off offset:576 nt
	v_mul_f32_e32 v1, 0xbfb8aa3b, v29
	v_rcp_f32_e32 v2, v2
	v_exp_f32_e32 v1, v1
	v_mul_f32_e32 v2, v28, v2
	v_add_f32_e32 v1, 1.0, v1
	v_mul_f32_e32 v2, v44, v2
	v_rcp_f32_e32 v1, v1
	v_cvt_pk_bf16_f32 v2, v2, s0
	global_store_short v[106:107], v2, off offset:64 nt
	v_add_f32_e32 v2, 1.0, v3
	v_mul_f32_e32 v3, 0xbfb8aa3b, v31
	v_rcp_f32_e32 v2, v2
	v_exp_f32_e32 v3, v3
	v_mul_f32_e32 v1, v29, v1
	v_mul_f32_e32 v1, v45, v1
	v_cvt_pk_bf16_f32 v1, v1, s0
	global_store_short v[92:93], v1, off offset:1600 nt
	v_mul_f32_e32 v1, v30, v2
	v_add_f32_e32 v2, 1.0, v3
	v_rcp_f32_e32 v2, v2
	v_mul_f32_e32 v1, v46, v1
	v_cvt_pk_bf16_f32 v1, v1, s0
	global_store_short v[108:109], v1, off offset:3136 nt
	v_mul_f32_e32 v1, v31, v2
	v_mul_f32_e32 v1, v47, v1
	v_cvt_pk_bf16_f32 v1, v1, s0
	global_store_short v[94:95], v1, off offset:576 nt
	s_cbranch_scc0 .LBB0_733

; DI unsigned swz(int row, int chunk) { return (unsigned)row * 128u + (unsigned)((chunk ^ ((row >> 1) & 7)) << 4); }
; #define MFMA32(a, b, c) __builtin_amdgcn_mfma_f32_32x32x16_bf16((a), (b), (c), 0, 0, 0)
;     ...
;         for (int kt = 0; kt < nk; ++kt) {
; #pragma unroll
;             for (int i = 0; i < 4; ++i) *(u32x4*)(lds + swz(lr + 32 * i, lc)) = ra[i];
; #pragma unroll
;             for (int i = 0; i < 8; ++i) *(u32x4*)(lds + 16384 + swz(lr + 32 * i, lc)) = rb[i];
;             __syncthreads();
;             if (kt + 1 < nk) {
; #pragma unroll
;                 for (int i = 0; i < 4; ++i) ra[i] = *(const u32x4*)((Au + (size_t)(32 * i) * lda + (kt + 1) * 64) + voA);
; #pragma unroll
;                 for (int i = 0; i < 8; ++i) rb[i] = *(const u32x4*)((Bu + (size_t)(32 * i) * ldb + (kt + 1) * 64) + voB);
;             }
;             __builtin_amdgcn_s_setprio(1);
; #pragma unroll 2
;             for (int ks = 0; ks < 4; ++ks) {
;                 bf16x8 af[2], bfr[4];
;                 const unsigned xo = (c0 ^ (unsigned)(2 * ks)) << 4;
; #pragma unroll
;                 for (int i = 0; i < 2; ++i) af[i] = *(const bf16x8*)(lds + (roA + xo) + i * 4096);
; #pragma unroll
;                 for (int j = 0; j < 4; ++j) bfr[j] = *(const bf16x8*)(lds + (roB + xo) + j * 4096);
; #pragma unroll
;                 for (int i = 0; i < 2; ++i)
; #pragma unroll
;                     for (int j = 0; j < 4; ++j) acc[i][j] = MFMA32(af[i], bfr[j], acc[i][j]);
;             }
;             __builtin_amdgcn_s_setprio(0);
;             __syncthreads();
.LBB0_780:
	s_mov_b32 s0, s94
	s_add_i32 s94, s94, 1
	s_cmp_lt_u32 s0, 43
	s_waitcnt vmcnt(0)
	ds_write_b128 v193, v[130:133]
	ds_write_b128 v193, v[138:141] offset:4096
	ds_write_b128 v193, v[170:173] offset:8192
	ds_write_b128 v193, v[134:137] offset:12288
	ds_write_b128 v193, v[174:177] offset:16384
	ds_write_b128 v193, v[166:169] offset:20480
	ds_write_b128 v193, v[162:165] offset:24576
	ds_write_b128 v193, v[158:161] offset:28672
	ds_write_b128 v193, v[154:157] offset:32768
	ds_write_b128 v193, v[150:153] offset:36864
	ds_write_b128 v193, v[146:149] offset:40960
	ds_write_b128 v193, v[142:145] offset:45056
	s_waitcnt lgkmcnt(0)
	s_barrier
	s_cbranch_scc0 .LBB0_782
	s_lshl_b32 s18, s94, 7
	s_mov_b32 s19, 0
	s_setprio 1
	v_xor_b32_e32 v1, 0, v187
	v_add_u32_e32 v202, v188, v1
	v_add_u32_e32 v1, v189, v1
	ds_read_b128 v[194:197], v202
	ds_read_b128 v[198:201], v1 offset:16384
	ds_read_b128 v[202:205], v202 offset:4096
	ds_read_b128 v[206:209], v1 offset:20480
	ds_read_b128 v[210:213], v1 offset:24576
	ds_read_b128 v[218:221], v1 offset:28672
	s_waitcnt lgkmcnt(4)
	v_mfma_f32_32x32x16_bf16 v[114:129], v[194:197], v[198:201], v[114:129]
	v_lshl_add_u64 v[222:223], v[182:183], 0, s[18:19]
	global_load_dwordx4 v[130:133], v[222:223], off
	s_add_u32 s18, s18, 0x2c000
	s_mov_b32 s10, 32
	v_xor_b32_e32 v1, s10, v187
	s_waitcnt lgkmcnt(2)
	v_mfma_f32_32x32x16_bf16 v[82:97], v[194:197], v[206:209], v[82:97]
	v_lshl_add_u64 v[224:225], v[182:183], 0, s[18:19]
	global_load_dwordx4 v[138:141], v[224:225], off
	s_add_u32 s18, s18, 0x2c000
	s_waitcnt lgkmcnt(1)
	v_mfma_f32_32x32x16_bf16 v[50:65], v[194:197], v[210:213], v[50:65]
	v_lshl_add_u64 v[226:227], v[182:183], 0, s[18:19]
	global_load_dwordx4 v[170:173], v[226:227], off
	s_add_u32 s18, s18, 0x2c000
	s_waitcnt lgkmcnt(0)
	v_mfma_f32_32x32x16_bf16 v[18:33], v[194:197], v[218:221], v[18:33]
	v_lshl_add_u64 v[222:223], v[182:183], 0, s[18:19]
	global_load_dwordx4 v[134:137], v[222:223], off
	s_sub_u32 s18, s18, 0x84000
	v_mfma_f32_32x32x16_bf16 v[98:113], v[202:205], v[198:201], v[98:113]
	v_lshl_add_u64 v[224:225], v[184:185], 0, s[18:19]
	global_load_dwordx4 v[174:177], v[224:225], off
	s_add_u32 s18, s18, 0x2c000
	v_mfma_f32_32x32x16_bf16 v[66:81], v[202:205], v[206:209], v[66:81]
	v_lshl_add_u64 v[226:227], v[184:185], 0, s[18:19]
	global_load_dwordx4 v[166:169], v[226:227], off
	s_add_u32 s18, s18, 0x2c000
	v_add_u32_e32 v206, v188, v1
	v_add_u32_e32 v1, v189, v1
	v_mfma_f32_32x32x16_bf16 v[34:49], v[202:205], v[210:213], v[34:49]
	v_lshl_add_u64 v[222:223], v[184:185], 0, s[18:19]
	global_load_dwordx4 v[162:165], v[222:223], off
	s_add_u32 s18, s18, 0x2c000
	v_mfma_f32_32x32x16_bf16 v[2:17], v[202:205], v[218:221], v[2:17]
	v_lshl_add_u64 v[224:225], v[184:185], 0, s[18:19]
	global_load_dwordx4 v[158:161], v[224:225], off
	s_add_u32 s18, s18, 0x2c000
	ds_read_b128 v[194:197], v206
	ds_read_b128 v[198:201], v1 offset:16384
	ds_read_b128 v[202:205], v206 offset:4096
	ds_read_b128 v[206:209], v1 offset:20480
	ds_read_b128 v[210:213], v1 offset:24576
	ds_read_b128 v[218:221], v1 offset:28672
	s_waitcnt lgkmcnt(4)
	v_mfma_f32_32x32x16_bf16 v[114:129], v[194:197], v[198:201], v[114:129]
	v_lshl_add_u64 v[226:227], v[184:185], 0, s[18:19]
	global_load_dwordx4 v[154:157], v[226:227], off
	s_add_u32 s18, s18, 0x2c000
	s_waitcnt lgkmcnt(2)
	v_mfma_f32_32x32x16_bf16 v[82:97], v[194:197], v[206:209], v[82:97]
	v_lshl_add_u64 v[222:223], v[184:185], 0, s[18:19]
	global_load_dwordx4 v[150:153], v[222:223], off
	s_add_u32 s18, s18, 0x2c000
	s_waitcnt lgkmcnt(1)
	v_mfma_f32_32x32x16_bf16 v[50:65], v[194:197], v[210:213], v[50:65]
	v_lshl_add_u64 v[224:225], v[184:185], 0, s[18:19]
	global_load_dwordx4 v[146:149], v[224:225], off
	s_add_u32 s18, s18, 0x2c000
	s_waitcnt lgkmcnt(0)
	v_mfma_f32_32x32x16_bf16 v[18:33], v[194:197], v[218:221], v[18:33]
	v_lshl_add_u64 v[226:227], v[184:185], 0, s[18:19]
	global_load_dwordx4 v[142:145], v[226:227], off
	v_mfma_f32_32x32x16_bf16 v[98:113], v[202:205], v[198:201], v[98:113]
	v_mfma_f32_32x32x16_bf16 v[66:81], v[202:205], v[206:209], v[66:81]
	v_mfma_f32_32x32x16_bf16 v[34:49], v[202:205], v[210:213], v[34:49]
	v_mfma_f32_32x32x16_bf16 v[2:17], v[202:205], v[218:221], v[2:17]
	v_xor_b32_e32 v1, 64, v187
	v_add_u32_e32 v202, v188, v1
	v_add_u32_e32 v1, v189, v1
	ds_read_b128 v[194:197], v202
	ds_read_b128 v[198:201], v1 offset:16384
	ds_read_b128 v[202:205], v202 offset:4096
	ds_read_b128 v[206:209], v1 offset:20480
	ds_read_b128 v[210:213], v1 offset:24576
	ds_read_b128 v[218:221], v1 offset:28672
	s_waitcnt lgkmcnt(4)
	v_mfma_f32_32x32x16_bf16 v[114:129], v[194:197], v[198:201], v[114:129]
	s_mov_b32 s10, 96
	v_xor_b32_e32 v1, s10, v187
	s_waitcnt lgkmcnt(2)
	v_mfma_f32_32x32x16_bf16 v[82:97], v[194:197], v[206:209], v[82:97]
	s_waitcnt lgkmcnt(1)
	v_mfma_f32_32x32x16_bf16 v[50:65], v[194:197], v[210:213], v[50:65]
	s_waitcnt lgkmcnt(0)
	v_mfma_f32_32x32x16_bf16 v[18:33], v[194:197], v[218:221], v[18:33]
	v_mfma_f32_32x32x16_bf16 v[98:113], v[202:205], v[198:201], v[98:113]
	v_mfma_f32_32x32x16_bf16 v[66:81], v[202:205], v[206:209], v[66:81]
	v_add_u32_e32 v206, v188, v1
	v_add_u32_e32 v1, v189, v1
	v_mfma_f32_32x32x16_bf16 v[34:49], v[202:205], v[210:213], v[34:49]
	v_mfma_f32_32x32x16_bf16 v[2:17], v[202:205], v[218:221], v[2:17]
	ds_read_b128 v[194:197], v206
	ds_read_b128 v[198:201], v1 offset:16384
	ds_read_b128 v[202:205], v206 offset:4096
	ds_read_b128 v[206:209], v1 offset:20480
	ds_read_b128 v[210:213], v1 offset:24576
	ds_read_b128 v[218:221], v1 offset:28672
	s_waitcnt lgkmcnt(4)
	v_mfma_f32_32x32x16_bf16 v[114:129], v[194:197], v[198:201], v[114:129]
	s_waitcnt lgkmcnt(2)
	v_mfma_f32_32x32x16_bf16 v[82:97], v[194:197], v[206:209], v[82:97]
	s_waitcnt lgkmcnt(1)
	v_mfma_f32_32x32x16_bf16 v[50:65], v[194:197], v[210:213], v[50:65]
	s_waitcnt lgkmcnt(0)
	v_mfma_f32_32x32x16_bf16 v[18:33], v[194:197], v[218:221], v[18:33]
	v_mfma_f32_32x32x16_bf16 v[98:113], v[202:205], v[198:201], v[98:113]
	v_mfma_f32_32x32x16_bf16 v[66:81], v[202:205], v[206:209], v[66:81]
	v_mfma_f32_32x32x16_bf16 v[34:49], v[202:205], v[210:213], v[34:49]
	v_mfma_f32_32x32x16_bf16 v[2:17], v[202:205], v[218:221], v[2:17]
	s_branch .Lkint_done_783

; DI int cu(int r) { return (r & 3) + 8 * (r >> 2); }
;     ...
;             __builtin_amdgcn_s_setprio(0);
;             __syncthreads();
;     template <int NI> DI void operator()(const f32x16 (&acc)[2][NI], int row0, int col0, int lane) const {
;         const bool lat = row0 < NLAT;
;         const float* src = (lat ? srcL + (size_t)row0 * DM : srcC + (size_t)(row0 - NLAT) * DM) + col0;
;         float* dst = (lat ? dstL + (size_t)row0 * DM : dstC + (size_t)(row0 - NLAT) * DM) + col0;
;         const float* g = mod + ((lat ? (row0 >> 13) : 8) * 6 + gate_idx) * 1024 + col0;
;         const unsigned l31 = lane & 31, lo = (unsigned)(4 * (lane >> 5) * DM) + l31;
; #pragma unroll
;         for (int ni = 0; ni < NI; ++ni) {
;             const float gv = (g + 32 * ni)[l31];
;             float sv[32];
; #pragma unroll
;             for (int q = 0; q < 32; ++q) sv[q] = __builtin_nontemporal_load(&(src + (32 * (q >> 4) + cu(q & 15)) * DM + 32 * ni)[lo]);
; #pragma unroll
;             for (int q = 0; q < 32; ++q) (dst + (32 * (q >> 4) + cu(q & 15)) * DM + 32 * ni)[lo] = sv[q] + gv * acc[q >> 4][ni][q & 15];
;             asm volatile("" ::: "memory");
;         }
.Lkint_done_783:
	s_setprio 0
	s_cmp_eq_u32 s94, 44
	s_barrier
	s_cbranch_scc0 .LBB0_780
	s_waitcnt vmcnt(8)
	v_add_u32_e32 v136, s80, v190
	v_add_u32_e32 v131, 0xffff0000, v136
	v_ashrrev_i32_e32 v132, 31, v136
	v_cmp_gt_i32_e32 vcc, s7, v136
	v_mov_b32_e32 v134, s49
	v_or_b32_e32 v130, s93, v191
	v_cndmask_b32_e32 v133, 0, v132, vcc
	v_cndmask_b32_e32 v132, v131, v136, vcc
	v_mov_b32_e32 v131, s27
	v_cndmask_b32_e32 v135, v131, v134, vcc
	v_mov_b32_e32 v131, s26
	v_mov_b32_e32 v134, s48
	v_cndmask_b32_e32 v134, v131, v134, vcc
	v_lshlrev_b64 v[132:133], 12, v[132:133]
	v_lshl_add_u64 v[132:133], v[134:135], 0, v[132:133]
	v_min_i32_e32 v134, 0x10000, v136
	v_ashrrev_i32_e32 v134, 13, v134
	v_mul_i32_i24_e32 v134, 0x1800, v134
	v_ashrrev_i32_e32 v131, 31, v130
	v_ashrrev_i32_e32 v135, 31, v134
	v_mov_b32_e32 v1, v186
	v_lshlrev_b64 v[130:131], 2, v[130:131]
	v_lshl_add_u64 v[134:135], v[134:135], 2, s[12:13]
	v_lshl_add_u64 v[132:133], v[132:133], 0, v[130:131]
	v_lshl_add_u64 v[130:131], v[134:135], 0, v[130:131]
	v_and_b32_e32 v135, 31, v1
	v_lshlrev_b32_e32 v1, 7, v1
	v_lshlrev_b32_e32 v136, 2, v135
	v_mov_b32_e32 v137, v0
	v_and_or_b32 v134, v1, s8, v135
	v_lshl_add_u64 v[136:137], v[130:131], 0, v[136:137]
	v_mov_b32_e32 v135, v0
	v_lshl_add_u64 v[130:131], v[134:135], 2, v[132:133]
	v_add_co_u32_e32 v132, vcc, s9, v136
	s_waitcnt vmcnt(0)
	v_lshl_add_u64 v[144:145], v[136:137], 0, s[4:5]
	v_addc_co_u32_e32 v133, vcc, 0, v137, vcc
	global_load_dword v1, v[132:133], off
	global_load_dword v184, v[130:131], off nt
	v_add_co_u32_e32 v132, vcc, s14, v130
	s_add_i32 s92, s92, s81
	s_nop 0
	v_addc_co_u32_e32 v133, vcc, 0, v131, vcc
	v_add_co_u32_e32 v134, vcc, s15, v130
	s_cmpk_gt_i32 s92, 0x107
	s_nop 0
	v_addc_co_u32_e32 v135, vcc, 0, v131, vcc
	v_add_co_u32_e32 v136, vcc, s16, v130
	s_waitcnt vmcnt(0)
	v_fmac_f32_e32 v184, v114, v1
	v_addc_co_u32_e32 v137, vcc, 0, v131, vcc
	v_add_co_u32_e32 v138, vcc, s28, v130
	s_nop 1
	v_addc_co_u32_e32 v139, vcc, 0, v131, vcc
	v_add_co_u32_e32 v140, vcc, s30, v130
	s_nop 1
	v_addc_co_u32_e32 v141, vcc, 0, v131, vcc
	v_add_co_u32_e32 v142, vcc, s31, v130
	s_nop 1
	v_addc_co_u32_e32 v143, vcc, 0, v131, vcc
	v_add_co_u32_e32 v154, vcc, s17, v130
	global_load_dword v185, v[134:135], off offset:-4096 nt
	global_load_dword v194, v[134:135], off nt
	global_load_dword v195, v[138:139], off offset:-4096 nt
	global_load_dword v196, v[138:139], off nt
	global_load_dword v197, v[140:141], off offset:-4096 nt
	global_load_dword v198, v[140:141], off nt
	global_load_dword v199, v[142:143], off offset:-4096 nt
	global_load_dword v200, v[136:137], off nt
	v_addc_co_u32_e32 v155, vcc, 0, v131, vcc
	v_add_co_u32_e32 v146, vcc, s35, v130
	s_waitcnt vmcnt(7)
	v_fmac_f32_e32 v185, v115, v1
	v_addc_co_u32_e32 v147, vcc, 0, v131, vcc
	v_add_co_u32_e32 v148, vcc, s47, v130
	s_waitcnt vmcnt(6)
	v_fmac_f32_e32 v194, v116, v1
	v_addc_co_u32_e32 v149, vcc, 0, v131, vcc
	v_add_co_u32_e32 v150, vcc, s63, v130
	s_waitcnt vmcnt(0)
	v_fmac_f32_e32 v200, v117, v1
	v_addc_co_u32_e32 v151, vcc, 0, v131, vcc
	v_add_co_u32_e32 v152, vcc, s69, v130
	v_fmac_f32_e32 v195, v118, v1
	s_nop 0
	v_addc_co_u32_e32 v153, vcc, 0, v131, vcc
	global_load_dword v201, v[142:143], off nt
	global_load_dword v202, v[146:147], off offset:-4096 nt
	global_load_dword v203, v[146:147], off nt
	global_load_dword v204, v[148:149], off offset:-4096 nt
	global_load_dword v205, v[148:149], off nt
	global_load_dword v206, v[150:151], off offset:-4096 nt
	global_load_dword v207, v[150:151], off nt
	global_load_dword v208, v[152:153], off offset:-4096 nt
	v_add_co_u32_e32 v156, vcc, s71, v130
	v_fmac_f32_e32 v196, v119, v1
	s_nop 0
	v_addc_co_u32_e32 v157, vcc, 0, v131, vcc
	v_add_co_u32_e32 v158, vcc, s73, v130
	v_fmac_f32_e32 v197, v120, v1
	s_nop 0
	v_addc_co_u32_e32 v159, vcc, 0, v131, vcc
	v_add_co_u32_e32 v160, vcc, s75, v130
	v_fmac_f32_e32 v198, v121, v1
	s_nop 0
	v_addc_co_u32_e32 v161, vcc, 0, v131, vcc
	v_add_co_u32_e32 v162, vcc, s79, v130
	v_fmac_f32_e32 v199, v122, v1
	s_nop 0
	v_addc_co_u32_e32 v163, vcc, 0, v131, vcc
	global_load_dword v209, v[152:153], off nt
	global_load_dword v210, v[156:157], off offset:-4096 nt
	global_load_dword v211, v[156:157], off nt
	global_load_dword v212, v[158:159], off offset:-4096 nt
	global_load_dword v213, v[158:159], off nt
	global_load_dword v214, v[160:161], off offset:-4096 nt
	global_load_dword v215, v[160:161], off nt
	global_load_dword v218, v[162:163], off offset:-4096 nt
	v_add_co_u32_e32 v164, vcc, s87, v130
	s_waitcnt vmcnt(15)
	v_fmac_f32_e32 v201, v123, v1
	v_addc_co_u32_e32 v165, vcc, 0, v131, vcc
	v_add_co_u32_e32 v166, vcc, s89, v130
	global_load_dword v219, v[162:163], off nt
	global_load_dword v220, v[164:165], off offset:-4096 nt
	global_load_dword v221, v[164:165], off nt
	v_addc_co_u32_e32 v167, vcc, 0, v131, vcc
	v_add_co_u32_e32 v168, vcc, s91, v130
	s_waitcnt vmcnt(11)
	v_fmac_f32_e32 v208, v98, v1
	v_addc_co_u32_e32 v169, vcc, 0, v131, vcc
	global_load_dword v222, v[166:167], off offset:-4096 nt
	global_load_dword v223, v[166:167], off nt
	global_load_dword v224, v[168:169], off offset:-4096 nt
	global_load_dword v225, v[168:169], off nt
	v_add_co_u32_e32 v182, vcc, s29, v130
	v_fmac_f32_e32 v202, v124, v1
	s_nop 0
	v_addc_co_u32_e32 v183, vcc, 0, v131, vcc
	v_add_co_u32_e32 v176, vcc, s7, v130
	s_waitcnt vmcnt(14)
	v_fmac_f32_e32 v209, v99, v1
	v_addc_co_u32_e32 v177, vcc, 0, v131, vcc
	v_add_co_u32_e32 v174, vcc, s34, v130
	s_waitcnt vmcnt(13)
	v_fmac_f32_e32 v210, v100, v1
	v_addc_co_u32_e32 v175, vcc, 0, v131, vcc
	v_add_co_u32_e32 v172, vcc, s46, v130
	s_waitcnt vmcnt(12)
; DI int cu(int r) { return (r & 3) + 8 * (r >> 2); }
;     template <int NI> DI void operator()(const f32x16 (&acc)[2][NI], int row0, int col0, int lane) const {
;     ...
;         for (int ni = 0; ni < NI; ++ni) {
;             const float gv = (g + 32 * ni)[l31];
;             float sv[32];
; #pragma unroll
;             for (int q = 0; q < 32; ++q) sv[q] = __builtin_nontemporal_load(&(src + (32 * (q >> 4) + cu(q & 15)) * DM + 32 * ni)[lo]);
; #pragma unroll
;             for (int q = 0; q < 32; ++q) (dst + (32 * (q >> 4) + cu(q & 15)) * DM + 32 * ni)[lo] = sv[q] + gv * acc[q >> 4][ni][q & 15];
;             asm volatile("" ::: "memory");
;         }
	v_fmac_f32_e32 v211, v101, v1
	v_addc_co_u32_e32 v173, vcc, 0, v131, vcc
	v_add_co_u32_e32 v170, vcc, s62, v130
	s_waitcnt vmcnt(11)
	v_fmac_f32_e32 v212, v102, v1
	v_addc_co_u32_e32 v171, vcc, 0, v131, vcc
	v_add_co_u32_e32 v98, vcc, s68, v130
	s_waitcnt vmcnt(10)
	v_fmac_f32_e32 v213, v103, v1
	v_addc_co_u32_e32 v99, vcc, 0, v131, vcc
	v_add_co_u32_e32 v100, vcc, s70, v130
	s_waitcnt vmcnt(9)
	v_fmac_f32_e32 v214, v104, v1
	v_addc_co_u32_e32 v101, vcc, 0, v131, vcc
	v_add_co_u32_e32 v102, vcc, s72, v130
	s_waitcnt vmcnt(8)
	v_fmac_f32_e32 v215, v105, v1
	v_addc_co_u32_e32 v103, vcc, 0, v131, vcc
	v_add_co_u32_e32 v104, vcc, s74, v130
	s_waitcnt vmcnt(7)
	v_fmac_f32_e32 v218, v106, v1
	v_addc_co_u32_e32 v105, vcc, 0, v131, vcc
	v_add_co_u32_e32 v106, vcc, s78, v130
	v_fmac_f32_e32 v203, v125, v1
	v_fmac_f32_e32 v204, v126, v1
	v_fmac_f32_e32 v205, v127, v1
	v_fmac_f32_e32 v206, v128, v1
	v_fmac_f32_e32 v207, v129, v1
	global_store_dword v[130:131], v184, off
	global_store_dword v[134:135], v185, off offset:-4096
	global_store_dword v[134:135], v194, off
	global_store_dword v[136:137], v200, off
	global_store_dword v[138:139], v195, off offset:-4096
	global_store_dword v[138:139], v196, off
	global_store_dword v[140:141], v197, off offset:-4096
	global_store_dword v[140:141], v198, off
	global_store_dword v[142:143], v199, off offset:-4096
	global_store_dword v[142:143], v201, off
	global_store_dword v[146:147], v202, off offset:-4096
	global_store_dword v[146:147], v203, off
	global_store_dword v[148:149], v204, off offset:-4096
	global_store_dword v[148:149], v205, off
	global_store_dword v[150:151], v206, off offset:-4096
	global_store_dword v[150:151], v207, off
	global_store_dword v[152:153], v208, off offset:-4096
	s_waitcnt vmcnt(23)
	v_fmac_f32_e32 v219, v107, v1
	v_addc_co_u32_e32 v107, vcc, 0, v131, vcc
	s_waitcnt vmcnt(22)
	v_fmac_f32_e32 v220, v108, v1
	v_add_co_u32_e32 v108, vcc, s86, v130
	s_waitcnt vmcnt(21)
	v_fmac_f32_e32 v221, v109, v1
	v_addc_co_u32_e32 v109, vcc, 0, v131, vcc
	s_waitcnt vmcnt(20)
	v_fmac_f32_e32 v222, v110, v1
	v_add_co_u32_e32 v110, vcc, s88, v130
	s_waitcnt vmcnt(19)
	v_fmac_f32_e32 v223, v111, v1
	s_waitcnt vmcnt(18)
	v_fmac_f32_e32 v224, v112, v1
	s_waitcnt vmcnt(17)
	v_fmac_f32_e32 v225, v113, v1
	v_addc_co_u32_e32 v111, vcc, 0, v131, vcc
	global_store_dword v[152:153], v209, off
	global_store_dword v[156:157], v210, off offset:-4096
	global_store_dword v[156:157], v211, off
	global_store_dword v[158:159], v212, off offset:-4096
	global_store_dword v[158:159], v213, off
	global_store_dword v[160:161], v214, off offset:-4096
	global_store_dword v[160:161], v215, off
	global_store_dword v[162:163], v218, off offset:-4096
	global_store_dword v[162:163], v219, off
	global_store_dword v[164:165], v220, off offset:-4096
	global_store_dword v[164:165], v221, off
	global_store_dword v[166:167], v222, off offset:-4096
	global_store_dword v[166:167], v223, off
	global_store_dword v[168:169], v224, off offset:-4096
	global_store_dword v[168:169], v225, off
	v_add_co_u32_e32 v112, vcc, s90, v130
	global_load_dword v1, v[144:145], off offset:128
	global_load_dword v114, v[130:131], off offset:128 nt
	global_load_dword v115, v[132:133], off offset:128 nt
	v_addc_co_u32_e32 v113, vcc, 0, v131, vcc
	global_load_dword v116, v[134:135], off offset:128 nt
	global_load_dword v117, v[136:137], off offset:128 nt
	global_load_dword v118, v[154:155], off offset:128 nt
	global_load_dword v119, v[138:139], off offset:128 nt
	global_load_dword v120, v[182:183], off offset:128 nt
	global_load_dword v121, v[176:177], off offset:128 nt
	global_load_dword v122, v[140:141], off offset:128 nt
	global_load_dword v123, v[142:143], off offset:128 nt
	global_load_dword v124, v[174:175], off offset:128 nt
	global_load_dword v125, v[172:173], off offset:128 nt
	global_load_dword v126, v[146:147], off offset:128 nt
	global_load_dword v127, v[148:149], off offset:128 nt
	global_load_dword v128, v[170:171], off offset:128 nt
	global_load_dword v129, v[150:151], off offset:128 nt
	global_load_dword v184, v[98:99], off offset:128 nt
	global_load_dword v185, v[152:153], off offset:128 nt
	global_load_dword v194, v[100:101], off offset:128 nt
	global_load_dword v195, v[102:103], off offset:128 nt
	global_load_dword v196, v[156:157], off offset:128 nt
	global_load_dword v197, v[158:159], off offset:128 nt
	global_load_dword v198, v[104:105], off offset:128 nt
	global_load_dword v199, v[106:107], off offset:128 nt
	global_load_dword v200, v[160:161], off offset:128 nt
	global_load_dword v201, v[162:163], off offset:128 nt
	global_load_dword v202, v[108:109], off offset:128 nt
	global_load_dword v203, v[110:111], off offset:128 nt
	global_load_dword v204, v[164:165], off offset:128 nt
	global_load_dword v205, v[166:167], off offset:128 nt
	global_load_dword v206, v[112:113], off offset:128 nt
	global_load_dword v207, v[168:169], off offset:128 nt
	s_waitcnt vmcnt(31)
	v_fmac_f32_e32 v114, v82, v1
	s_waitcnt vmcnt(30)
	v_fmac_f32_e32 v115, v83, v1
	s_waitcnt vmcnt(29)
	v_fmac_f32_e32 v116, v84, v1
	s_waitcnt vmcnt(28)
	v_fmac_f32_e32 v117, v85, v1
	s_waitcnt vmcnt(27)
	v_fmac_f32_e32 v118, v86, v1
	s_waitcnt vmcnt(26)
	v_fmac_f32_e32 v119, v87, v1
	s_waitcnt vmcnt(25)
	v_fmac_f32_e32 v120, v88, v1
	s_waitcnt vmcnt(23)
	v_fmac_f32_e32 v122, v89, v1
	v_fmac_f32_e32 v121, v90, v1
	s_waitcnt vmcnt(22)
	v_fmac_f32_e32 v123, v91, v1
	s_waitcnt vmcnt(21)
	v_fmac_f32_e32 v124, v92, v1
	s_waitcnt vmcnt(19)
	v_fmac_f32_e32 v126, v93, v1
	v_fmac_f32_e32 v125, v94, v1
	s_waitcnt vmcnt(18)
	v_fmac_f32_e32 v127, v95, v1
	s_waitcnt vmcnt(17)
; DI int cu(int r) { return (r & 3) + 8 * (r >> 2); }
;     template <int NI> DI void operator()(const f32x16 (&acc)[2][NI], int row0, int col0, int lane) const {
;     ...
;         for (int ni = 0; ni < NI; ++ni) {
;             const float gv = (g + 32 * ni)[l31];
;             float sv[32];
; #pragma unroll
;             for (int q = 0; q < 32; ++q) sv[q] = __builtin_nontemporal_load(&(src + (32 * (q >> 4) + cu(q & 15)) * DM + 32 * ni)[lo]);
; #pragma unroll
;             for (int q = 0; q < 32; ++q) (dst + (32 * (q >> 4) + cu(q & 15)) * DM + 32 * ni)[lo] = sv[q] + gv * acc[q >> 4][ni][q & 15];
;             asm volatile("" ::: "memory");
;         }
	v_fmac_f32_e32 v128, v96, v1
	s_waitcnt vmcnt(16)
	v_fmac_f32_e32 v129, v97, v1
	s_waitcnt vmcnt(15)
	v_fmac_f32_e32 v184, v66, v1
	s_waitcnt vmcnt(14)
	v_fmac_f32_e32 v185, v67, v1
	s_waitcnt vmcnt(13)
	v_fmac_f32_e32 v194, v68, v1
	s_waitcnt vmcnt(11)
	v_fmac_f32_e32 v196, v69, v1
	v_fmac_f32_e32 v195, v70, v1
	s_waitcnt vmcnt(10)
	v_fmac_f32_e32 v197, v71, v1
	s_waitcnt vmcnt(9)
	v_fmac_f32_e32 v198, v72, v1
	s_waitcnt vmcnt(7)
	v_fmac_f32_e32 v200, v73, v1
	v_fmac_f32_e32 v199, v74, v1
	s_waitcnt vmcnt(6)
	v_fmac_f32_e32 v201, v75, v1
	s_waitcnt vmcnt(5)
	v_fmac_f32_e32 v202, v76, v1
	s_waitcnt vmcnt(3)
	v_fmac_f32_e32 v204, v77, v1
	v_fmac_f32_e32 v203, v78, v1
	s_waitcnt vmcnt(2)
	v_fmac_f32_e32 v205, v79, v1
	s_waitcnt vmcnt(1)
	v_fmac_f32_e32 v206, v80, v1
	s_waitcnt vmcnt(0)
	v_fmac_f32_e32 v207, v81, v1
	global_store_dword v[130:131], v114, off offset:128
	global_store_dword v[132:133], v115, off offset:128
	global_store_dword v[134:135], v116, off offset:128
	global_store_dword v[136:137], v117, off offset:128
	global_store_dword v[154:155], v118, off offset:128
	global_store_dword v[138:139], v119, off offset:128
	global_store_dword v[182:183], v120, off offset:128
	global_store_dword v[140:141], v122, off offset:128
	global_store_dword v[176:177], v121, off offset:128
	global_store_dword v[142:143], v123, off offset:128
	global_store_dword v[174:175], v124, off offset:128
	global_store_dword v[146:147], v126, off offset:128
	global_store_dword v[172:173], v125, off offset:128
	global_store_dword v[148:149], v127, off offset:128
	global_store_dword v[170:171], v128, off offset:128
	global_store_dword v[150:151], v129, off offset:128
	global_store_dword v[98:99], v184, off offset:128
	global_store_dword v[152:153], v185, off offset:128
	global_store_dword v[100:101], v194, off offset:128
	global_store_dword v[156:157], v196, off offset:128
	global_store_dword v[102:103], v195, off offset:128
	global_store_dword v[158:159], v197, off offset:128
	global_store_dword v[104:105], v198, off offset:128
	global_store_dword v[160:161], v200, off offset:128
	global_store_dword v[106:107], v199, off offset:128
	global_store_dword v[162:163], v201, off offset:128
	global_store_dword v[108:109], v202, off offset:128
	global_store_dword v[164:165], v204, off offset:128
	global_store_dword v[110:111], v203, off offset:128
	global_store_dword v[166:167], v205, off offset:128
	global_store_dword v[112:113], v206, off offset:128
	global_store_dword v[168:169], v207, off offset:128
	global_load_dword v1, v[144:145], off offset:256
	global_load_dword v66, v[130:131], off offset:256 nt
	global_load_dword v67, v[132:133], off offset:256 nt
	global_load_dword v68, v[134:135], off offset:256 nt
	global_load_dword v69, v[136:137], off offset:256 nt
	global_load_dword v70, v[154:155], off offset:256 nt
	global_load_dword v71, v[138:139], off offset:256 nt
	global_load_dword v72, v[182:183], off offset:256 nt
	global_load_dword v73, v[140:141], off offset:256 nt
	global_load_dword v74, v[176:177], off offset:256 nt
	global_load_dword v75, v[142:143], off offset:256 nt
	global_load_dword v76, v[174:175], off offset:256 nt
	global_load_dword v77, v[146:147], off offset:256 nt
	global_load_dword v78, v[172:173], off offset:256 nt
	global_load_dword v79, v[148:149], off offset:256 nt
	global_load_dword v80, v[170:171], off offset:256 nt
	global_load_dword v81, v[150:151], off offset:256 nt
	global_load_dword v82, v[98:99], off offset:256 nt
	global_load_dword v83, v[152:153], off offset:256 nt
	global_load_dword v84, v[100:101], off offset:256 nt
	global_load_dword v85, v[156:157], off offset:256 nt
	global_load_dword v86, v[102:103], off offset:256 nt
	global_load_dword v87, v[158:159], off offset:256 nt
	global_load_dword v88, v[104:105], off offset:256 nt
	global_load_dword v89, v[160:161], off offset:256 nt
	global_load_dword v90, v[106:107], off offset:256 nt
	global_load_dword v91, v[162:163], off offset:256 nt
	global_load_dword v92, v[108:109], off offset:256 nt
	global_load_dword v93, v[164:165], off offset:256 nt
	global_load_dword v94, v[110:111], off offset:256 nt
	global_load_dword v95, v[166:167], off offset:256 nt
	global_load_dword v96, v[112:113], off offset:256 nt
	global_load_dword v97, v[168:169], off offset:256 nt
	s_waitcnt vmcnt(31)
	v_fmac_f32_e32 v66, v50, v1
	s_waitcnt vmcnt(30)
	v_fmac_f32_e32 v67, v51, v1
	s_waitcnt vmcnt(29)
	v_fmac_f32_e32 v68, v52, v1
	s_waitcnt vmcnt(28)
	v_fmac_f32_e32 v69, v53, v1
	s_waitcnt vmcnt(27)
	v_fmac_f32_e32 v70, v54, v1
	s_waitcnt vmcnt(26)
	v_fmac_f32_e32 v71, v55, v1
	s_waitcnt vmcnt(25)
	v_fmac_f32_e32 v72, v56, v1
	s_waitcnt vmcnt(24)
	v_fmac_f32_e32 v73, v57, v1
	s_waitcnt vmcnt(23)
	v_fmac_f32_e32 v74, v58, v1
	s_waitcnt vmcnt(22)
	v_fmac_f32_e32 v75, v59, v1
	s_waitcnt vmcnt(21)
	v_fmac_f32_e32 v76, v60, v1
	s_waitcnt vmcnt(20)
	v_fmac_f32_e32 v77, v61, v1
	s_waitcnt vmcnt(19)
	v_fmac_f32_e32 v78, v62, v1
	s_waitcnt vmcnt(18)
	v_fmac_f32_e32 v79, v63, v1
	s_waitcnt vmcnt(17)
	v_fmac_f32_e32 v80, v64, v1
	s_waitcnt vmcnt(16)
	v_fmac_f32_e32 v81, v65, v1
	s_waitcnt vmcnt(15)
	v_fmac_f32_e32 v82, v34, v1
	s_waitcnt vmcnt(14)
	v_fmac_f32_e32 v83, v35, v1
	s_waitcnt vmcnt(13)
	v_fmac_f32_e32 v84, v36, v1
	s_waitcnt vmcnt(12)
	v_fmac_f32_e32 v85, v37, v1
	s_waitcnt vmcnt(11)
	v_fmac_f32_e32 v86, v38, v1
	s_waitcnt vmcnt(10)
	v_fmac_f32_e32 v87, v39, v1
	s_waitcnt vmcnt(9)
	v_fmac_f32_e32 v88, v40, v1
	s_waitcnt vmcnt(8)
	v_fmac_f32_e32 v89, v41, v1
	s_waitcnt vmcnt(7)
	v_fmac_f32_e32 v90, v42, v1
	s_waitcnt vmcnt(6)
	v_fmac_f32_e32 v91, v43, v1
	s_waitcnt vmcnt(5)
	v_fmac_f32_e32 v92, v44, v1
	s_waitcnt vmcnt(4)
; DI int cu(int r) { return (r & 3) + 8 * (r >> 2); }
;     template <int NI> DI void operator()(const f32x16 (&acc)[2][NI], int row0, int col0, int lane) const {
;     ...
;         for (int ni = 0; ni < NI; ++ni) {
;             const float gv = (g + 32 * ni)[l31];
;             float sv[32];
; #pragma unroll
;             for (int q = 0; q < 32; ++q) sv[q] = __builtin_nontemporal_load(&(src + (32 * (q >> 4) + cu(q & 15)) * DM + 32 * ni)[lo]);
; #pragma unroll
;             for (int q = 0; q < 32; ++q) (dst + (32 * (q >> 4) + cu(q & 15)) * DM + 32 * ni)[lo] = sv[q] + gv * acc[q >> 4][ni][q & 15];
;             asm volatile("" ::: "memory");
;         }
	v_fmac_f32_e32 v93, v45, v1
	s_waitcnt vmcnt(3)
	v_fmac_f32_e32 v94, v46, v1
	s_waitcnt vmcnt(2)
	v_fmac_f32_e32 v95, v47, v1
	s_waitcnt vmcnt(1)
	v_fmac_f32_e32 v96, v48, v1
	s_waitcnt vmcnt(0)
	v_fmac_f32_e32 v97, v49, v1
	global_store_dword v[130:131], v66, off offset:256
	global_store_dword v[132:133], v67, off offset:256
	global_store_dword v[134:135], v68, off offset:256
	global_store_dword v[136:137], v69, off offset:256
	global_store_dword v[154:155], v70, off offset:256
	global_store_dword v[138:139], v71, off offset:256
	global_store_dword v[182:183], v72, off offset:256
	global_store_dword v[140:141], v73, off offset:256
	global_store_dword v[176:177], v74, off offset:256
	global_store_dword v[142:143], v75, off offset:256
	global_store_dword v[174:175], v76, off offset:256
	global_store_dword v[146:147], v77, off offset:256
	global_store_dword v[172:173], v78, off offset:256
	global_store_dword v[148:149], v79, off offset:256
	global_store_dword v[170:171], v80, off offset:256
	global_store_dword v[150:151], v81, off offset:256
	global_store_dword v[98:99], v82, off offset:256
	global_store_dword v[152:153], v83, off offset:256
	global_store_dword v[100:101], v84, off offset:256
	global_store_dword v[156:157], v85, off offset:256
	global_store_dword v[102:103], v86, off offset:256
	global_store_dword v[158:159], v87, off offset:256
	global_store_dword v[104:105], v88, off offset:256
	global_store_dword v[160:161], v89, off offset:256
	global_store_dword v[106:107], v90, off offset:256
	global_store_dword v[162:163], v91, off offset:256
	global_store_dword v[108:109], v92, off offset:256
	global_store_dword v[164:165], v93, off offset:256
	global_store_dword v[110:111], v94, off offset:256
	global_store_dword v[166:167], v95, off offset:256
	global_store_dword v[112:113], v96, off offset:256
	global_store_dword v[168:169], v97, off offset:256
	global_load_dword v1, v[144:145], off offset:384
	global_load_dword v34, v[130:131], off offset:384 nt
	global_load_dword v35, v[132:133], off offset:384 nt
	global_load_dword v36, v[134:135], off offset:384 nt
	global_load_dword v37, v[136:137], off offset:384 nt
	global_load_dword v38, v[154:155], off offset:384 nt
	global_load_dword v39, v[138:139], off offset:384 nt
	global_load_dword v40, v[182:183], off offset:384 nt
	global_load_dword v41, v[140:141], off offset:384 nt
	global_load_dword v42, v[176:177], off offset:384 nt
	global_load_dword v43, v[142:143], off offset:384 nt
	global_load_dword v44, v[174:175], off offset:384 nt
	global_load_dword v45, v[146:147], off offset:384 nt
	global_load_dword v46, v[172:173], off offset:384 nt
	global_load_dword v47, v[148:149], off offset:384 nt
	global_load_dword v48, v[170:171], off offset:384 nt
	global_load_dword v49, v[150:151], off offset:384 nt
	global_load_dword v50, v[98:99], off offset:384 nt
	global_load_dword v51, v[152:153], off offset:384 nt
	global_load_dword v52, v[100:101], off offset:384 nt
	global_load_dword v53, v[156:157], off offset:384 nt
	global_load_dword v54, v[102:103], off offset:384 nt
	global_load_dword v55, v[158:159], off offset:384 nt
	global_load_dword v56, v[104:105], off offset:384 nt
	global_load_dword v57, v[160:161], off offset:384 nt
	global_load_dword v58, v[106:107], off offset:384 nt
	global_load_dword v59, v[162:163], off offset:384 nt
	global_load_dword v60, v[108:109], off offset:384 nt
	global_load_dword v61, v[164:165], off offset:384 nt
	global_load_dword v62, v[110:111], off offset:384 nt
	global_load_dword v63, v[166:167], off offset:384 nt
	global_load_dword v64, v[112:113], off offset:384 nt
	global_load_dword v65, v[168:169], off offset:384 nt
	s_waitcnt vmcnt(31)
	v_fmac_f32_e32 v34, v18, v1
	s_waitcnt vmcnt(30)
	v_fmac_f32_e32 v35, v19, v1
	s_waitcnt vmcnt(29)
	v_fmac_f32_e32 v36, v20, v1
	s_waitcnt vmcnt(28)
	v_fmac_f32_e32 v37, v21, v1
	s_waitcnt vmcnt(27)
	v_fmac_f32_e32 v38, v22, v1
	s_waitcnt vmcnt(26)
	v_fmac_f32_e32 v39, v23, v1
	s_waitcnt vmcnt(25)
	v_fmac_f32_e32 v40, v24, v1
	s_waitcnt vmcnt(24)
	v_fmac_f32_e32 v41, v25, v1
	s_waitcnt vmcnt(23)
	v_fmac_f32_e32 v42, v26, v1
	s_waitcnt vmcnt(22)
	v_fmac_f32_e32 v43, v27, v1
	s_waitcnt vmcnt(21)
	v_fmac_f32_e32 v44, v28, v1
	s_waitcnt vmcnt(20)
	v_fmac_f32_e32 v45, v29, v1
	s_waitcnt vmcnt(19)
	v_fmac_f32_e32 v46, v30, v1
	s_waitcnt vmcnt(18)
	v_fmac_f32_e32 v47, v31, v1
	s_waitcnt vmcnt(17)
	v_fmac_f32_e32 v48, v32, v1
	s_waitcnt vmcnt(16)
	v_fmac_f32_e32 v49, v33, v1
	s_waitcnt vmcnt(15)
	v_fmac_f32_e32 v50, v2, v1
	s_waitcnt vmcnt(14)
	v_fmac_f32_e32 v51, v3, v1
	s_waitcnt vmcnt(13)
	v_fmac_f32_e32 v52, v4, v1
	s_waitcnt vmcnt(12)
	v_fmac_f32_e32 v53, v5, v1
	s_waitcnt vmcnt(11)
	v_fmac_f32_e32 v54, v6, v1
	s_waitcnt vmcnt(10)
	v_fmac_f32_e32 v55, v7, v1
	s_waitcnt vmcnt(9)
	v_fmac_f32_e32 v56, v8, v1
	s_waitcnt vmcnt(8)
	v_fmac_f32_e32 v57, v9, v1
	s_waitcnt vmcnt(7)
	v_fmac_f32_e32 v58, v10, v1
	s_waitcnt vmcnt(6)
	v_fmac_f32_e32 v59, v11, v1
	s_waitcnt vmcnt(5)
	v_fmac_f32_e32 v60, v12, v1
	s_waitcnt vmcnt(4)
	v_fmac_f32_e32 v61, v13, v1
	s_waitcnt vmcnt(3)
	v_fmac_f32_e32 v62, v14, v1
	s_waitcnt vmcnt(2)
	v_fmac_f32_e32 v63, v15, v1
	s_waitcnt vmcnt(1)
	v_fmac_f32_e32 v64, v16, v1
	s_waitcnt vmcnt(0)
	v_fmac_f32_e32 v65, v17, v1
	global_store_dword v[130:131], v34, off offset:384
	global_store_dword v[132:133], v35, off offset:384
	global_store_dword v[134:135], v36, off offset:384
	global_store_dword v[136:137], v37, off offset:384
	global_store_dword v[154:155], v38, off offset:384
	global_store_dword v[138:139], v39, off offset:384
	global_store_dword v[182:183], v40, off offset:384
	global_store_dword v[140:141], v41, off offset:384
	global_store_dword v[176:177], v42, off offset:384
	global_store_dword v[142:143], v43, off offset:384
	global_store_dword v[174:175], v44, off offset:384
	global_store_dword v[146:147], v45, off offset:384
	global_store_dword v[172:173], v46, off offset:384
	global_store_dword v[148:149], v47, off offset:384
	global_store_dword v[170:171], v48, off offset:384
	global_store_dword v[150:151], v49, off offset:384
	global_store_dword v[98:99], v50, off offset:384
	global_store_dword v[152:153], v51, off offset:384
	global_store_dword v[100:101], v52, off offset:384
	global_store_dword v[156:157], v53, off offset:384
	global_store_dword v[102:103], v54, off offset:384
	global_store_dword v[158:159], v55, off offset:384
	global_store_dword v[104:105], v56, off offset:384
	global_store_dword v[160:161], v57, off offset:384
	global_store_dword v[106:107], v58, off offset:384
	global_store_dword v[162:163], v59, off offset:384
	global_store_dword v[108:109], v60, off offset:384
	global_store_dword v[164:165], v61, off offset:384
	global_store_dword v[110:111], v62, off offset:384
	global_store_dword v[166:167], v63, off offset:384
	global_store_dword v[112:113], v64, off offset:384
	global_store_dword v[168:169], v65, off offset:384
	s_cbranch_scc0 .LBB0_779

; DI unsigned swz(int row, int chunk) { return (unsigned)row * 128u + (unsigned)((chunk ^ ((row >> 1) & 7)) << 4); }
; #define MFMA32(a, b, c) __builtin_amdgcn_mfma_f32_32x32x16_bf16((a), (b), (c), 0, 0, 0)
;     ...
;             for (int i = 0; i < 4; ++i) *(u32x4*)(lds + swz(lr + 32 * i, lc)) = ra[i];
; #pragma unroll
;             for (int i = 0; i < 8; ++i) *(u32x4*)(lds + 16384 + swz(lr + 32 * i, lc)) = rb[i];
;             __syncthreads();
;             if (kt + 1 < nk) {
; #pragma unroll
;                 for (int i = 0; i < 4; ++i) ra[i] = *(const u32x4*)((Au + (size_t)(32 * i) * lda + (kt + 1) * 64) + voA);
; #pragma unroll
;                 for (int i = 0; i < 8; ++i) rb[i] = *(const u32x4*)((Bu + (size_t)(32 * i) * ldb + (kt + 1) * 64) + voB);
;             }
;             __builtin_amdgcn_s_setprio(1);
; #pragma unroll 2
;             for (int ks = 0; ks < 4; ++ks) {
;                 bf16x8 af[2], bfr[4];
;                 const unsigned xo = (c0 ^ (unsigned)(2 * ks)) << 4;
; #pragma unroll
;                 for (int i = 0; i < 2; ++i) af[i] = *(const bf16x8*)(lds + (roA + xo) + i * 4096);
; #pragma unroll
;                 for (int j = 0; j < 4; ++j) bfr[j] = *(const bf16x8*)(lds + (roB + xo) + j * 4096);
; #pragma unroll
;                 for (int i = 0; i < 2; ++i)
; #pragma unroll
;                     for (int j = 0; j < 4; ++j) acc[i][j] = MFMA32(af[i], bfr[j], acc[i][j]);
;             }
;             __builtin_amdgcn_s_setprio(0);
.LBB0_871:
	s_mov_b32 s0, s5
	s_add_i32 s5, s5, 1
	s_cmp_lt_u32 s0, 15
	s_waitcnt vmcnt(0)
	ds_write_b128 v192, v[130:133]
	ds_write_b128 v192, v[138:141] offset:4096
	ds_write_b128 v192, v[170:173] offset:8192
	ds_write_b128 v192, v[134:137] offset:12288
	ds_write_b128 v192, v[174:177] offset:16384
	ds_write_b128 v192, v[166:169] offset:20480
	ds_write_b128 v192, v[162:165] offset:24576
	ds_write_b128 v192, v[158:161] offset:28672
	ds_write_b128 v192, v[154:157] offset:32768
	ds_write_b128 v192, v[150:153] offset:36864
	ds_write_b128 v192, v[146:149] offset:40960
	ds_write_b128 v192, v[142:145] offset:45056
	s_waitcnt lgkmcnt(0)
	s_barrier
	s_cbranch_scc0 .LBB0_873
	s_lshl_b32 s22, s5, 7
	s_mov_b32 s23, 0
	s_setprio 1
	v_xor_b32_e32 v1, 0, v187
	v_add_u32_e32 v193, v188, v1
	v_add_u32_e32 v1, v189, v1
	ds_read_b128 v[194:197], v193
	ds_read_b128 v[198:201], v1 offset:16384
	ds_read_b128 v[202:205], v193 offset:4096
	ds_read_b128 v[206:209], v1 offset:20480
	ds_read_b128 v[210:213], v1 offset:24576
	ds_read_b128 v[218:221], v1 offset:28672
	s_waitcnt lgkmcnt(4)
	v_mfma_f32_32x32x16_bf16 v[114:129], v[194:197], v[198:201], v[114:129]
	v_lshl_add_u64 v[222:223], v[182:183], 0, s[22:23]
	global_load_dwordx4 v[130:133], v[222:223], off
	s_add_u32 s22, s22, 0x10000
	s_mov_b32 s7, 32
	v_xor_b32_e32 v1, s7, v187
	v_add_u32_e32 v193, v188, v1
	v_add_u32_e32 v1, v189, v1
	s_waitcnt lgkmcnt(2)
	v_mfma_f32_32x32x16_bf16 v[98:113], v[194:197], v[206:209], v[98:113]
	v_lshl_add_u64 v[224:225], v[182:183], 0, s[22:23]
	global_load_dwordx4 v[138:141], v[224:225], off
	s_add_u32 s22, s22, 0x10000
	s_waitcnt lgkmcnt(1)
	v_mfma_f32_32x32x16_bf16 v[82:97], v[194:197], v[210:213], v[82:97]
	v_lshl_add_u64 v[226:227], v[182:183], 0, s[22:23]
	global_load_dwordx4 v[170:173], v[226:227], off
	s_add_u32 s22, s22, 0x10000
	s_waitcnt lgkmcnt(0)
	v_mfma_f32_32x32x16_bf16 v[66:81], v[194:197], v[218:221], v[66:81]
	v_lshl_add_u64 v[222:223], v[182:183], 0, s[22:23]
	global_load_dwordx4 v[134:137], v[222:223], off
	s_sub_u32 s22, s22, 0x30000
	v_mfma_f32_32x32x16_bf16 v[50:65], v[202:205], v[198:201], v[50:65]
	v_lshl_add_u64 v[224:225], v[184:185], 0, s[22:23]
	global_load_dwordx4 v[174:177], v[224:225], off
	s_add_u32 s22, s22, 0x10000
	v_mfma_f32_32x32x16_bf16 v[34:49], v[202:205], v[206:209], v[34:49]
	v_lshl_add_u64 v[226:227], v[184:185], 0, s[22:23]
	global_load_dwordx4 v[166:169], v[226:227], off
	s_add_u32 s22, s22, 0x10000
	v_mfma_f32_32x32x16_bf16 v[18:33], v[202:205], v[210:213], v[18:33]
	v_lshl_add_u64 v[222:223], v[184:185], 0, s[22:23]
	global_load_dwordx4 v[162:165], v[222:223], off
	s_add_u32 s22, s22, 0x10000
	v_mfma_f32_32x32x16_bf16 v[2:17], v[202:205], v[218:221], v[2:17]
	v_lshl_add_u64 v[224:225], v[184:185], 0, s[22:23]
	global_load_dwordx4 v[158:161], v[224:225], off
	s_add_u32 s22, s22, 0x10000
	ds_read_b128 v[194:197], v193
	ds_read_b128 v[198:201], v1 offset:16384
	ds_read_b128 v[202:205], v193 offset:4096
	ds_read_b128 v[206:209], v1 offset:20480
	ds_read_b128 v[210:213], v1 offset:24576
	ds_read_b128 v[218:221], v1 offset:28672
	s_waitcnt lgkmcnt(4)
	v_mfma_f32_32x32x16_bf16 v[114:129], v[194:197], v[198:201], v[114:129]
	v_lshl_add_u64 v[226:227], v[184:185], 0, s[22:23]
	global_load_dwordx4 v[154:157], v[226:227], off
	s_add_u32 s22, s22, 0x10000
	s_waitcnt lgkmcnt(2)
	v_mfma_f32_32x32x16_bf16 v[98:113], v[194:197], v[206:209], v[98:113]
	v_lshl_add_u64 v[222:223], v[184:185], 0, s[22:23]
	global_load_dwordx4 v[150:153], v[222:223], off
	s_add_u32 s22, s22, 0x10000
	s_waitcnt lgkmcnt(1)
	v_mfma_f32_32x32x16_bf16 v[82:97], v[194:197], v[210:213], v[82:97]
	v_lshl_add_u64 v[224:225], v[184:185], 0, s[22:23]
	global_load_dwordx4 v[146:149], v[224:225], off
	s_add_u32 s22, s22, 0x10000
	s_waitcnt lgkmcnt(0)
	v_mfma_f32_32x32x16_bf16 v[66:81], v[194:197], v[218:221], v[66:81]
	v_lshl_add_u64 v[226:227], v[184:185], 0, s[22:23]
	global_load_dwordx4 v[142:145], v[226:227], off
	v_mfma_f32_32x32x16_bf16 v[50:65], v[202:205], v[198:201], v[50:65]
	v_mfma_f32_32x32x16_bf16 v[34:49], v[202:205], v[206:209], v[34:49]
	v_mfma_f32_32x32x16_bf16 v[18:33], v[202:205], v[210:213], v[18:33]
	v_mfma_f32_32x32x16_bf16 v[2:17], v[202:205], v[218:221], v[2:17]
	v_xor_b32_e32 v1, 64, v187
	v_add_u32_e32 v193, v188, v1
	v_add_u32_e32 v1, v189, v1
	ds_read_b128 v[194:197], v193
	ds_read_b128 v[198:201], v1 offset:16384
	ds_read_b128 v[202:205], v193 offset:4096
	ds_read_b128 v[206:209], v1 offset:20480
	ds_read_b128 v[210:213], v1 offset:24576
	ds_read_b128 v[218:221], v1 offset:28672
	s_waitcnt lgkmcnt(4)
	v_mfma_f32_32x32x16_bf16 v[114:129], v[194:197], v[198:201], v[114:129]
	s_mov_b32 s7, 96
	v_xor_b32_e32 v1, s7, v187
	v_add_u32_e32 v193, v188, v1
	v_add_u32_e32 v1, v189, v1
	s_waitcnt lgkmcnt(2)
	v_mfma_f32_32x32x16_bf16 v[98:113], v[194:197], v[206:209], v[98:113]
	s_waitcnt lgkmcnt(1)
	v_mfma_f32_32x32x16_bf16 v[82:97], v[194:197], v[210:213], v[82:97]
	s_waitcnt lgkmcnt(0)
	v_mfma_f32_32x32x16_bf16 v[66:81], v[194:197], v[218:221], v[66:81]
	v_mfma_f32_32x32x16_bf16 v[50:65], v[202:205], v[198:201], v[50:65]
	v_mfma_f32_32x32x16_bf16 v[34:49], v[202:205], v[206:209], v[34:49]
	v_mfma_f32_32x32x16_bf16 v[18:33], v[202:205], v[210:213], v[18:33]
	v_mfma_f32_32x32x16_bf16 v[2:17], v[202:205], v[218:221], v[2:17]
	ds_read_b128 v[194:197], v193
	ds_read_b128 v[198:201], v1 offset:16384
	ds_read_b128 v[202:205], v193 offset:4096
	ds_read_b128 v[206:209], v1 offset:20480
	ds_read_b128 v[210:213], v1 offset:24576
	ds_read_b128 v[218:221], v1 offset:28672
	s_waitcnt lgkmcnt(4)
	v_mfma_f32_32x32x16_bf16 v[114:129], v[194:197], v[198:201], v[114:129]
	s_waitcnt lgkmcnt(2)
	v_mfma_f32_32x32x16_bf16 v[98:113], v[194:197], v[206:209], v[98:113]
	s_waitcnt lgkmcnt(1)
	v_mfma_f32_32x32x16_bf16 v[82:97], v[194:197], v[210:213], v[82:97]
	s_waitcnt lgkmcnt(0)
	v_mfma_f32_32x32x16_bf16 v[66:81], v[194:197], v[218:221], v[66:81]
	v_mfma_f32_32x32x16_bf16 v[50:65], v[202:205], v[198:201], v[50:65]
	v_mfma_f32_32x32x16_bf16 v[34:49], v[202:205], v[206:209], v[34:49]
	v_mfma_f32_32x32x16_bf16 v[18:33], v[202:205], v[210:213], v[18:33]
	v_mfma_f32_32x32x16_bf16 v[2:17], v[202:205], v[218:221], v[2:17]
	s_branch .Lkint_done_874

; DI int cu(int r) { return (r & 3) + 8 * (r >> 2); }
;     ...
;             __builtin_amdgcn_s_setprio(0);
;             __syncthreads();
;     template <int NI> DI void operator()(const f32x16 (&acc)[2][NI], int row0, int col0, int lane) const {
;         if (col0 >= ldc) return;
;         const unsigned lo = (unsigned)(4 * (lane >> 5) * ldc + (lane & 31));
;         bf16_t* base = C + (size_t)row0 * ldc + col0;
; #pragma unroll
;         for (int mi = 0; mi < 2; ++mi)
; #pragma unroll
;             for (int ni = 0; ni < NI; ++ni)
; #pragma unroll
;                 for (int r = 0; r < 16; ++r) (base + (size_t)(32 * mi + cu(r)) * ldc + 32 * ni)[lo] = f2bf(acc[mi][ni][r]);
.Lkint_done_874:
	s_setprio 0
	s_cmp_eq_u32 s5, 16
	s_barrier
	s_cbranch_scc0 .LBB0_871
	s_waitcnt vmcnt(11)
	v_or_b32_e32 v130, s4, v190
	v_mov_b32_e32 v1, v186
	v_cmp_gt_i32_e32 vcc, s15, v130
	s_and_saveexec_b64 s[4:5], vcc
	s_cbranch_execz .LBB0_869
	v_lshrrev_b32_e32 v132, 3, v1
	v_add_u32_e32 v131, s6, v191
	v_and_b32_e32 v132, 0x1fffffc, v132
	s_waitcnt vmcnt(8)
	v_mov_b64_e32 v[134:135], s[82:83]
	v_mul_lo_u32 v132, v132, s15
	v_mad_i64_i32 v[134:135], s[6:7], v131, s16, v[134:135]
	v_ashrrev_i32_e32 v131, 31, v130
	v_and_or_b32 v132, v1, 31, v132
	v_lshl_add_u64 v[130:131], v[130:131], 1, v[134:135]
	v_mov_b32_e32 v133, v0
	v_lshl_add_u64 v[130:131], v[132:133], 1, v[130:131]
	v_cvt_pk_bf16_f32 v1, v114, s0
	v_add_co_u32_e32 v114, vcc, s17, v130
	global_store_short v[130:131], v1, off
	v_cvt_pk_bf16_f32 v1, v115, s0
	v_addc_co_u32_e32 v115, vcc, 0, v131, vcc
	v_add_co_u32_e32 v132, vcc, s30, v130
	global_store_short v[114:115], v1, off offset:1792
	s_nop 0
	v_addc_co_u32_e32 v133, vcc, 0, v131, vcc
	v_cvt_pk_bf16_f32 v1, v116, s0
	v_add_co_u32_e32 v116, vcc, s31, v130
	global_store_short v[132:133], v1, off offset:3584
	v_cvt_pk_bf16_f32 v1, v117, s0
	v_addc_co_u32_e32 v117, vcc, 0, v131, vcc
	v_add_co_u32_e32 v134, vcc, s34, v130
	global_store_short v[116:117], v1, off offset:1280
	s_nop 0
	v_addc_co_u32_e32 v135, vcc, 0, v131, vcc
	v_cvt_pk_bf16_f32 v1, v118, s0
	v_add_co_u32_e32 v118, vcc, s35, v130
	global_store_short v[134:135], v1, off offset:2048
	v_cvt_pk_bf16_f32 v1, v119, s0
	v_addc_co_u32_e32 v119, vcc, 0, v131, vcc
	v_add_co_u32_e32 v136, vcc, s46, v130
	global_store_short v[118:119], v1, off offset:3840
	s_nop 0
	v_addc_co_u32_e32 v137, vcc, 0, v131, vcc
	v_cvt_pk_bf16_f32 v1, v120, s0
	v_add_co_u32_e32 v120, vcc, s47, v130
	global_store_short v[136:137], v1, off offset:1536
	v_cvt_pk_bf16_f32 v1, v121, s0
	v_addc_co_u32_e32 v121, vcc, 0, v131, vcc
	v_add_co_u32_e32 v138, vcc, s62, v130
	global_store_short v[120:121], v1, off offset:3328
	s_nop 0
	v_addc_co_u32_e32 v139, vcc, 0, v131, vcc
	v_cvt_pk_bf16_f32 v1, v122, s0
	v_add_co_u32_e32 v122, vcc, s63, v130
	global_store_short v[138:139], v1, off
	v_cvt_pk_bf16_f32 v1, v123, s0
	v_addc_co_u32_e32 v123, vcc, 0, v131, vcc
	v_add_co_u32_e32 v140, vcc, s68, v130
	global_store_short v[122:123], v1, off offset:1792
	s_nop 0
	v_addc_co_u32_e32 v141, vcc, 0, v131, vcc
	v_cvt_pk_bf16_f32 v1, v124, s0
	v_add_co_u32_e32 v124, vcc, s69, v130
	global_store_short v[140:141], v1, off offset:3584
	v_cvt_pk_bf16_f32 v1, v125, s0
	v_addc_co_u32_e32 v125, vcc, 0, v131, vcc
	s_waitcnt vmcnt(11)
	v_add_co_u32_e32 v142, vcc, s70, v130
	global_store_short v[124:125], v1, off offset:1280
	s_nop 0
	v_addc_co_u32_e32 v143, vcc, 0, v131, vcc
	v_cvt_pk_bf16_f32 v1, v126, s0
	v_add_co_u32_e32 v126, vcc, s71, v130
	global_store_short v[142:143], v1, off offset:2048
	v_cvt_pk_bf16_f32 v1, v127, s0
	v_addc_co_u32_e32 v127, vcc, 0, v131, vcc
	v_add_co_u32_e32 v144, vcc, s72, v130
	global_store_short v[126:127], v1, off offset:3840
	s_nop 0
	v_addc_co_u32_e32 v145, vcc, 0, v131, vcc
	v_cvt_pk_bf16_f32 v1, v128, s0
	v_add_co_u32_e32 v128, vcc, s73, v130
	global_store_short v[144:145], v1, off offset:1536
	v_cvt_pk_bf16_f32 v1, v129, s0
	v_addc_co_u32_e32 v129, vcc, 0, v131, vcc
	global_store_short v[128:129], v1, off offset:3328
	v_cvt_pk_bf16_f32 v1, v98, s0
	global_store_short v[130:131], v1, off offset:64
	v_cvt_pk_bf16_f32 v1, v99, s0
	global_store_short v[114:115], v1, off offset:1856
	v_cvt_pk_bf16_f32 v1, v100, s0
	global_store_short v[132:133], v1, off offset:3648
	v_cvt_pk_bf16_f32 v1, v101, s0
	global_store_short v[116:117], v1, off offset:1344
	v_cvt_pk_bf16_f32 v1, v102, s0
	global_store_short v[134:135], v1, off offset:2112
	v_cvt_pk_bf16_f32 v1, v103, s0
	global_store_short v[118:119], v1, off offset:3904
	v_cvt_pk_bf16_f32 v1, v104, s0
	global_store_short v[136:137], v1, off offset:1600
	v_cvt_pk_bf16_f32 v1, v105, s0
	global_store_short v[120:121], v1, off offset:3392
	v_cvt_pk_bf16_f32 v1, v106, s0
	global_store_short v[138:139], v1, off offset:64
	v_cvt_pk_bf16_f32 v1, v107, s0
	global_store_short v[122:123], v1, off offset:1856
	v_cvt_pk_bf16_f32 v1, v108, s0
	global_store_short v[140:141], v1, off offset:3648
	v_cvt_pk_bf16_f32 v1, v109, s0
	global_store_short v[124:125], v1, off offset:1344
	v_cvt_pk_bf16_f32 v1, v110, s0
	global_store_short v[142:143], v1, off offset:2112
	v_cvt_pk_bf16_f32 v1, v111, s0
	global_store_short v[126:127], v1, off offset:3904
	v_cvt_pk_bf16_f32 v1, v112, s0
	global_store_short v[144:145], v1, off offset:1600
	v_cvt_pk_bf16_f32 v1, v113, s0
	global_store_short v[128:129], v1, off offset:3392
	v_cvt_pk_bf16_f32 v1, v82, s0
	global_store_short v[130:131], v1, off offset:128
	v_cvt_pk_bf16_f32 v1, v83, s0
	global_store_short v[114:115], v1, off offset:1920
	v_cvt_pk_bf16_f32 v1, v84, s0
	global_store_short v[132:133], v1, off offset:3712
	v_cvt_pk_bf16_f32 v1, v85, s0
	global_store_short v[116:117], v1, off offset:1408
	v_cvt_pk_bf16_f32 v1, v86, s0
	global_store_short v[134:135], v1, off offset:2176
	v_cvt_pk_bf16_f32 v1, v87, s0
	global_store_short v[118:119], v1, off offset:3968
	v_cvt_pk_bf16_f32 v1, v88, s0
	global_store_short v[136:137], v1, off offset:1664
	v_cvt_pk_bf16_f32 v1, v89, s0
	global_store_short v[120:121], v1, off offset:3456
	v_cvt_pk_bf16_f32 v1, v90, s0
	global_store_short v[138:139], v1, off offset:128
	v_cvt_pk_bf16_f32 v1, v91, s0
	global_store_short v[122:123], v1, off offset:1920
	v_cvt_pk_bf16_f32 v1, v92, s0
	global_store_short v[140:141], v1, off offset:3712
	v_cvt_pk_bf16_f32 v1, v93, s0
	global_store_short v[124:125], v1, off offset:1408
; DI int cu(int r) { return (r & 3) + 8 * (r >> 2); }
;     template <int NI> DI void operator()(const f32x16 (&acc)[2][NI], int row0, int col0, int lane) const {
;         if (col0 >= ldc) return;
;         const unsigned lo = (unsigned)(4 * (lane >> 5) * ldc + (lane & 31));
;         bf16_t* base = C + (size_t)row0 * ldc + col0;
; #pragma unroll
;         for (int mi = 0; mi < 2; ++mi)
; #pragma unroll
;             for (int ni = 0; ni < NI; ++ni)
; #pragma unroll
;                 for (int r = 0; r < 16; ++r) (base + (size_t)(32 * mi + cu(r)) * ldc + 32 * ni)[lo] = f2bf(acc[mi][ni][r]);
	v_cvt_pk_bf16_f32 v1, v94, s0
	global_store_short v[142:143], v1, off offset:2176
	v_cvt_pk_bf16_f32 v1, v95, s0
	global_store_short v[126:127], v1, off offset:3968
	v_cvt_pk_bf16_f32 v1, v96, s0
	global_store_short v[144:145], v1, off offset:1664
	v_cvt_pk_bf16_f32 v1, v97, s0
	global_store_short v[128:129], v1, off offset:3456
	v_cvt_pk_bf16_f32 v1, v66, s0
	global_store_short v[130:131], v1, off offset:192
	v_cvt_pk_bf16_f32 v1, v67, s0
	global_store_short v[114:115], v1, off offset:1984
	v_cvt_pk_bf16_f32 v1, v68, s0
	global_store_short v[132:133], v1, off offset:3776
	v_cvt_pk_bf16_f32 v1, v69, s0
	global_store_short v[116:117], v1, off offset:1472
	v_cvt_pk_bf16_f32 v1, v70, s0
	global_store_short v[134:135], v1, off offset:2240
	v_cvt_pk_bf16_f32 v1, v71, s0
	global_store_short v[118:119], v1, off offset:4032
	v_cvt_pk_bf16_f32 v1, v72, s0
	global_store_short v[136:137], v1, off offset:1728
	v_cvt_pk_bf16_f32 v1, v73, s0
	global_store_short v[120:121], v1, off offset:3520
	v_cvt_pk_bf16_f32 v1, v74, s0
	global_store_short v[138:139], v1, off offset:192
	v_cvt_pk_bf16_f32 v1, v75, s0
	global_store_short v[122:123], v1, off offset:1984
	v_cvt_pk_bf16_f32 v1, v76, s0
	global_store_short v[140:141], v1, off offset:3776
	v_cvt_pk_bf16_f32 v1, v77, s0
	global_store_short v[124:125], v1, off offset:1472
	v_cvt_pk_bf16_f32 v1, v78, s0
	global_store_short v[142:143], v1, off offset:2240
	v_cvt_pk_bf16_f32 v1, v79, s0
	global_store_short v[126:127], v1, off offset:4032
	v_cvt_pk_bf16_f32 v1, v80, s0
	v_add_co_u32_e32 v66, vcc, s74, v130
	global_store_short v[144:145], v1, off offset:1728
	v_cvt_pk_bf16_f32 v1, v81, s0
	v_addc_co_u32_e32 v67, vcc, 0, v131, vcc
	global_store_short v[128:129], v1, off offset:3520
	v_cvt_pk_bf16_f32 v1, v50, s0
	v_add_co_u32_e32 v50, vcc, s75, v130
	global_store_short v[66:67], v1, off
	v_cvt_pk_bf16_f32 v1, v51, s0
	v_addc_co_u32_e32 v51, vcc, 0, v131, vcc
	v_add_co_u32_e32 v68, vcc, s14, v130
	global_store_short v[50:51], v1, off offset:1792
	s_nop 0
	v_addc_co_u32_e32 v69, vcc, 0, v131, vcc
	v_cvt_pk_bf16_f32 v1, v52, s0
	v_add_co_u32_e32 v52, vcc, s78, v130
	global_store_short v[68:69], v1, off offset:3584
	v_cvt_pk_bf16_f32 v1, v53, s0
	v_addc_co_u32_e32 v53, vcc, 0, v131, vcc
	v_add_co_u32_e32 v70, vcc, s79, v130
	global_store_short v[52:53], v1, off offset:1280
	s_nop 0
	v_addc_co_u32_e32 v71, vcc, 0, v131, vcc
	v_cvt_pk_bf16_f32 v1, v54, s0
	v_add_co_u32_e32 v54, vcc, s86, v130
	global_store_short v[70:71], v1, off offset:2048
	v_cvt_pk_bf16_f32 v1, v55, s0
	v_addc_co_u32_e32 v55, vcc, 0, v131, vcc
	v_add_co_u32_e32 v72, vcc, s87, v130
	global_store_short v[54:55], v1, off offset:3840
	s_nop 0
	v_addc_co_u32_e32 v73, vcc, 0, v131, vcc
	v_cvt_pk_bf16_f32 v1, v56, s0
	v_add_co_u32_e32 v56, vcc, s88, v130
	global_store_short v[72:73], v1, off offset:1536
	v_cvt_pk_bf16_f32 v1, v57, s0
	v_addc_co_u32_e32 v57, vcc, 0, v131, vcc
	v_add_co_u32_e32 v74, vcc, s89, v130
	global_store_short v[56:57], v1, off offset:3328
	s_nop 0
	v_addc_co_u32_e32 v75, vcc, 0, v131, vcc
	v_cvt_pk_bf16_f32 v1, v58, s0
	v_add_co_u32_e32 v58, vcc, s90, v130
	global_store_short v[74:75], v1, off
	v_cvt_pk_bf16_f32 v1, v59, s0
	v_addc_co_u32_e32 v59, vcc, 0, v131, vcc
	v_add_co_u32_e32 v76, vcc, s91, v130
	global_store_short v[58:59], v1, off offset:1792
	s_nop 0
	v_addc_co_u32_e32 v77, vcc, 0, v131, vcc
	v_cvt_pk_bf16_f32 v1, v60, s0
	v_add_co_u32_e32 v60, vcc, s92, v130
	global_store_short v[76:77], v1, off offset:3584
	v_cvt_pk_bf16_f32 v1, v61, s0
	v_addc_co_u32_e32 v61, vcc, 0, v131, vcc
	v_add_co_u32_e32 v78, vcc, s12, v130
	global_store_short v[60:61], v1, off offset:1280
	s_nop 0
	v_addc_co_u32_e32 v79, vcc, 0, v131, vcc
	v_cvt_pk_bf16_f32 v1, v62, s0
	v_add_co_u32_e32 v62, vcc, s93, v130
	global_store_short v[78:79], v1, off offset:2048
	v_cvt_pk_bf16_f32 v1, v63, s0
	v_addc_co_u32_e32 v63, vcc, 0, v131, vcc
	v_add_co_u32_e32 v80, vcc, s94, v130
	global_store_short v[62:63], v1, off offset:3840
	s_nop 0
	v_addc_co_u32_e32 v81, vcc, 0, v131, vcc
	v_cvt_pk_bf16_f32 v1, v64, s0
	v_add_co_u32_e32 v64, vcc, s95, v130
; DI int cu(int r) { return (r & 3) + 8 * (r >> 2); }
;     template <int NI> DI void operator()(const f32x16 (&acc)[2][NI], int row0, int col0, int lane) const {
;         if (col0 >= ldc) return;
;         const unsigned lo = (unsigned)(4 * (lane >> 5) * ldc + (lane & 31));
;         bf16_t* base = C + (size_t)row0 * ldc + col0;
; #pragma unroll
;         for (int mi = 0; mi < 2; ++mi)
; #pragma unroll
;             for (int ni = 0; ni < NI; ++ni)
; #pragma unroll
;                 for (int r = 0; r < 16; ++r) (base + (size_t)(32 * mi + cu(r)) * ldc + 32 * ni)[lo] = f2bf(acc[mi][ni][r]);
	global_store_short v[80:81], v1, off offset:1536
	v_cvt_pk_bf16_f32 v1, v65, s0
	v_addc_co_u32_e32 v65, vcc, 0, v131, vcc
	global_store_short v[64:65], v1, off offset:3328
	v_cvt_pk_bf16_f32 v1, v34, s0
	global_store_short v[66:67], v1, off offset:64
	v_cvt_pk_bf16_f32 v1, v35, s0
	global_store_short v[50:51], v1, off offset:1856
	v_cvt_pk_bf16_f32 v1, v36, s0
	global_store_short v[68:69], v1, off offset:3648
	v_cvt_pk_bf16_f32 v1, v37, s0
	global_store_short v[52:53], v1, off offset:1344
	v_cvt_pk_bf16_f32 v1, v38, s0
	global_store_short v[70:71], v1, off offset:2112
	v_cvt_pk_bf16_f32 v1, v39, s0
	global_store_short v[54:55], v1, off offset:3904
	v_cvt_pk_bf16_f32 v1, v40, s0
	global_store_short v[72:73], v1, off offset:1600
	v_cvt_pk_bf16_f32 v1, v41, s0
	global_store_short v[56:57], v1, off offset:3392
	v_cvt_pk_bf16_f32 v1, v42, s0
	global_store_short v[74:75], v1, off offset:64
	v_cvt_pk_bf16_f32 v1, v43, s0
	global_store_short v[58:59], v1, off offset:1856
	v_cvt_pk_bf16_f32 v1, v44, s0
	global_store_short v[76:77], v1, off offset:3648
	v_cvt_pk_bf16_f32 v1, v45, s0
	global_store_short v[60:61], v1, off offset:1344
	v_cvt_pk_bf16_f32 v1, v46, s0
	global_store_short v[78:79], v1, off offset:2112
	v_cvt_pk_bf16_f32 v1, v47, s0
	global_store_short v[62:63], v1, off offset:3904
	v_cvt_pk_bf16_f32 v1, v48, s0
	global_store_short v[80:81], v1, off offset:1600
	v_cvt_pk_bf16_f32 v1, v49, s0
	global_store_short v[64:65], v1, off offset:3392
	v_cvt_pk_bf16_f32 v1, v18, s0
	global_store_short v[66:67], v1, off offset:128
	v_cvt_pk_bf16_f32 v1, v19, s0
	global_store_short v[50:51], v1, off offset:1920
	v_cvt_pk_bf16_f32 v1, v20, s0
	global_store_short v[68:69], v1, off offset:3712
	v_cvt_pk_bf16_f32 v1, v21, s0
	global_store_short v[52:53], v1, off offset:1408
	v_cvt_pk_bf16_f32 v1, v22, s0
	global_store_short v[70:71], v1, off offset:2176
	v_cvt_pk_bf16_f32 v1, v23, s0
	global_store_short v[54:55], v1, off offset:3968
	v_cvt_pk_bf16_f32 v1, v24, s0
	global_store_short v[72:73], v1, off offset:1664
	v_cvt_pk_bf16_f32 v1, v25, s0
	global_store_short v[56:57], v1, off offset:3456
	v_cvt_pk_bf16_f32 v1, v26, s0
	global_store_short v[74:75], v1, off offset:128
	v_cvt_pk_bf16_f32 v1, v27, s0
	global_store_short v[58:59], v1, off offset:1920
	v_cvt_pk_bf16_f32 v1, v28, s0
	global_store_short v[76:77], v1, off offset:3712
	v_cvt_pk_bf16_f32 v1, v29, s0
	global_store_short v[60:61], v1, off offset:1408
	v_cvt_pk_bf16_f32 v1, v30, s0
	global_store_short v[78:79], v1, off offset:2176
	v_cvt_pk_bf16_f32 v1, v31, s0
	global_store_short v[62:63], v1, off offset:3968
	v_cvt_pk_bf16_f32 v1, v32, s0
	global_store_short v[80:81], v1, off offset:1664
	v_cvt_pk_bf16_f32 v1, v33, s0
	global_store_short v[64:65], v1, off offset:3456
	v_cvt_pk_bf16_f32 v1, v2, s0
	global_store_short v[66:67], v1, off offset:192
	v_cvt_pk_bf16_f32 v1, v3, s0
	global_store_short v[50:51], v1, off offset:1984
	v_cvt_pk_bf16_f32 v1, v4, s0
	global_store_short v[68:69], v1, off offset:3776
	v_cvt_pk_bf16_f32 v1, v5, s0
	global_store_short v[52:53], v1, off offset:1472
	v_cvt_pk_bf16_f32 v1, v6, s0
	global_store_short v[70:71], v1, off offset:2240
	v_cvt_pk_bf16_f32 v1, v7, s0
	global_store_short v[54:55], v1, off offset:4032
	v_cvt_pk_bf16_f32 v1, v8, s0
	global_store_short v[72:73], v1, off offset:1728
	v_cvt_pk_bf16_f32 v1, v9, s0
	global_store_short v[56:57], v1, off offset:3520
	v_cvt_pk_bf16_f32 v1, v10, s0
	global_store_short v[74:75], v1, off offset:192
	v_cvt_pk_bf16_f32 v1, v11, s0
	global_store_short v[58:59], v1, off offset:1984
	v_cvt_pk_bf16_f32 v1, v12, s0
	global_store_short v[76:77], v1, off offset:3776
	v_cvt_pk_bf16_f32 v1, v13, s0
	global_store_short v[60:61], v1, off offset:1472
	v_cvt_pk_bf16_f32 v1, v14, s0
	global_store_short v[78:79], v1, off offset:2240
	v_cvt_pk_bf16_f32 v1, v15, s0
	global_store_short v[62:63], v1, off offset:4032
	v_cvt_pk_bf16_f32 v1, v16, s0
	global_store_short v[80:81], v1, off offset:1728
	v_cvt_pk_bf16_f32 v1, v17, s0
	global_store_short v[64:65], v1, off offset:3520
	s_branch .LBB0_869

; DI unsigned swz(int row, int chunk) { return (unsigned)row * 128u + (unsigned)((chunk ^ ((row >> 1) & 7)) << 4); }
; #define MFMA32(a, b, c) __builtin_amdgcn_mfma_f32_32x32x16_bf16((a), (b), (c), 0, 0, 0)
;     ...
;             for (int i = 0; i < 4; ++i) *(u32x4*)(lds + swz(lr + 32 * i, lc)) = ra[i];
; #pragma unroll
;             for (int i = 0; i < 8; ++i) *(u32x4*)(lds + 16384 + swz(lr + 32 * i, lc)) = rb[i];
;             __syncthreads();
;             if (kt + 1 < nk) {
; #pragma unroll
;                 for (int i = 0; i < 4; ++i) ra[i] = *(const u32x4*)((Au + (size_t)(32 * i) * lda + (kt + 1) * 64) + voA);
; #pragma unroll
;                 for (int i = 0; i < 8; ++i) rb[i] = *(const u32x4*)((Bu + (size_t)(32 * i) * ldb + (kt + 1) * 64) + voB);
;             }
;             __builtin_amdgcn_s_setprio(1);
; #pragma unroll 2
;             for (int ks = 0; ks < 4; ++ks) {
;                 bf16x8 af[2], bfr[4];
;                 const unsigned xo = (c0 ^ (unsigned)(2 * ks)) << 4;
; #pragma unroll
;                 for (int i = 0; i < 2; ++i) af[i] = *(const bf16x8*)(lds + (roA + xo) + i * 4096);
; #pragma unroll
;                 for (int j = 0; j < 4; ++j) bfr[j] = *(const bf16x8*)(lds + (roB + xo) + j * 4096);
; #pragma unroll
;                 for (int i = 0; i < 2; ++i)
; #pragma unroll
;                     for (int j = 0; j < 4; ++j) acc[i][j] = MFMA32(af[i], bfr[j], acc[i][j]);
;             }
;             __builtin_amdgcn_s_setprio(0);
.LBB0_1252:
	s_mov_b32 s4, s9
	s_add_i32 s9, s9, 1
	s_cmp_lt_u32 s4, 15
	s_waitcnt vmcnt(0)
	ds_write_b128 v192, v[130:133]
	ds_write_b128 v192, v[138:141] offset:4096
	ds_write_b128 v192, v[170:173] offset:8192
	ds_write_b128 v192, v[134:137] offset:12288
	ds_write_b128 v192, v[174:177] offset:16384
	ds_write_b128 v192, v[166:169] offset:20480
	ds_write_b128 v192, v[162:165] offset:24576
	ds_write_b128 v192, v[158:161] offset:28672
	ds_write_b128 v192, v[154:157] offset:32768
	ds_write_b128 v192, v[150:153] offset:36864
	ds_write_b128 v192, v[146:149] offset:40960
	ds_write_b128 v192, v[142:145] offset:45056
	s_waitcnt lgkmcnt(0)
	s_barrier
	s_cbranch_scc0 .LBB0_1254
	s_lshl_b32 s18, s9, 7
	s_mov_b32 s19, 0
	s_setprio 1
	v_xor_b32_e32 v1, 0, v187
	v_add_u32_e32 v193, v188, v1
	v_add_u32_e32 v1, v189, v1
	ds_read_b128 v[194:197], v193
	ds_read_b128 v[198:201], v1 offset:16384
	ds_read_b128 v[202:205], v193 offset:4096
	ds_read_b128 v[206:209], v1 offset:20480
	ds_read_b128 v[210:213], v1 offset:24576
	ds_read_b128 v[218:221], v1 offset:28672
	s_waitcnt lgkmcnt(4)
	v_mfma_f32_32x32x16_bf16 v[114:129], v[194:197], v[198:201], v[114:129]
	v_lshl_add_u64 v[222:223], v[182:183], 0, s[18:19]
	global_load_dwordx4 v[130:133], v[222:223], off
	s_add_u32 s18, s18, 0x10000
	s_mov_b32 s11, 32
	v_xor_b32_e32 v1, s11, v187
	v_add_u32_e32 v193, v188, v1
	v_add_u32_e32 v1, v189, v1
	s_waitcnt lgkmcnt(2)
	v_mfma_f32_32x32x16_bf16 v[82:97], v[194:197], v[206:209], v[82:97]
	v_lshl_add_u64 v[224:225], v[182:183], 0, s[18:19]
	global_load_dwordx4 v[138:141], v[224:225], off
	s_add_u32 s18, s18, 0x10000
	s_waitcnt lgkmcnt(1)
	v_mfma_f32_32x32x16_bf16 v[50:65], v[194:197], v[210:213], v[50:65]
	v_lshl_add_u64 v[226:227], v[182:183], 0, s[18:19]
	global_load_dwordx4 v[170:173], v[226:227], off
	s_add_u32 s18, s18, 0x10000
	s_waitcnt lgkmcnt(0)
	v_mfma_f32_32x32x16_bf16 v[18:33], v[194:197], v[218:221], v[18:33]
	v_lshl_add_u64 v[222:223], v[182:183], 0, s[18:19]
	global_load_dwordx4 v[134:137], v[222:223], off
	s_sub_u32 s18, s18, 0x30000
	v_mfma_f32_32x32x16_bf16 v[98:113], v[202:205], v[198:201], v[98:113]
	v_lshl_add_u64 v[224:225], v[184:185], 0, s[18:19]
	global_load_dwordx4 v[174:177], v[224:225], off
	s_add_u32 s18, s18, 0x10000
	v_mfma_f32_32x32x16_bf16 v[66:81], v[202:205], v[206:209], v[66:81]
	v_lshl_add_u64 v[226:227], v[184:185], 0, s[18:19]
	global_load_dwordx4 v[166:169], v[226:227], off
	s_add_u32 s18, s18, 0x10000
	v_mfma_f32_32x32x16_bf16 v[34:49], v[202:205], v[210:213], v[34:49]
	v_lshl_add_u64 v[222:223], v[184:185], 0, s[18:19]
	global_load_dwordx4 v[162:165], v[222:223], off
	s_add_u32 s18, s18, 0x10000
	v_mfma_f32_32x32x16_bf16 v[2:17], v[202:205], v[218:221], v[2:17]
	v_lshl_add_u64 v[224:225], v[184:185], 0, s[18:19]
	global_load_dwordx4 v[158:161], v[224:225], off
	s_add_u32 s18, s18, 0x10000
	ds_read_b128 v[194:197], v193
	ds_read_b128 v[198:201], v1 offset:16384
	ds_read_b128 v[202:205], v193 offset:4096
	ds_read_b128 v[206:209], v1 offset:20480
	ds_read_b128 v[210:213], v1 offset:24576
	ds_read_b128 v[218:221], v1 offset:28672
	s_waitcnt lgkmcnt(4)
	v_mfma_f32_32x32x16_bf16 v[114:129], v[194:197], v[198:201], v[114:129]
	v_lshl_add_u64 v[226:227], v[184:185], 0, s[18:19]
	global_load_dwordx4 v[154:157], v[226:227], off
	s_add_u32 s18, s18, 0x10000
	s_waitcnt lgkmcnt(2)
	v_mfma_f32_32x32x16_bf16 v[82:97], v[194:197], v[206:209], v[82:97]
	v_lshl_add_u64 v[222:223], v[184:185], 0, s[18:19]
	global_load_dwordx4 v[150:153], v[222:223], off
	s_add_u32 s18, s18, 0x10000
	s_waitcnt lgkmcnt(1)
	v_mfma_f32_32x32x16_bf16 v[50:65], v[194:197], v[210:213], v[50:65]
	v_lshl_add_u64 v[224:225], v[184:185], 0, s[18:19]
	global_load_dwordx4 v[146:149], v[224:225], off
	s_add_u32 s18, s18, 0x10000
	s_waitcnt lgkmcnt(0)
	v_mfma_f32_32x32x16_bf16 v[18:33], v[194:197], v[218:221], v[18:33]
	v_lshl_add_u64 v[226:227], v[184:185], 0, s[18:19]
	global_load_dwordx4 v[142:145], v[226:227], off
	v_mfma_f32_32x32x16_bf16 v[98:113], v[202:205], v[198:201], v[98:113]
	v_mfma_f32_32x32x16_bf16 v[66:81], v[202:205], v[206:209], v[66:81]
	v_mfma_f32_32x32x16_bf16 v[34:49], v[202:205], v[210:213], v[34:49]
	v_mfma_f32_32x32x16_bf16 v[2:17], v[202:205], v[218:221], v[2:17]
	v_xor_b32_e32 v1, 64, v187
	v_add_u32_e32 v193, v188, v1
	v_add_u32_e32 v1, v189, v1
	ds_read_b128 v[194:197], v193
	ds_read_b128 v[198:201], v1 offset:16384
	ds_read_b128 v[202:205], v193 offset:4096
	ds_read_b128 v[206:209], v1 offset:20480
	ds_read_b128 v[210:213], v1 offset:24576
	ds_read_b128 v[218:221], v1 offset:28672
	s_waitcnt lgkmcnt(4)
	v_mfma_f32_32x32x16_bf16 v[114:129], v[194:197], v[198:201], v[114:129]
	s_mov_b32 s11, 96
	v_xor_b32_e32 v1, s11, v187
	v_add_u32_e32 v193, v188, v1
	v_add_u32_e32 v1, v189, v1
	s_waitcnt lgkmcnt(2)
	v_mfma_f32_32x32x16_bf16 v[82:97], v[194:197], v[206:209], v[82:97]
	s_waitcnt lgkmcnt(1)
	v_mfma_f32_32x32x16_bf16 v[50:65], v[194:197], v[210:213], v[50:65]
	s_waitcnt lgkmcnt(0)
	v_mfma_f32_32x32x16_bf16 v[18:33], v[194:197], v[218:221], v[18:33]
	v_mfma_f32_32x32x16_bf16 v[98:113], v[202:205], v[198:201], v[98:113]
	v_mfma_f32_32x32x16_bf16 v[66:81], v[202:205], v[206:209], v[66:81]
	v_mfma_f32_32x32x16_bf16 v[34:49], v[202:205], v[210:213], v[34:49]
	v_mfma_f32_32x32x16_bf16 v[2:17], v[202:205], v[218:221], v[2:17]
	ds_read_b128 v[194:197], v193
	ds_read_b128 v[198:201], v1 offset:16384
	ds_read_b128 v[202:205], v193 offset:4096
	ds_read_b128 v[206:209], v1 offset:20480
	ds_read_b128 v[210:213], v1 offset:24576
	ds_read_b128 v[218:221], v1 offset:28672
	s_waitcnt lgkmcnt(4)
	v_mfma_f32_32x32x16_bf16 v[114:129], v[194:197], v[198:201], v[114:129]
	s_waitcnt lgkmcnt(2)
	v_mfma_f32_32x32x16_bf16 v[82:97], v[194:197], v[206:209], v[82:97]
	s_waitcnt lgkmcnt(1)
	v_mfma_f32_32x32x16_bf16 v[50:65], v[194:197], v[210:213], v[50:65]
	s_waitcnt lgkmcnt(0)
	v_mfma_f32_32x32x16_bf16 v[18:33], v[194:197], v[218:221], v[18:33]
	v_mfma_f32_32x32x16_bf16 v[98:113], v[202:205], v[198:201], v[98:113]
	v_mfma_f32_32x32x16_bf16 v[66:81], v[202:205], v[206:209], v[66:81]
	v_mfma_f32_32x32x16_bf16 v[34:49], v[202:205], v[210:213], v[34:49]
	v_mfma_f32_32x32x16_bf16 v[2:17], v[202:205], v[218:221], v[2:17]
	s_branch .Lkint_done_1255

; DI int cu(int r) { return (r & 3) + 8 * (r >> 2); }
;     ...
;             __builtin_amdgcn_s_setprio(0);
;             __syncthreads();
;     template <int NI> DI void operator()(const f32x16 (&acc)[2][NI], int row0, int col0, int lane) const {
;         const bool lat = row0 < NLAT;
;         const float* src = (lat ? srcL + (size_t)row0 * DM : srcC + (size_t)(row0 - NLAT) * DM) + col0;
;         float* dst = (lat ? dstL + (size_t)row0 * DM : dstC + (size_t)(row0 - NLAT) * DM) + col0;
;         const float* g = mod + ((lat ? (row0 >> 13) : 8) * 6 + gate_idx) * 1024 + col0;
;         const unsigned l31 = lane & 31, lo = (unsigned)(4 * (lane >> 5) * DM) + l31;
; #pragma unroll
;         for (int ni = 0; ni < NI; ++ni) {
;             const float gv = (g + 32 * ni)[l31];
;             float sv[32];
; #pragma unroll
;             for (int q = 0; q < 32; ++q) sv[q] = __builtin_nontemporal_load(&(src + (32 * (q >> 4) + cu(q & 15)) * DM + 32 * ni)[lo]);
; #pragma unroll
;             for (int q = 0; q < 32; ++q) (dst + (32 * (q >> 4) + cu(q & 15)) * DM + 32 * ni)[lo] = sv[q] + gv * acc[q >> 4][ni][q & 15];
;             asm volatile("" ::: "memory");
;         }
.Lkint_done_1255:
	s_setprio 0
	s_cmp_eq_u32 s9, 16
	s_barrier
	s_cbranch_scc0 .LBB0_1252
	s_waitcnt vmcnt(8)
	v_add_u32_e32 v136, s8, v190
	v_add_u32_e32 v131, 0xffff0000, v136
	v_ashrrev_i32_e32 v132, 31, v136
	v_cmp_gt_i32_e32 vcc, s30, v136
	v_mov_b32_e32 v134, s49
	v_or_b32_e32 v130, s10, v191
	v_cndmask_b32_e32 v133, 0, v132, vcc
	v_cndmask_b32_e32 v132, v131, v136, vcc
	v_mov_b32_e32 v131, s27
	v_cndmask_b32_e32 v135, v131, v134, vcc
	v_mov_b32_e32 v131, s26
	v_mov_b32_e32 v134, s48
	v_cndmask_b32_e32 v134, v131, v134, vcc
	v_lshlrev_b64 v[132:133], 12, v[132:133]
	v_lshl_add_u64 v[132:133], v[134:135], 0, v[132:133]
	v_min_i32_e32 v134, 0x10000, v136
	v_ashrrev_i32_e32 v134, 13, v134
	v_mul_i32_i24_e32 v134, 0x1800, v134
	v_ashrrev_i32_e32 v131, 31, v130
	v_ashrrev_i32_e32 v135, 31, v134
	v_mov_b32_e32 v1, v186
	v_lshlrev_b64 v[130:131], 2, v[130:131]
	v_lshl_add_u64 v[134:135], v[134:135], 2, s[28:29]
	v_lshl_add_u64 v[132:133], v[132:133], 0, v[130:131]
	v_lshl_add_u64 v[130:131], v[134:135], 0, v[130:131]
	v_and_b32_e32 v135, 31, v1
	v_lshlrev_b32_e32 v1, 7, v1
	v_lshlrev_b32_e32 v136, 2, v135
	v_mov_b32_e32 v137, v0
	v_and_or_b32 v134, v1, s31, v135
	v_lshl_add_u64 v[136:137], v[130:131], 0, v[136:137]
	v_mov_b32_e32 v135, v0
	v_lshl_add_u64 v[130:131], v[134:135], 2, v[132:133]
	v_add_co_u32_e32 v132, vcc, s34, v136
	s_waitcnt vmcnt(0)
	v_lshl_add_u64 v[144:145], v[136:137], 0, s[6:7]
	v_addc_co_u32_e32 v133, vcc, 0, v137, vcc
	global_load_dword v1, v[132:133], off
	global_load_dword v184, v[130:131], off nt
	v_add_co_u32_e32 v132, vcc, s35, v130
	s_add_i32 s66, s66, s81
	s_nop 0
	v_addc_co_u32_e32 v133, vcc, 0, v131, vcc
	v_add_co_u32_e32 v134, vcc, s34, v130
	s_cmpk_gt_i32 s66, 0xff
	s_nop 0
	v_addc_co_u32_e32 v135, vcc, 0, v131, vcc
	v_add_co_u32_e32 v136, vcc, s36, v130
	s_waitcnt vmcnt(0)
	v_fmac_f32_e32 v184, v114, v1
	v_addc_co_u32_e32 v137, vcc, 0, v131, vcc
	v_add_co_u32_e32 v138, vcc, s38, v130
	s_nop 1
	v_addc_co_u32_e32 v139, vcc, 0, v131, vcc
	v_add_co_u32_e32 v140, vcc, s40, v130
	s_nop 1
	v_addc_co_u32_e32 v141, vcc, 0, v131, vcc
	v_add_co_u32_e32 v142, vcc, s41, v130
	s_nop 1
	v_addc_co_u32_e32 v143, vcc, 0, v131, vcc
	v_add_co_u32_e32 v154, vcc, s37, v130
	global_load_dword v185, v[134:135], off offset:-4096 nt
	global_load_dword v193, v[134:135], off nt
	global_load_dword v194, v[138:139], off offset:-4096 nt
	global_load_dword v195, v[138:139], off nt
	global_load_dword v196, v[140:141], off offset:-4096 nt
	global_load_dword v197, v[140:141], off nt
	global_load_dword v198, v[142:143], off offset:-4096 nt
	global_load_dword v199, v[136:137], off nt
	v_addc_co_u32_e32 v155, vcc, 0, v131, vcc
	v_add_co_u32_e32 v146, vcc, s43, v130
	s_waitcnt vmcnt(7)
	v_fmac_f32_e32 v185, v115, v1
	v_addc_co_u32_e32 v147, vcc, 0, v131, vcc
	v_add_co_u32_e32 v148, vcc, s45, v130
	s_waitcnt vmcnt(6)
	v_fmac_f32_e32 v193, v116, v1
	v_addc_co_u32_e32 v149, vcc, 0, v131, vcc
	v_add_co_u32_e32 v150, vcc, s47, v130
	s_waitcnt vmcnt(0)
	v_fmac_f32_e32 v199, v117, v1
	v_addc_co_u32_e32 v151, vcc, 0, v131, vcc
	v_add_co_u32_e32 v152, vcc, s52, v130
	v_fmac_f32_e32 v194, v118, v1
	s_nop 0
	v_addc_co_u32_e32 v153, vcc, 0, v131, vcc
	global_load_dword v200, v[142:143], off nt
	global_load_dword v201, v[146:147], off offset:-4096 nt
	global_load_dword v202, v[146:147], off nt
	global_load_dword v203, v[148:149], off offset:-4096 nt
	global_load_dword v204, v[148:149], off nt
	global_load_dword v205, v[150:151], off offset:-4096 nt
	global_load_dword v206, v[150:151], off nt
	global_load_dword v207, v[152:153], off offset:-4096 nt
	v_add_co_u32_e32 v156, vcc, s54, v130
	v_fmac_f32_e32 v195, v119, v1
	s_nop 0
	v_addc_co_u32_e32 v157, vcc, 0, v131, vcc
	v_add_co_u32_e32 v158, vcc, s56, v130
	v_fmac_f32_e32 v196, v120, v1
	s_nop 0
	v_addc_co_u32_e32 v159, vcc, 0, v131, vcc
	v_add_co_u32_e32 v160, vcc, s58, v130
	v_fmac_f32_e32 v197, v121, v1
	s_nop 0
	v_addc_co_u32_e32 v161, vcc, 0, v131, vcc
	v_add_co_u32_e32 v162, vcc, s59, v130
	v_fmac_f32_e32 v198, v122, v1
	s_nop 0
	v_addc_co_u32_e32 v163, vcc, 0, v131, vcc
	global_load_dword v208, v[152:153], off nt
	global_load_dword v209, v[156:157], off offset:-4096 nt
	global_load_dword v210, v[156:157], off nt
	global_load_dword v211, v[158:159], off offset:-4096 nt
	global_load_dword v212, v[158:159], off nt
	global_load_dword v213, v[160:161], off offset:-4096 nt
	global_load_dword v214, v[160:161], off nt
	global_load_dword v215, v[162:163], off offset:-4096 nt
	v_add_co_u32_e32 v164, vcc, s61, v130
	s_waitcnt vmcnt(15)
	v_fmac_f32_e32 v200, v123, v1
	v_addc_co_u32_e32 v165, vcc, 0, v131, vcc
	v_add_co_u32_e32 v166, vcc, s63, v130
	global_load_dword v218, v[162:163], off nt
	global_load_dword v219, v[164:165], off offset:-4096 nt
	global_load_dword v220, v[164:165], off nt
	v_addc_co_u32_e32 v167, vcc, 0, v131, vcc
	v_add_co_u32_e32 v168, vcc, s65, v130
	s_waitcnt vmcnt(11)
	v_fmac_f32_e32 v207, v98, v1
	v_addc_co_u32_e32 v169, vcc, 0, v131, vcc
	global_load_dword v221, v[166:167], off offset:-4096 nt
	global_load_dword v222, v[166:167], off nt
	global_load_dword v223, v[168:169], off offset:-4096 nt
	global_load_dword v224, v[168:169], off nt
	v_add_co_u32_e32 v182, vcc, s39, v130
	v_fmac_f32_e32 v201, v124, v1
	s_nop 0
	v_addc_co_u32_e32 v183, vcc, 0, v131, vcc
	v_add_co_u32_e32 v176, vcc, s30, v130
	s_waitcnt vmcnt(14)
	v_fmac_f32_e32 v208, v99, v1
	v_addc_co_u32_e32 v177, vcc, 0, v131, vcc
	v_add_co_u32_e32 v174, vcc, s42, v130
	s_waitcnt vmcnt(13)
	v_fmac_f32_e32 v209, v100, v1
	v_addc_co_u32_e32 v175, vcc, 0, v131, vcc
	v_add_co_u32_e32 v172, vcc, s44, v130
	s_waitcnt vmcnt(12)
; DI int cu(int r) { return (r & 3) + 8 * (r >> 2); }
;     template <int NI> DI void operator()(const f32x16 (&acc)[2][NI], int row0, int col0, int lane) const {
;     ...
;         for (int ni = 0; ni < NI; ++ni) {
;             const float gv = (g + 32 * ni)[l31];
;             float sv[32];
; #pragma unroll
;             for (int q = 0; q < 32; ++q) sv[q] = __builtin_nontemporal_load(&(src + (32 * (q >> 4) + cu(q & 15)) * DM + 32 * ni)[lo]);
; #pragma unroll
;             for (int q = 0; q < 32; ++q) (dst + (32 * (q >> 4) + cu(q & 15)) * DM + 32 * ni)[lo] = sv[q] + gv * acc[q >> 4][ni][q & 15];
;             asm volatile("" ::: "memory");
;         }
	v_fmac_f32_e32 v210, v101, v1
	v_addc_co_u32_e32 v173, vcc, 0, v131, vcc
	v_add_co_u32_e32 v170, vcc, s46, v130
	s_waitcnt vmcnt(11)
	v_fmac_f32_e32 v211, v102, v1
	v_addc_co_u32_e32 v171, vcc, 0, v131, vcc
	v_add_co_u32_e32 v98, vcc, s17, v130
	s_waitcnt vmcnt(10)
	v_fmac_f32_e32 v212, v103, v1
	v_addc_co_u32_e32 v99, vcc, 0, v131, vcc
	v_add_co_u32_e32 v100, vcc, s53, v130
	s_waitcnt vmcnt(9)
	v_fmac_f32_e32 v213, v104, v1
	v_addc_co_u32_e32 v101, vcc, 0, v131, vcc
	v_add_co_u32_e32 v102, vcc, s55, v130
	s_waitcnt vmcnt(8)
	v_fmac_f32_e32 v214, v105, v1
	v_addc_co_u32_e32 v103, vcc, 0, v131, vcc
	v_add_co_u32_e32 v104, vcc, s57, v130
	s_waitcnt vmcnt(7)
	v_fmac_f32_e32 v215, v106, v1
	v_addc_co_u32_e32 v105, vcc, 0, v131, vcc
	v_add_co_u32_e32 v106, vcc, s16, v130
	v_fmac_f32_e32 v202, v125, v1
	v_fmac_f32_e32 v203, v126, v1
	v_fmac_f32_e32 v204, v127, v1
	v_fmac_f32_e32 v205, v128, v1
	v_fmac_f32_e32 v206, v129, v1
	global_store_dword v[130:131], v184, off
	global_store_dword v[134:135], v185, off offset:-4096
	global_store_dword v[134:135], v193, off
	global_store_dword v[136:137], v199, off
	global_store_dword v[138:139], v194, off offset:-4096
	global_store_dword v[138:139], v195, off
	global_store_dword v[140:141], v196, off offset:-4096
	global_store_dword v[140:141], v197, off
	global_store_dword v[142:143], v198, off offset:-4096
	global_store_dword v[142:143], v200, off
	global_store_dword v[146:147], v201, off offset:-4096
	global_store_dword v[146:147], v202, off
	global_store_dword v[148:149], v203, off offset:-4096
	global_store_dword v[148:149], v204, off
	global_store_dword v[150:151], v205, off offset:-4096
	global_store_dword v[150:151], v206, off
	global_store_dword v[152:153], v207, off offset:-4096
	s_waitcnt vmcnt(23)
	v_fmac_f32_e32 v218, v107, v1
	v_addc_co_u32_e32 v107, vcc, 0, v131, vcc
	s_waitcnt vmcnt(22)
	v_fmac_f32_e32 v219, v108, v1
	v_add_co_u32_e32 v108, vcc, s60, v130
	s_waitcnt vmcnt(21)
	v_fmac_f32_e32 v220, v109, v1
	v_addc_co_u32_e32 v109, vcc, 0, v131, vcc
	s_waitcnt vmcnt(20)
	v_fmac_f32_e32 v221, v110, v1
	v_add_co_u32_e32 v110, vcc, s62, v130
	s_waitcnt vmcnt(19)
	v_fmac_f32_e32 v222, v111, v1
	s_waitcnt vmcnt(18)
	v_fmac_f32_e32 v223, v112, v1
	s_waitcnt vmcnt(17)
	v_fmac_f32_e32 v224, v113, v1
	v_addc_co_u32_e32 v111, vcc, 0, v131, vcc
	global_store_dword v[152:153], v208, off
	global_store_dword v[156:157], v209, off offset:-4096
	global_store_dword v[156:157], v210, off
	global_store_dword v[158:159], v211, off offset:-4096
	global_store_dword v[158:159], v212, off
	global_store_dword v[160:161], v213, off offset:-4096
	global_store_dword v[160:161], v214, off
	global_store_dword v[162:163], v215, off offset:-4096
	global_store_dword v[162:163], v218, off
	global_store_dword v[164:165], v219, off offset:-4096
	global_store_dword v[164:165], v220, off
	global_store_dword v[166:167], v221, off offset:-4096
	global_store_dword v[166:167], v222, off
	global_store_dword v[168:169], v223, off offset:-4096
	global_store_dword v[168:169], v224, off
	v_add_co_u32_e32 v112, vcc, s64, v130
	global_load_dword v1, v[144:145], off offset:128
	global_load_dword v114, v[130:131], off offset:128 nt
	global_load_dword v115, v[132:133], off offset:128 nt
	v_addc_co_u32_e32 v113, vcc, 0, v131, vcc
	global_load_dword v116, v[134:135], off offset:128 nt
	global_load_dword v117, v[136:137], off offset:128 nt
	global_load_dword v118, v[154:155], off offset:128 nt
	global_load_dword v119, v[138:139], off offset:128 nt
	global_load_dword v120, v[182:183], off offset:128 nt
	global_load_dword v121, v[176:177], off offset:128 nt
	global_load_dword v122, v[140:141], off offset:128 nt
	global_load_dword v123, v[142:143], off offset:128 nt
	global_load_dword v124, v[174:175], off offset:128 nt
	global_load_dword v125, v[172:173], off offset:128 nt
	global_load_dword v126, v[146:147], off offset:128 nt
	global_load_dword v127, v[148:149], off offset:128 nt
	global_load_dword v128, v[170:171], off offset:128 nt
	global_load_dword v129, v[150:151], off offset:128 nt
	global_load_dword v184, v[98:99], off offset:128 nt
	global_load_dword v185, v[152:153], off offset:128 nt
	global_load_dword v193, v[100:101], off offset:128 nt
	global_load_dword v194, v[102:103], off offset:128 nt
	global_load_dword v195, v[156:157], off offset:128 nt
	global_load_dword v196, v[158:159], off offset:128 nt
	global_load_dword v197, v[104:105], off offset:128 nt
	global_load_dword v198, v[106:107], off offset:128 nt
	global_load_dword v199, v[160:161], off offset:128 nt
	global_load_dword v200, v[162:163], off offset:128 nt
	global_load_dword v201, v[108:109], off offset:128 nt
	global_load_dword v202, v[110:111], off offset:128 nt
	global_load_dword v203, v[164:165], off offset:128 nt
	global_load_dword v204, v[166:167], off offset:128 nt
	global_load_dword v205, v[112:113], off offset:128 nt
	global_load_dword v206, v[168:169], off offset:128 nt
	s_waitcnt vmcnt(31)
	v_fmac_f32_e32 v114, v82, v1
	s_waitcnt vmcnt(30)
	v_fmac_f32_e32 v115, v83, v1
	s_waitcnt vmcnt(29)
	v_fmac_f32_e32 v116, v84, v1
	s_waitcnt vmcnt(28)
	v_fmac_f32_e32 v117, v85, v1
	s_waitcnt vmcnt(27)
	v_fmac_f32_e32 v118, v86, v1
	s_waitcnt vmcnt(26)
	v_fmac_f32_e32 v119, v87, v1
	s_waitcnt vmcnt(25)
	v_fmac_f32_e32 v120, v88, v1
	s_waitcnt vmcnt(23)
	v_fmac_f32_e32 v122, v89, v1
	v_fmac_f32_e32 v121, v90, v1
	s_waitcnt vmcnt(22)
	v_fmac_f32_e32 v123, v91, v1
	s_waitcnt vmcnt(21)
	v_fmac_f32_e32 v124, v92, v1
	s_waitcnt vmcnt(19)
	v_fmac_f32_e32 v126, v93, v1
	v_fmac_f32_e32 v125, v94, v1
	s_waitcnt vmcnt(18)
	v_fmac_f32_e32 v127, v95, v1
	s_waitcnt vmcnt(17)
; DI int cu(int r) { return (r & 3) + 8 * (r >> 2); }
;     template <int NI> DI void operator()(const f32x16 (&acc)[2][NI], int row0, int col0, int lane) const {
;     ...
;         for (int ni = 0; ni < NI; ++ni) {
;             const float gv = (g + 32 * ni)[l31];
;             float sv[32];
; #pragma unroll
;             for (int q = 0; q < 32; ++q) sv[q] = __builtin_nontemporal_load(&(src + (32 * (q >> 4) + cu(q & 15)) * DM + 32 * ni)[lo]);
; #pragma unroll
;             for (int q = 0; q < 32; ++q) (dst + (32 * (q >> 4) + cu(q & 15)) * DM + 32 * ni)[lo] = sv[q] + gv * acc[q >> 4][ni][q & 15];
;             asm volatile("" ::: "memory");
;         }
	v_fmac_f32_e32 v128, v96, v1
	s_waitcnt vmcnt(16)
	v_fmac_f32_e32 v129, v97, v1
	s_waitcnt vmcnt(15)
	v_fmac_f32_e32 v184, v66, v1
	s_waitcnt vmcnt(14)
	v_fmac_f32_e32 v185, v67, v1
	s_waitcnt vmcnt(13)
	v_fmac_f32_e32 v193, v68, v1
	s_waitcnt vmcnt(11)
	v_fmac_f32_e32 v195, v69, v1
	v_fmac_f32_e32 v194, v70, v1
	s_waitcnt vmcnt(10)
	v_fmac_f32_e32 v196, v71, v1
	s_waitcnt vmcnt(9)
	v_fmac_f32_e32 v197, v72, v1
	s_waitcnt vmcnt(7)
	v_fmac_f32_e32 v199, v73, v1
	v_fmac_f32_e32 v198, v74, v1
	s_waitcnt vmcnt(6)
	v_fmac_f32_e32 v200, v75, v1
	s_waitcnt vmcnt(5)
	v_fmac_f32_e32 v201, v76, v1
	s_waitcnt vmcnt(3)
	v_fmac_f32_e32 v203, v77, v1
	v_fmac_f32_e32 v202, v78, v1
	s_waitcnt vmcnt(2)
	v_fmac_f32_e32 v204, v79, v1
	s_waitcnt vmcnt(1)
	v_fmac_f32_e32 v205, v80, v1
	s_waitcnt vmcnt(0)
	v_fmac_f32_e32 v206, v81, v1
	global_store_dword v[130:131], v114, off offset:128
	global_store_dword v[132:133], v115, off offset:128
	global_store_dword v[134:135], v116, off offset:128
	global_store_dword v[136:137], v117, off offset:128
	global_store_dword v[154:155], v118, off offset:128
	global_store_dword v[138:139], v119, off offset:128
	global_store_dword v[182:183], v120, off offset:128
	global_store_dword v[140:141], v122, off offset:128
	global_store_dword v[176:177], v121, off offset:128
	global_store_dword v[142:143], v123, off offset:128
	global_store_dword v[174:175], v124, off offset:128
	global_store_dword v[146:147], v126, off offset:128
	global_store_dword v[172:173], v125, off offset:128
	global_store_dword v[148:149], v127, off offset:128
	global_store_dword v[170:171], v128, off offset:128
	global_store_dword v[150:151], v129, off offset:128
	global_store_dword v[98:99], v184, off offset:128
	global_store_dword v[152:153], v185, off offset:128
	global_store_dword v[100:101], v193, off offset:128
	global_store_dword v[156:157], v195, off offset:128
	global_store_dword v[102:103], v194, off offset:128
	global_store_dword v[158:159], v196, off offset:128
	global_store_dword v[104:105], v197, off offset:128
	global_store_dword v[160:161], v199, off offset:128
	global_store_dword v[106:107], v198, off offset:128
	global_store_dword v[162:163], v200, off offset:128
	global_store_dword v[108:109], v201, off offset:128
	global_store_dword v[164:165], v203, off offset:128
	global_store_dword v[110:111], v202, off offset:128
	global_store_dword v[166:167], v204, off offset:128
	global_store_dword v[112:113], v205, off offset:128
	global_store_dword v[168:169], v206, off offset:128
	global_load_dword v1, v[144:145], off offset:256
	global_load_dword v66, v[130:131], off offset:256 nt
	global_load_dword v67, v[132:133], off offset:256 nt
	global_load_dword v68, v[134:135], off offset:256 nt
	global_load_dword v69, v[136:137], off offset:256 nt
	global_load_dword v70, v[154:155], off offset:256 nt
	global_load_dword v71, v[138:139], off offset:256 nt
	global_load_dword v72, v[182:183], off offset:256 nt
	global_load_dword v73, v[140:141], off offset:256 nt
	global_load_dword v74, v[176:177], off offset:256 nt
	global_load_dword v75, v[142:143], off offset:256 nt
	global_load_dword v76, v[174:175], off offset:256 nt
	global_load_dword v77, v[146:147], off offset:256 nt
	global_load_dword v78, v[172:173], off offset:256 nt
	global_load_dword v79, v[148:149], off offset:256 nt
	global_load_dword v80, v[170:171], off offset:256 nt
	global_load_dword v81, v[150:151], off offset:256 nt
	global_load_dword v82, v[98:99], off offset:256 nt
	global_load_dword v83, v[152:153], off offset:256 nt
	global_load_dword v84, v[100:101], off offset:256 nt
	global_load_dword v85, v[156:157], off offset:256 nt
	global_load_dword v86, v[102:103], off offset:256 nt
	global_load_dword v87, v[158:159], off offset:256 nt
	global_load_dword v88, v[104:105], off offset:256 nt
	global_load_dword v89, v[160:161], off offset:256 nt
	global_load_dword v90, v[106:107], off offset:256 nt
	global_load_dword v91, v[162:163], off offset:256 nt
	global_load_dword v92, v[108:109], off offset:256 nt
	global_load_dword v93, v[164:165], off offset:256 nt
	global_load_dword v94, v[110:111], off offset:256 nt
	global_load_dword v95, v[166:167], off offset:256 nt
	global_load_dword v96, v[112:113], off offset:256 nt
	global_load_dword v97, v[168:169], off offset:256 nt
	s_waitcnt vmcnt(31)
	v_fmac_f32_e32 v66, v50, v1
	s_waitcnt vmcnt(30)
	v_fmac_f32_e32 v67, v51, v1
	s_waitcnt vmcnt(29)
	v_fmac_f32_e32 v68, v52, v1
	s_waitcnt vmcnt(28)
	v_fmac_f32_e32 v69, v53, v1
	s_waitcnt vmcnt(27)
	v_fmac_f32_e32 v70, v54, v1
	s_waitcnt vmcnt(26)
	v_fmac_f32_e32 v71, v55, v1
	s_waitcnt vmcnt(25)
	v_fmac_f32_e32 v72, v56, v1
	s_waitcnt vmcnt(24)
	v_fmac_f32_e32 v73, v57, v1
	s_waitcnt vmcnt(23)
	v_fmac_f32_e32 v74, v58, v1
	s_waitcnt vmcnt(22)
	v_fmac_f32_e32 v75, v59, v1
	s_waitcnt vmcnt(21)
	v_fmac_f32_e32 v76, v60, v1
	s_waitcnt vmcnt(20)
	v_fmac_f32_e32 v77, v61, v1
	s_waitcnt vmcnt(19)
	v_fmac_f32_e32 v78, v62, v1
	s_waitcnt vmcnt(18)
	v_fmac_f32_e32 v79, v63, v1
	s_waitcnt vmcnt(17)
	v_fmac_f32_e32 v80, v64, v1
	s_waitcnt vmcnt(16)
	v_fmac_f32_e32 v81, v65, v1
	s_waitcnt vmcnt(15)
	v_fmac_f32_e32 v82, v34, v1
	s_waitcnt vmcnt(14)
	v_fmac_f32_e32 v83, v35, v1
	s_waitcnt vmcnt(13)
	v_fmac_f32_e32 v84, v36, v1
	s_waitcnt vmcnt(12)
	v_fmac_f32_e32 v85, v37, v1
	s_waitcnt vmcnt(11)
	v_fmac_f32_e32 v86, v38, v1
	s_waitcnt vmcnt(10)
	v_fmac_f32_e32 v87, v39, v1
	s_waitcnt vmcnt(9)
	v_fmac_f32_e32 v88, v40, v1
	s_waitcnt vmcnt(8)
	v_fmac_f32_e32 v89, v41, v1
	s_waitcnt vmcnt(7)
	v_fmac_f32_e32 v90, v42, v1
	s_waitcnt vmcnt(6)
	v_fmac_f32_e32 v91, v43, v1
	s_waitcnt vmcnt(5)
	v_fmac_f32_e32 v92, v44, v1
	s_waitcnt vmcnt(4)
; DI int cu(int r) { return (r & 3) + 8 * (r >> 2); }
;     template <int NI> DI void operator()(const f32x16 (&acc)[2][NI], int row0, int col0, int lane) const {
;     ...
;         for (int ni = 0; ni < NI; ++ni) {
;             const float gv = (g + 32 * ni)[l31];
;             float sv[32];
; #pragma unroll
;             for (int q = 0; q < 32; ++q) sv[q] = __builtin_nontemporal_load(&(src + (32 * (q >> 4) + cu(q & 15)) * DM + 32 * ni)[lo]);
; #pragma unroll
;             for (int q = 0; q < 32; ++q) (dst + (32 * (q >> 4) + cu(q & 15)) * DM + 32 * ni)[lo] = sv[q] + gv * acc[q >> 4][ni][q & 15];
;             asm volatile("" ::: "memory");
;         }
	v_fmac_f32_e32 v93, v45, v1
	s_waitcnt vmcnt(3)
	v_fmac_f32_e32 v94, v46, v1
	s_waitcnt vmcnt(2)
	v_fmac_f32_e32 v95, v47, v1
	s_waitcnt vmcnt(1)
	v_fmac_f32_e32 v96, v48, v1
	s_waitcnt vmcnt(0)
	v_fmac_f32_e32 v97, v49, v1
	global_store_dword v[130:131], v66, off offset:256
	global_store_dword v[132:133], v67, off offset:256
	global_store_dword v[134:135], v68, off offset:256
	global_store_dword v[136:137], v69, off offset:256
	global_store_dword v[154:155], v70, off offset:256
	global_store_dword v[138:139], v71, off offset:256
	global_store_dword v[182:183], v72, off offset:256
	global_store_dword v[140:141], v73, off offset:256
	global_store_dword v[176:177], v74, off offset:256
	global_store_dword v[142:143], v75, off offset:256
	global_store_dword v[174:175], v76, off offset:256
	global_store_dword v[146:147], v77, off offset:256
	global_store_dword v[172:173], v78, off offset:256
	global_store_dword v[148:149], v79, off offset:256
	global_store_dword v[170:171], v80, off offset:256
	global_store_dword v[150:151], v81, off offset:256
	global_store_dword v[98:99], v82, off offset:256
	global_store_dword v[152:153], v83, off offset:256
	global_store_dword v[100:101], v84, off offset:256
	global_store_dword v[156:157], v85, off offset:256
	global_store_dword v[102:103], v86, off offset:256
	global_store_dword v[158:159], v87, off offset:256
	global_store_dword v[104:105], v88, off offset:256
	global_store_dword v[160:161], v89, off offset:256
	global_store_dword v[106:107], v90, off offset:256
	global_store_dword v[162:163], v91, off offset:256
	global_store_dword v[108:109], v92, off offset:256
	global_store_dword v[164:165], v93, off offset:256
	global_store_dword v[110:111], v94, off offset:256
	global_store_dword v[166:167], v95, off offset:256
	global_store_dword v[112:113], v96, off offset:256
	global_store_dword v[168:169], v97, off offset:256
	global_load_dword v1, v[144:145], off offset:384
	global_load_dword v34, v[130:131], off offset:384 nt
	global_load_dword v35, v[132:133], off offset:384 nt
	global_load_dword v36, v[134:135], off offset:384 nt
	global_load_dword v37, v[136:137], off offset:384 nt
	global_load_dword v38, v[154:155], off offset:384 nt
	global_load_dword v39, v[138:139], off offset:384 nt
	global_load_dword v40, v[182:183], off offset:384 nt
	global_load_dword v41, v[140:141], off offset:384 nt
	global_load_dword v42, v[176:177], off offset:384 nt
	global_load_dword v43, v[142:143], off offset:384 nt
	global_load_dword v44, v[174:175], off offset:384 nt
	global_load_dword v45, v[146:147], off offset:384 nt
	global_load_dword v46, v[172:173], off offset:384 nt
	global_load_dword v47, v[148:149], off offset:384 nt
	global_load_dword v48, v[170:171], off offset:384 nt
	global_load_dword v49, v[150:151], off offset:384 nt
	global_load_dword v50, v[98:99], off offset:384 nt
	global_load_dword v51, v[152:153], off offset:384 nt
	global_load_dword v52, v[100:101], off offset:384 nt
	global_load_dword v53, v[156:157], off offset:384 nt
	global_load_dword v54, v[102:103], off offset:384 nt
	global_load_dword v55, v[158:159], off offset:384 nt
	global_load_dword v56, v[104:105], off offset:384 nt
	global_load_dword v57, v[160:161], off offset:384 nt
	global_load_dword v58, v[106:107], off offset:384 nt
	global_load_dword v59, v[162:163], off offset:384 nt
	global_load_dword v60, v[108:109], off offset:384 nt
	global_load_dword v61, v[164:165], off offset:384 nt
	global_load_dword v62, v[110:111], off offset:384 nt
	global_load_dword v63, v[166:167], off offset:384 nt
	global_load_dword v64, v[112:113], off offset:384 nt
	global_load_dword v65, v[168:169], off offset:384 nt
	s_waitcnt vmcnt(31)
	v_fmac_f32_e32 v34, v18, v1
	s_waitcnt vmcnt(30)
	v_fmac_f32_e32 v35, v19, v1
	s_waitcnt vmcnt(29)
	v_fmac_f32_e32 v36, v20, v1
	s_waitcnt vmcnt(28)
	v_fmac_f32_e32 v37, v21, v1
	s_waitcnt vmcnt(27)
	v_fmac_f32_e32 v38, v22, v1
	s_waitcnt vmcnt(26)
	v_fmac_f32_e32 v39, v23, v1
	s_waitcnt vmcnt(25)
	v_fmac_f32_e32 v40, v24, v1
	s_waitcnt vmcnt(24)
	v_fmac_f32_e32 v41, v25, v1
	s_waitcnt vmcnt(23)
	v_fmac_f32_e32 v42, v26, v1
	s_waitcnt vmcnt(22)
	v_fmac_f32_e32 v43, v27, v1
	s_waitcnt vmcnt(21)
	v_fmac_f32_e32 v44, v28, v1
	s_waitcnt vmcnt(20)
	v_fmac_f32_e32 v45, v29, v1
	s_waitcnt vmcnt(19)
	v_fmac_f32_e32 v46, v30, v1
	s_waitcnt vmcnt(18)
	v_fmac_f32_e32 v47, v31, v1
	s_waitcnt vmcnt(17)
	v_fmac_f32_e32 v48, v32, v1
	s_waitcnt vmcnt(16)
	v_fmac_f32_e32 v49, v33, v1
	s_waitcnt vmcnt(15)
	v_fmac_f32_e32 v50, v2, v1
	s_waitcnt vmcnt(14)
	v_fmac_f32_e32 v51, v3, v1
	s_waitcnt vmcnt(13)
	v_fmac_f32_e32 v52, v4, v1
	s_waitcnt vmcnt(12)
	v_fmac_f32_e32 v53, v5, v1
	s_waitcnt vmcnt(11)
	v_fmac_f32_e32 v54, v6, v1
	s_waitcnt vmcnt(10)
	v_fmac_f32_e32 v55, v7, v1
	s_waitcnt vmcnt(9)
	v_fmac_f32_e32 v56, v8, v1
	s_waitcnt vmcnt(8)
	v_fmac_f32_e32 v57, v9, v1
	s_waitcnt vmcnt(7)
	v_fmac_f32_e32 v58, v10, v1
	s_waitcnt vmcnt(6)
	v_fmac_f32_e32 v59, v11, v1
	s_waitcnt vmcnt(5)
	v_fmac_f32_e32 v60, v12, v1
	s_waitcnt vmcnt(4)
	v_fmac_f32_e32 v61, v13, v1
	s_waitcnt vmcnt(3)
	v_fmac_f32_e32 v62, v14, v1
	s_waitcnt vmcnt(2)
	v_fmac_f32_e32 v63, v15, v1
	s_waitcnt vmcnt(1)
	v_fmac_f32_e32 v64, v16, v1
	s_waitcnt vmcnt(0)
	v_fmac_f32_e32 v65, v17, v1
	global_store_dword v[130:131], v34, off offset:384
	global_store_dword v[132:133], v35, off offset:384
	global_store_dword v[134:135], v36, off offset:384
	global_store_dword v[136:137], v37, off offset:384
	global_store_dword v[154:155], v38, off offset:384
	global_store_dword v[138:139], v39, off offset:384
	global_store_dword v[182:183], v40, off offset:384
	global_store_dword v[140:141], v41, off offset:384
	global_store_dword v[176:177], v42, off offset:384
	global_store_dword v[142:143], v43, off offset:384
	global_store_dword v[174:175], v44, off offset:384
	global_store_dword v[146:147], v45, off offset:384
	global_store_dword v[172:173], v46, off offset:384
	global_store_dword v[148:149], v47, off offset:384
	global_store_dword v[170:171], v48, off offset:384
	global_store_dword v[150:151], v49, off offset:384
	global_store_dword v[98:99], v50, off offset:384
	global_store_dword v[152:153], v51, off offset:384
	global_store_dword v[100:101], v52, off offset:384
	global_store_dword v[156:157], v53, off offset:384
	global_store_dword v[102:103], v54, off offset:384
	global_store_dword v[158:159], v55, off offset:384
	global_store_dword v[104:105], v56, off offset:384
	global_store_dword v[160:161], v57, off offset:384
	global_store_dword v[106:107], v58, off offset:384
	global_store_dword v[162:163], v59, off offset:384
	global_store_dword v[108:109], v60, off offset:384
	global_store_dword v[164:165], v61, off offset:384
	global_store_dword v[110:111], v62, off offset:384
	global_store_dword v[166:167], v63, off offset:384
	global_store_dword v[112:113], v64, off offset:384
	global_store_dword v[168:169], v65, off offset:384
	s_cbranch_scc0 .LBB0_1251

; DI unsigned swz(int row, int chunk) { return (unsigned)row * 128u + (unsigned)((chunk ^ ((row >> 1) & 7)) << 4); }
; #define MFMA32(a, b, c) __builtin_amdgcn_mfma_f32_32x32x16_bf16((a), (b), (c), 0, 0, 0)
;     ...
;             for (int i = 0; i < 4; ++i) *(u32x4*)(lds + swz(lr + 32 * i, lc)) = ra[i];
; #pragma unroll
;             for (int i = 0; i < 8; ++i) *(u32x4*)(lds + 16384 + swz(lr + 32 * i, lc)) = rb[i];
;             __syncthreads();
;             if (kt + 1 < nk) {
; #pragma unroll
;                 for (int i = 0; i < 4; ++i) ra[i] = *(const u32x4*)((Au + (size_t)(32 * i) * lda + (kt + 1) * 64) + voA);
; #pragma unroll
;                 for (int i = 0; i < 8; ++i) rb[i] = *(const u32x4*)((Bu + (size_t)(32 * i) * ldb + (kt + 1) * 64) + voB);
;             }
;             __builtin_amdgcn_s_setprio(1);
; #pragma unroll 2
;             for (int ks = 0; ks < 4; ++ks) {
;                 bf16x8 af[2], bfr[4];
;                 const unsigned xo = (c0 ^ (unsigned)(2 * ks)) << 4;
; #pragma unroll
;                 for (int i = 0; i < 2; ++i) af[i] = *(const bf16x8*)(lds + (roA + xo) + i * 4096);
; #pragma unroll
;                 for (int j = 0; j < 4; ++j) bfr[j] = *(const bf16x8*)(lds + (roB + xo) + j * 4096);
; #pragma unroll
;                 for (int i = 0; i < 2; ++i)
; #pragma unroll
;                     for (int j = 0; j < 4; ++j) acc[i][j] = MFMA32(af[i], bfr[j], acc[i][j]);
;             }
;             __builtin_amdgcn_s_setprio(0);
.LBB0_1338:
	s_mov_b32 s4, s7
	s_add_i32 s7, s7, 1
	s_cmp_lg_u32 s4, 15
	s_waitcnt vmcnt(9)
	ds_write_b128 v206, v[148:151]
	ds_write_b128 v206, v[144:147] offset:4096
	ds_write_b128 v206, v[152:155] offset:8192
	s_waitcnt vmcnt(7)
	ds_write_b128 v206, v[156:159] offset:12288
	ds_write_b128 v206, v[160:163] offset:16384
	s_waitcnt vmcnt(6)
	ds_write_b128 v206, v[164:167] offset:20480
	s_waitcnt vmcnt(5)
	ds_write_b128 v206, v[168:171] offset:24576
	s_waitcnt vmcnt(4)
	ds_write_b128 v206, v[172:175] offset:28672
	s_waitcnt vmcnt(3)
	ds_write_b128 v206, v[176:179] offset:32768
	s_waitcnt vmcnt(2)
	ds_write_b128 v206, v[180:183] offset:36864
	s_waitcnt vmcnt(1)
	ds_write_b128 v206, v[184:187] offset:40960
	s_waitcnt vmcnt(0)
	ds_write_b128 v206, v[188:191] offset:45056
	s_waitcnt lgkmcnt(0)
	s_barrier
	s_cbranch_scc0 .LBB0_1340
	s_lshl_b32 s18, s7, 7
	s_mov_b32 s19, 0
	s_setprio 1
	v_xor_b32_e32 v1, 0, v201
	v_add_u32_e32 v10, v202, v1
	v_add_u32_e32 v1, v203, v1
	ds_read_b128 v[2:5], v10
	ds_read_b128 v[6:9], v1 offset:16384
	ds_read_b128 v[10:13], v10 offset:4096
	ds_read_b128 v[208:211], v1 offset:20480
	ds_read_b128 v[212:215], v1 offset:24576
	ds_read_b128 v[218:221], v1 offset:28672
	s_waitcnt lgkmcnt(4)
	v_mfma_f32_32x32x16_bf16 v[128:143], v[2:5], v[6:9], v[128:143]
	v_lshl_add_u64 v[222:223], v[196:197], 0, s[18:19]
	global_load_dwordx4 v[148:151], v[222:223], off
	s_add_u32 s18, s18, 0x10000
	s_mov_b32 s9, 32
	v_xor_b32_e32 v1, s9, v201
	v_add_u32_e32 v14, v202, v1
	v_add_u32_e32 v1, v203, v1
	s_waitcnt lgkmcnt(2)
	v_mfma_f32_32x32x16_bf16 v[112:127], v[2:5], v[208:211], v[112:127]
	v_lshl_add_u64 v[224:225], v[196:197], 0, s[18:19]
	global_load_dwordx4 v[144:147], v[224:225], off
	s_add_u32 s18, s18, 0x10000
	s_waitcnt lgkmcnt(1)
	v_mfma_f32_32x32x16_bf16 v[48:63], v[2:5], v[212:215], v[48:63]
	v_lshl_add_u64 v[226:227], v[196:197], 0, s[18:19]
	global_load_dwordx4 v[152:155], v[226:227], off
	s_add_u32 s18, s18, 0x10000
	s_waitcnt lgkmcnt(0)
	v_mfma_f32_32x32x16_bf16 v[64:79], v[2:5], v[218:221], v[64:79]
	v_lshl_add_u64 v[222:223], v[196:197], 0, s[18:19]
	global_load_dwordx4 v[156:159], v[222:223], off
	s_sub_u32 s18, s18, 0x30000
	v_mfma_f32_32x32x16_bf16 v[80:95], v[10:13], v[6:9], v[80:95]
	v_lshl_add_u64 v[224:225], v[198:199], 0, s[18:19]
	global_load_dwordx4 v[160:163], v[224:225], off
	s_add_u32 s18, s18, 0x10000
	v_mfma_f32_32x32x16_bf16 v[96:111], v[10:13], v[208:211], v[96:111]
	v_lshl_add_u64 v[226:227], v[198:199], 0, s[18:19]
	global_load_dwordx4 v[164:167], v[226:227], off
	s_add_u32 s18, s18, 0x10000
	v_mfma_f32_32x32x16_bf16 v[16:31], v[10:13], v[212:215], v[16:31]
	v_lshl_add_u64 v[222:223], v[198:199], 0, s[18:19]
	global_load_dwordx4 v[168:171], v[222:223], off
	s_add_u32 s18, s18, 0x10000
	v_mfma_f32_32x32x16_bf16 v[32:47], v[10:13], v[218:221], v[32:47]
	v_lshl_add_u64 v[224:225], v[198:199], 0, s[18:19]
	global_load_dwordx4 v[172:175], v[224:225], off
	s_add_u32 s18, s18, 0x10000
	ds_read_b128 v[2:5], v14
	ds_read_b128 v[6:9], v1 offset:16384
	ds_read_b128 v[10:13], v14 offset:4096
	ds_read_b128 v[208:211], v1 offset:20480
	ds_read_b128 v[212:215], v1 offset:24576
	ds_read_b128 v[218:221], v1 offset:28672
	s_waitcnt lgkmcnt(4)
	v_mfma_f32_32x32x16_bf16 v[128:143], v[2:5], v[6:9], v[128:143]
	v_lshl_add_u64 v[226:227], v[198:199], 0, s[18:19]
	global_load_dwordx4 v[176:179], v[226:227], off
	s_add_u32 s18, s18, 0x10000
	s_waitcnt lgkmcnt(2)
	v_mfma_f32_32x32x16_bf16 v[112:127], v[2:5], v[208:211], v[112:127]
	v_lshl_add_u64 v[222:223], v[198:199], 0, s[18:19]
	global_load_dwordx4 v[180:183], v[222:223], off
	s_add_u32 s18, s18, 0x10000
	s_waitcnt lgkmcnt(1)
	v_mfma_f32_32x32x16_bf16 v[48:63], v[2:5], v[212:215], v[48:63]
	v_lshl_add_u64 v[224:225], v[198:199], 0, s[18:19]
	global_load_dwordx4 v[184:187], v[224:225], off
	s_add_u32 s18, s18, 0x10000
	s_waitcnt lgkmcnt(0)
	v_mfma_f32_32x32x16_bf16 v[64:79], v[2:5], v[218:221], v[64:79]
	v_lshl_add_u64 v[226:227], v[198:199], 0, s[18:19]
	global_load_dwordx4 v[188:191], v[226:227], off
	v_mfma_f32_32x32x16_bf16 v[80:95], v[10:13], v[6:9], v[80:95]
	v_mfma_f32_32x32x16_bf16 v[96:111], v[10:13], v[208:211], v[96:111]
	v_mfma_f32_32x32x16_bf16 v[16:31], v[10:13], v[212:215], v[16:31]
	v_mfma_f32_32x32x16_bf16 v[32:47], v[10:13], v[218:221], v[32:47]
	v_xor_b32_e32 v1, 64, v201
	v_add_u32_e32 v10, v202, v1
	v_add_u32_e32 v1, v203, v1
	ds_read_b128 v[2:5], v10
	ds_read_b128 v[6:9], v1 offset:16384
	ds_read_b128 v[10:13], v10 offset:4096
	ds_read_b128 v[208:211], v1 offset:20480
	ds_read_b128 v[212:215], v1 offset:24576
	ds_read_b128 v[218:221], v1 offset:28672
	s_waitcnt lgkmcnt(4)
	v_mfma_f32_32x32x16_bf16 v[128:143], v[2:5], v[6:9], v[128:143]
	s_mov_b32 s9, 96
	v_xor_b32_e32 v1, s9, v201
	v_add_u32_e32 v14, v202, v1
	v_add_u32_e32 v1, v203, v1
	s_waitcnt lgkmcnt(2)
	v_mfma_f32_32x32x16_bf16 v[112:127], v[2:5], v[208:211], v[112:127]
	s_waitcnt lgkmcnt(1)
	v_mfma_f32_32x32x16_bf16 v[48:63], v[2:5], v[212:215], v[48:63]
	s_waitcnt lgkmcnt(0)
	v_mfma_f32_32x32x16_bf16 v[64:79], v[2:5], v[218:221], v[64:79]
	v_mfma_f32_32x32x16_bf16 v[80:95], v[10:13], v[6:9], v[80:95]
	v_mfma_f32_32x32x16_bf16 v[96:111], v[10:13], v[208:211], v[96:111]
	v_mfma_f32_32x32x16_bf16 v[16:31], v[10:13], v[212:215], v[16:31]
	v_mfma_f32_32x32x16_bf16 v[32:47], v[10:13], v[218:221], v[32:47]
	ds_read_b128 v[2:5], v14
	ds_read_b128 v[6:9], v1 offset:16384
	ds_read_b128 v[10:13], v14 offset:4096
	ds_read_b128 v[208:211], v1 offset:20480
	ds_read_b128 v[212:215], v1 offset:24576
	ds_read_b128 v[218:221], v1 offset:28672
	s_waitcnt lgkmcnt(4)
	v_mfma_f32_32x32x16_bf16 v[128:143], v[2:5], v[6:9], v[128:143]
	s_waitcnt lgkmcnt(2)
	v_mfma_f32_32x32x16_bf16 v[112:127], v[2:5], v[208:211], v[112:127]
	s_waitcnt lgkmcnt(1)
	v_mfma_f32_32x32x16_bf16 v[48:63], v[2:5], v[212:215], v[48:63]
	s_waitcnt lgkmcnt(0)
	v_mfma_f32_32x32x16_bf16 v[64:79], v[2:5], v[218:221], v[64:79]
	v_mfma_f32_32x32x16_bf16 v[80:95], v[10:13], v[6:9], v[80:95]
	v_mfma_f32_32x32x16_bf16 v[96:111], v[10:13], v[208:211], v[96:111]
	v_mfma_f32_32x32x16_bf16 v[16:31], v[10:13], v[212:215], v[16:31]
	v_mfma_f32_32x32x16_bf16 v[32:47], v[10:13], v[218:221], v[32:47]
	s_branch .Lkint_done_1341

; DI float sigmoidf_(float x) { return __builtin_amdgcn_rcpf(1.0f + __builtin_amdgcn_exp2f(-1.4426950408889634f * x)); }
; DI int cu(int r) { return (r & 3) + 8 * (r >> 2); }
;     ...
;             __builtin_amdgcn_s_setprio(0);
;             __syncthreads();
;     template <int NI> DI void operator()(const f32x16 (&acc)[2][NI], int row0, int col0, int lane) const {
;         const unsigned lo = (unsigned)(4 * (lane >> 5) * FFH + (lane & 31));
;         bf16_t* base = Hd + (size_t)row0 * FFH + (col0 >> 1);
; #pragma unroll
;         for (int pr = 0; pr < NI / 2; ++pr)
; #pragma unroll
;             for (int mi = 0; mi < 2; ++mi)
; #pragma unroll
;                 for (int r = 0; r < 16; ++r) { const float g = acc[mi][2 * pr][r], u = acc[mi][2 * pr + 1][r]; __builtin_nontemporal_store(f2bf(g * sigmoidf_(g) * u), &(base + (32 * mi + cu(r)) * FFH + 32 * pr)[lo]); }
;     }
.Lkint_done_1341:
	s_setprio 0
	s_cmp_eq_u32 s7, 16
	s_barrier
	s_cbranch_scc0 .LBB0_1338
	v_mov_b32_e32 v1, v200
	v_or_b32_e32 v6, s8, v205
	v_lshrrev_b32_e32 v2, 3, v1
	v_and_b32_e32 v2, 0xfffffc, v2
	v_mul_u32_u24_e32 v2, 0xb00, v2
	v_and_or_b32 v2, v1, 31, v2
	v_mul_f32_e32 v1, 0xbfb8aa3b, v128
	v_exp_f32_e32 v1, v1
	v_add_u32_e32 v3, s6, v204
	v_mov_b64_e32 v[4:5], s[82:83]
	v_ashrrev_i32_e32 v6, 1, v6
	v_mad_i64_i32 v[4:5], s[6:7], v3, s14, v[4:5]
	v_ashrrev_i32_e32 v7, 31, v6
	v_mul_f32_e32 v3, 0xbfb8aa3b, v129
	v_lshl_add_u64 v[4:5], v[6:7], 1, v[4:5]
	v_exp_f32_e32 v6, v3
	v_add_f32_e32 v1, 1.0, v1
	v_rcp_f32_e32 v1, v1
	v_mov_b32_e32 v3, v0
	v_lshl_add_u64 v[2:3], v[2:3], 1, v[4:5]
	v_add_f32_e32 v4, 1.0, v6
	v_rcp_f32_e32 v4, v4
	v_mul_f32_e32 v1, v128, v1
	v_mul_f32_e32 v1, v112, v1
	v_cvt_pk_bf16_f32 v1, v1, s0
	global_store_short v[2:3], v1, off nt
	v_mul_f32_e32 v1, v129, v4
	v_mul_f32_e32 v4, 0xbfb8aa3b, v130
	v_exp_f32_e32 v6, v4
	v_mul_f32_e32 v1, v113, v1
	v_add_co_u32_e32 v4, vcc, s15, v2
	v_add_f32_e32 v6, 1.0, v6
	v_rcp_f32_e32 v6, v6
	v_cvt_pk_bf16_f32 v1, v1, s0
	v_addc_co_u32_e32 v5, vcc, 0, v3, vcc
	v_mul_f32_e32 v6, v130, v6
	global_store_short v[4:5], v1, off offset:1536 nt
	v_mul_f32_e32 v1, 0xbfb8aa3b, v131
	v_mul_f32_e32 v6, v114, v6
	v_exp_f32_e32 v1, v1
	v_cvt_pk_bf16_f32 v8, v6, s0
	v_add_co_u32_e32 v6, vcc, s16, v2
	v_add_f32_e32 v1, 1.0, v1
	s_nop 0
	v_addc_co_u32_e32 v7, vcc, 0, v3, vcc
	global_store_short v[6:7], v8, off offset:3072 nt
	v_mul_f32_e32 v8, 0xbfb8aa3b, v132
	v_exp_f32_e32 v10, v8
	v_rcp_f32_e32 v1, v1
	v_add_co_u32_e32 v8, vcc, s17, v2
	v_add_f32_e32 v10, 1.0, v10
	v_rcp_f32_e32 v10, v10
	v_mul_f32_e32 v1, v131, v1
	v_mul_f32_e32 v1, v115, v1
	v_cvt_pk_bf16_f32 v1, v1, s0
	v_addc_co_u32_e32 v9, vcc, 0, v3, vcc
	global_store_short v[8:9], v1, off offset:512 nt
	v_mul_f32_e32 v1, 0xbfb8aa3b, v133
	v_mul_f32_e32 v10, v132, v10
	v_exp_f32_e32 v1, v1
	v_mul_f32_e32 v10, v116, v10
	v_cvt_pk_bf16_f32 v12, v10, s0
	v_add_co_u32_e32 v10, vcc, s24, v2
	v_add_f32_e32 v1, 1.0, v1
	s_nop 0
	v_addc_co_u32_e32 v11, vcc, 0, v3, vcc
	global_store_short v[10:11], v12, off nt
	v_mul_f32_e32 v12, 0xbfb8aa3b, v134
	v_exp_f32_e32 v14, v12
	v_rcp_f32_e32 v1, v1
	v_add_co_u32_e32 v12, vcc, s25, v2
	v_add_f32_e32 v14, 1.0, v14
	v_mul_f32_e32 v1, v133, v1
	v_rcp_f32_e32 v14, v14
	v_mul_f32_e32 v1, v117, v1
	v_cvt_pk_bf16_f32 v1, v1, s0
	v_addc_co_u32_e32 v13, vcc, 0, v3, vcc
	global_store_short v[12:13], v1, off offset:1536 nt
	v_mul_f32_e32 v1, 0xbfb8aa3b, v135
	v_exp_f32_e32 v1, v1
	v_mul_f32_e32 v14, v134, v14
	v_mul_f32_e32 v14, v118, v14
	v_cvt_pk_bf16_f32 v112, v14, s0
	v_add_co_u32_e32 v14, vcc, s30, v2
	v_add_f32_e32 v1, 1.0, v1
	s_nop 0
	v_addc_co_u32_e32 v15, vcc, 0, v3, vcc
	global_store_short v[14:15], v112, off offset:3072 nt
	v_mul_f32_e32 v112, 0xbfb8aa3b, v136
	v_rcp_f32_e32 v1, v1
	v_exp_f32_e32 v114, v112
	v_add_co_u32_e32 v112, vcc, s31, v2
	v_mul_f32_e32 v1, v135, v1
	v_add_f32_e32 v114, 1.0, v114
	v_mul_f32_e32 v1, v119, v1
	v_rcp_f32_e32 v114, v114
	v_cvt_pk_bf16_f32 v1, v1, s0
	v_addc_co_u32_e32 v113, vcc, 0, v3, vcc
	global_store_short v[112:113], v1, off offset:512 nt
	v_mul_f32_e32 v1, 0xbfb8aa3b, v137
	v_exp_f32_e32 v1, v1
	v_mul_f32_e32 v114, v136, v114
	v_mul_f32_e32 v114, v120, v114
	v_cvt_pk_bf16_f32 v116, v114, s0
	v_add_co_u32_e32 v114, vcc, s34, v2
	v_add_f32_e32 v1, 1.0, v1
	s_nop 0
	v_addc_co_u32_e32 v115, vcc, 0, v3, vcc
	v_rcp_f32_e32 v1, v1
	global_store_short v[114:115], v116, off nt
	v_mul_f32_e32 v116, 0xbfb8aa3b, v138
	v_exp_f32_e32 v118, v116
	v_mul_f32_e32 v1, v137, v1
	v_mul_f32_e32 v1, v121, v1
	v_add_co_u32_e32 v116, vcc, s35, v2
	v_add_f32_e32 v118, 1.0, v118
	v_cvt_pk_bf16_f32 v1, v1, s0
	v_addc_co_u32_e32 v117, vcc, 0, v3, vcc
	v_rcp_f32_e32 v118, v118
	global_store_short v[116:117], v1, off offset:1536 nt
	v_mul_f32_e32 v1, 0xbfb8aa3b, v139
	v_exp_f32_e32 v1, v1
	v_mul_f32_e32 v118, v138, v118
	v_mul_f32_e32 v118, v122, v118
	v_cvt_pk_bf16_f32 v120, v118, s0
	v_add_f32_e32 v1, 1.0, v1
	v_add_co_u32_e32 v118, vcc, s36, v2
	v_rcp_f32_e32 v1, v1
	s_nop 0
	v_addc_co_u32_e32 v119, vcc, 0, v3, vcc
	global_store_short v[118:119], v120, off offset:3072 nt
	v_mul_f32_e32 v120, 0xbfb8aa3b, v140
	v_exp_f32_e32 v122, v120
	v_mul_f32_e32 v1, v139, v1
	v_mul_f32_e32 v1, v123, v1
	v_add_co_u32_e32 v120, vcc, s37, v2
	v_cvt_pk_bf16_f32 v1, v1, s0
	s_nop 0
	v_addc_co_u32_e32 v121, vcc, 0, v3, vcc
	v_add_f32_e32 v122, 1.0, v122
	v_rcp_f32_e32 v122, v122
	global_store_short v[120:121], v1, off offset:512 nt
	v_mul_f32_e32 v1, 0xbfb8aa3b, v141
	v_exp_f32_e32 v1, v1
	v_mul_f32_e32 v122, v140, v122
	v_mul_f32_e32 v122, v124, v122
	v_cvt_pk_bf16_f32 v124, v122, s0
	v_add_f32_e32 v1, 1.0, v1
	v_rcp_f32_e32 v1, v1
	v_add_co_u32_e32 v122, vcc, s38, v2
	s_add_i32 s61, s61, s81
	s_nop 0
	v_addc_co_u32_e32 v123, vcc, 0, v3, vcc
	global_store_short v[122:123], v124, off nt
	v_mul_f32_e32 v124, 0xbfb8aa3b, v142
	v_exp_f32_e32 v128, v124
	v_mul_f32_e32 v1, v141, v1
	v_mul_f32_e32 v1, v125, v1
	v_add_co_u32_e32 v124, vcc, s39, v2
	v_cvt_pk_bf16_f32 v1, v1, s0
	s_nop 0
	v_addc_co_u32_e32 v125, vcc, 0, v3, vcc
	v_add_f32_e32 v128, 1.0, v128
	global_store_short v[124:125], v1, off offset:1536 nt
	v_mul_f32_e32 v1, 0xbfb8aa3b, v143
	v_rcp_f32_e32 v128, v128
	v_exp_f32_e32 v1, v1
	s_cmpk_gt_i32 s61, 0x57f
	v_mul_f32_e32 v128, v142, v128
	v_add_f32_e32 v1, 1.0, v1
	v_mul_f32_e32 v126, v126, v128
	v_rcp_f32_e32 v1, v1
	v_add_co_u32_e32 v128, vcc, s40, v2
	v_cvt_pk_bf16_f32 v126, v126, s0
	s_nop 0
	v_addc_co_u32_e32 v129, vcc, 0, v3, vcc
	global_store_short v[128:129], v126, off offset:3072 nt
; DI float sigmoidf_(float x) { return __builtin_amdgcn_rcpf(1.0f + __builtin_amdgcn_exp2f(-1.4426950408889634f * x)); }
; DI int cu(int r) { return (r & 3) + 8 * (r >> 2); }
;     template <int NI> DI void operator()(const f32x16 (&acc)[2][NI], int row0, int col0, int lane) const {
;     ...
;         for (int pr = 0; pr < NI / 2; ++pr)
; #pragma unroll
;             for (int mi = 0; mi < 2; ++mi)
; #pragma unroll
;                 for (int r = 0; r < 16; ++r) { const float g = acc[mi][2 * pr][r], u = acc[mi][2 * pr + 1][r]; __builtin_nontemporal_store(f2bf(g * sigmoidf_(g) * u), &(base + (32 * mi + cu(r)) * FFH + 32 * pr)[lo]); }
	v_mul_f32_e32 v126, 0xbfb8aa3b, v80
	v_exp_f32_e32 v130, v126
	v_mul_f32_e32 v1, v143, v1
	v_mul_f32_e32 v1, v127, v1
	v_add_co_u32_e32 v126, vcc, s41, v2
	v_cvt_pk_bf16_f32 v1, v1, s0
	s_nop 0
	v_addc_co_u32_e32 v127, vcc, 0, v3, vcc
	v_add_f32_e32 v130, 1.0, v130
	global_store_short v[126:127], v1, off offset:512 nt
	v_mul_f32_e32 v1, 0xbfb8aa3b, v81
	v_rcp_f32_e32 v130, v130
	v_exp_f32_e32 v1, v1
	v_mul_f32_e32 v80, v80, v130
	v_add_f32_e32 v1, 1.0, v1
	v_mul_f32_e32 v80, v96, v80
	v_rcp_f32_e32 v1, v1
	v_add_co_u32_e32 v130, vcc, s42, v2
	v_cvt_pk_bf16_f32 v80, v80, s0
	s_nop 0
	v_addc_co_u32_e32 v131, vcc, 0, v3, vcc
	global_store_short v[130:131], v80, off nt
	v_mul_f32_e32 v80, 0xbfb8aa3b, v82
	v_exp_f32_e32 v96, v80
	v_mul_f32_e32 v1, v81, v1
	v_mul_f32_e32 v1, v97, v1
	v_add_co_u32_e32 v80, vcc, s43, v2
	v_cvt_pk_bf16_f32 v1, v1, s0
	s_nop 0
	v_addc_co_u32_e32 v81, vcc, 0, v3, vcc
	v_add_f32_e32 v96, 1.0, v96
	global_store_short v[80:81], v1, off offset:1536 nt
	v_mul_f32_e32 v1, 0xbfb8aa3b, v83
	v_rcp_f32_e32 v96, v96
	v_exp_f32_e32 v1, v1
	v_mul_f32_e32 v82, v82, v96
	v_add_f32_e32 v1, 1.0, v1
	v_mul_f32_e32 v82, v98, v82
	v_rcp_f32_e32 v1, v1
	v_add_co_u32_e32 v96, vcc, s44, v2
	v_cvt_pk_bf16_f32 v82, v82, s0
	s_nop 0
	v_addc_co_u32_e32 v97, vcc, 0, v3, vcc
	global_store_short v[96:97], v82, off offset:3072 nt
	v_mul_f32_e32 v82, 0xbfb8aa3b, v84
	v_exp_f32_e32 v98, v82
	v_mul_f32_e32 v1, v83, v1
	v_mul_f32_e32 v1, v99, v1
	v_add_co_u32_e32 v82, vcc, s12, v2
	v_cvt_pk_bf16_f32 v1, v1, s0
	s_nop 0
	v_addc_co_u32_e32 v83, vcc, 0, v3, vcc
	v_add_f32_e32 v98, 1.0, v98
	global_store_short v[82:83], v1, off offset:512 nt
	v_mul_f32_e32 v1, 0xbfb8aa3b, v85
	v_rcp_f32_e32 v98, v98
	v_exp_f32_e32 v1, v1
	v_mul_f32_e32 v84, v84, v98
	v_add_f32_e32 v1, 1.0, v1
	v_mul_f32_e32 v84, v100, v84
	v_rcp_f32_e32 v1, v1
	v_add_co_u32_e32 v98, vcc, s45, v2
	v_cvt_pk_bf16_f32 v84, v84, s0
	s_nop 0
	v_addc_co_u32_e32 v99, vcc, 0, v3, vcc
	global_store_short v[98:99], v84, off nt
	v_mul_f32_e32 v84, 0xbfb8aa3b, v86
	v_exp_f32_e32 v100, v84
	v_mul_f32_e32 v1, v85, v1
	v_mul_f32_e32 v1, v101, v1
	v_add_co_u32_e32 v84, vcc, s46, v2
	v_cvt_pk_bf16_f32 v1, v1, s0
	s_nop 0
	v_addc_co_u32_e32 v85, vcc, 0, v3, vcc
	v_add_f32_e32 v100, 1.0, v100
	global_store_short v[84:85], v1, off offset:1536 nt
	v_mul_f32_e32 v1, 0xbfb8aa3b, v87
	v_rcp_f32_e32 v100, v100
	v_exp_f32_e32 v1, v1
	v_mul_f32_e32 v86, v86, v100
	v_add_f32_e32 v1, 1.0, v1
	v_mul_f32_e32 v86, v102, v86
	v_rcp_f32_e32 v1, v1
	v_add_co_u32_e32 v100, vcc, s47, v2
	v_cvt_pk_bf16_f32 v86, v86, s0
	s_nop 0
	v_addc_co_u32_e32 v101, vcc, 0, v3, vcc
	global_store_short v[100:101], v86, off offset:3072 nt
	v_mul_f32_e32 v86, 0xbfb8aa3b, v88
	v_exp_f32_e32 v102, v86
	v_mul_f32_e32 v1, v87, v1
	v_mul_f32_e32 v1, v103, v1
	v_add_co_u32_e32 v86, vcc, s52, v2
	v_cvt_pk_bf16_f32 v1, v1, s0
	s_nop 0
	v_addc_co_u32_e32 v87, vcc, 0, v3, vcc
	v_add_f32_e32 v102, 1.0, v102
	global_store_short v[86:87], v1, off offset:512 nt
	v_mul_f32_e32 v1, 0xbfb8aa3b, v89
	v_rcp_f32_e32 v102, v102
	v_exp_f32_e32 v1, v1
	v_mul_f32_e32 v88, v88, v102
	v_add_f32_e32 v1, 1.0, v1
	v_mul_f32_e32 v88, v104, v88
	v_rcp_f32_e32 v1, v1
	v_add_co_u32_e32 v102, vcc, s53, v2
	v_cvt_pk_bf16_f32 v88, v88, s0
	s_nop 0
	v_addc_co_u32_e32 v103, vcc, 0, v3, vcc
	global_store_short v[102:103], v88, off nt
	v_mul_f32_e32 v88, 0xbfb8aa3b, v90
	v_exp_f32_e32 v104, v88
	v_mul_f32_e32 v1, v89, v1
	v_mul_f32_e32 v1, v105, v1
	v_add_co_u32_e32 v88, vcc, s54, v2
	v_cvt_pk_bf16_f32 v1, v1, s0
	s_nop 0
	v_addc_co_u32_e32 v89, vcc, 0, v3, vcc
	v_add_f32_e32 v104, 1.0, v104
	global_store_short v[88:89], v1, off offset:1536 nt
	v_mul_f32_e32 v1, 0xbfb8aa3b, v91
	v_rcp_f32_e32 v104, v104
	v_exp_f32_e32 v1, v1
	v_mul_f32_e32 v90, v90, v104
	v_add_f32_e32 v1, 1.0, v1
	v_mul_f32_e32 v90, v106, v90
	v_rcp_f32_e32 v1, v1
	v_add_co_u32_e32 v104, vcc, s55, v2
	v_cvt_pk_bf16_f32 v90, v90, s0
	s_nop 0
	v_addc_co_u32_e32 v105, vcc, 0, v3, vcc
	global_store_short v[104:105], v90, off offset:3072 nt
	v_mul_f32_e32 v90, 0xbfb8aa3b, v92
	v_exp_f32_e32 v106, v90
	v_mul_f32_e32 v1, v91, v1
	v_mul_f32_e32 v1, v107, v1
	v_add_co_u32_e32 v90, vcc, s56, v2
	v_cvt_pk_bf16_f32 v1, v1, s0
	s_nop 0
	v_addc_co_u32_e32 v91, vcc, 0, v3, vcc
	v_add_f32_e32 v106, 1.0, v106
	global_store_short v[90:91], v1, off offset:512 nt
	v_mul_f32_e32 v1, 0xbfb8aa3b, v93
	v_rcp_f32_e32 v106, v106
	v_exp_f32_e32 v1, v1
	v_mul_f32_e32 v92, v92, v106
	v_add_f32_e32 v1, 1.0, v1
	v_mul_f32_e32 v92, v108, v92
	v_rcp_f32_e32 v1, v1
	v_add_co_u32_e32 v106, vcc, s57, v2
	v_cvt_pk_bf16_f32 v92, v92, s0
	s_nop 0
	v_addc_co_u32_e32 v107, vcc, 0, v3, vcc
	global_store_short v[106:107], v92, off nt
	v_mul_f32_e32 v92, 0xbfb8aa3b, v94
	v_exp_f32_e32 v108, v92
	v_mul_f32_e32 v1, v93, v1
	v_mul_f32_e32 v1, v109, v1
	v_add_co_u32_e32 v92, vcc, s58, v2
	v_cvt_pk_bf16_f32 v1, v1, s0
	s_nop 0
	v_addc_co_u32_e32 v93, vcc, 0, v3, vcc
	v_add_f32_e32 v108, 1.0, v108
	global_store_short v[92:93], v1, off offset:1536 nt
	v_mul_f32_e32 v1, 0xbfb8aa3b, v95
	v_rcp_f32_e32 v108, v108
	v_exp_f32_e32 v1, v1
	v_mul_f32_e32 v94, v94, v108
	v_add_f32_e32 v1, 1.0, v1
	v_mul_f32_e32 v94, v110, v94
	v_rcp_f32_e32 v1, v1
	v_add_co_u32_e32 v108, vcc, s59, v2
	v_cvt_pk_bf16_f32 v94, v94, s0
	s_nop 0
	v_addc_co_u32_e32 v109, vcc, 0, v3, vcc
	global_store_short v[108:109], v94, off offset:3072 nt
	v_mul_f32_e32 v94, 0xbfb8aa3b, v48
	v_exp_f32_e32 v110, v94
	v_mul_f32_e32 v1, v95, v1
	v_mul_f32_e32 v1, v111, v1
	v_add_co_u32_e32 v94, vcc, s60, v2
	v_cvt_pk_bf16_f32 v1, v1, s0
	s_nop 0
	v_addc_co_u32_e32 v95, vcc, 0, v3, vcc
	v_add_f32_e32 v110, 1.0, v110
; DI float sigmoidf_(float x) { return __builtin_amdgcn_rcpf(1.0f + __builtin_amdgcn_exp2f(-1.4426950408889634f * x)); }
; DI int cu(int r) { return (r & 3) + 8 * (r >> 2); }
;     template <int NI> DI void operator()(const f32x16 (&acc)[2][NI], int row0, int col0, int lane) const {
;     ...
;         for (int pr = 0; pr < NI / 2; ++pr)
; #pragma unroll
;             for (int mi = 0; mi < 2; ++mi)
; #pragma unroll
;                 for (int r = 0; r < 16; ++r) { const float g = acc[mi][2 * pr][r], u = acc[mi][2 * pr + 1][r]; __builtin_nontemporal_store(f2bf(g * sigmoidf_(g) * u), &(base + (32 * mi + cu(r)) * FFH + 32 * pr)[lo]); }
	global_store_short v[94:95], v1, off offset:512 nt
	v_mul_f32_e32 v1, 0xbfb8aa3b, v49
	v_rcp_f32_e32 v110, v110
	v_exp_f32_e32 v1, v1
	v_mul_f32_e32 v48, v48, v110
	v_add_f32_e32 v1, 1.0, v1
	v_mul_f32_e32 v48, v64, v48
	v_rcp_f32_e32 v1, v1
	v_cvt_pk_bf16_f32 v48, v48, s0
	global_store_short v[2:3], v48, off offset:64 nt
	v_mul_f32_e32 v2, 0xbfb8aa3b, v50
	v_exp_f32_e32 v2, v2
	v_mul_f32_e32 v1, v49, v1
	v_mul_f32_e32 v1, v65, v1
	v_cvt_pk_bf16_f32 v1, v1, s0
	v_add_f32_e32 v2, 1.0, v2
	global_store_short v[4:5], v1, off offset:1600 nt
	v_mul_f32_e32 v1, 0xbfb8aa3b, v51
	v_rcp_f32_e32 v2, v2
	v_exp_f32_e32 v1, v1
	v_mul_f32_e32 v3, 0xbfb8aa3b, v30
	v_exp_f32_e32 v3, v3
	v_mul_f32_e32 v2, v50, v2
	v_add_f32_e32 v1, 1.0, v1
	v_mul_f32_e32 v2, v66, v2
	v_rcp_f32_e32 v1, v1
	v_cvt_pk_bf16_f32 v2, v2, s0
	global_store_short v[6:7], v2, off offset:3136 nt
	v_mul_f32_e32 v2, 0xbfb8aa3b, v52
	v_exp_f32_e32 v2, v2
	v_mul_f32_e32 v1, v51, v1
	v_mul_f32_e32 v1, v67, v1
	v_cvt_pk_bf16_f32 v1, v1, s0
	v_add_f32_e32 v2, 1.0, v2
	global_store_short v[8:9], v1, off offset:576 nt
	v_mul_f32_e32 v1, 0xbfb8aa3b, v53
	v_rcp_f32_e32 v2, v2
	v_exp_f32_e32 v1, v1
	v_mul_f32_e32 v2, v52, v2
	v_add_f32_e32 v1, 1.0, v1
	v_mul_f32_e32 v2, v68, v2
	v_rcp_f32_e32 v1, v1
	v_cvt_pk_bf16_f32 v2, v2, s0
	global_store_short v[10:11], v2, off offset:64 nt
	v_mul_f32_e32 v2, 0xbfb8aa3b, v54
	v_exp_f32_e32 v2, v2
	v_mul_f32_e32 v1, v53, v1
	v_mul_f32_e32 v1, v69, v1
	v_cvt_pk_bf16_f32 v1, v1, s0
	v_add_f32_e32 v2, 1.0, v2
	global_store_short v[12:13], v1, off offset:1600 nt
	v_mul_f32_e32 v1, 0xbfb8aa3b, v55
	v_rcp_f32_e32 v2, v2
	v_exp_f32_e32 v1, v1
	v_mul_f32_e32 v2, v54, v2
	v_add_f32_e32 v1, 1.0, v1
	v_mul_f32_e32 v2, v70, v2
	v_rcp_f32_e32 v1, v1
	v_cvt_pk_bf16_f32 v2, v2, s0
	global_store_short v[14:15], v2, off offset:3136 nt
	v_mul_f32_e32 v2, 0xbfb8aa3b, v56
	v_exp_f32_e32 v2, v2
	v_mul_f32_e32 v1, v55, v1
	v_mul_f32_e32 v1, v71, v1
	v_cvt_pk_bf16_f32 v1, v1, s0
	v_add_f32_e32 v2, 1.0, v2
	global_store_short v[112:113], v1, off offset:576 nt
	v_mul_f32_e32 v1, 0xbfb8aa3b, v57
	v_rcp_f32_e32 v2, v2
	v_exp_f32_e32 v1, v1
	v_mul_f32_e32 v2, v56, v2
	v_add_f32_e32 v1, 1.0, v1
	v_mul_f32_e32 v2, v72, v2
	v_rcp_f32_e32 v1, v1
	v_cvt_pk_bf16_f32 v2, v2, s0
	global_store_short v[114:115], v2, off offset:64 nt
	v_mul_f32_e32 v2, 0xbfb8aa3b, v58
	v_exp_f32_e32 v2, v2
	v_mul_f32_e32 v1, v57, v1
	v_mul_f32_e32 v1, v73, v1
	v_cvt_pk_bf16_f32 v1, v1, s0
	v_add_f32_e32 v2, 1.0, v2
	global_store_short v[116:117], v1, off offset:1600 nt
	v_mul_f32_e32 v1, 0xbfb8aa3b, v59
	v_rcp_f32_e32 v2, v2
	v_exp_f32_e32 v1, v1
	v_mul_f32_e32 v2, v58, v2
	v_add_f32_e32 v1, 1.0, v1
	v_mul_f32_e32 v2, v74, v2
	v_rcp_f32_e32 v1, v1
	v_cvt_pk_bf16_f32 v2, v2, s0
	global_store_short v[118:119], v2, off offset:3136 nt
	v_mul_f32_e32 v2, 0xbfb8aa3b, v60
	v_exp_f32_e32 v2, v2
	v_mul_f32_e32 v1, v59, v1
	v_mul_f32_e32 v1, v75, v1
	v_cvt_pk_bf16_f32 v1, v1, s0
	v_add_f32_e32 v2, 1.0, v2
	global_store_short v[120:121], v1, off offset:576 nt
	v_mul_f32_e32 v1, 0xbfb8aa3b, v61
	v_rcp_f32_e32 v2, v2
	v_exp_f32_e32 v1, v1
	v_mul_f32_e32 v2, v60, v2
	v_add_f32_e32 v1, 1.0, v1
	v_mul_f32_e32 v2, v76, v2
	v_rcp_f32_e32 v1, v1
	v_cvt_pk_bf16_f32 v2, v2, s0
	global_store_short v[122:123], v2, off offset:64 nt
	v_mul_f32_e32 v2, 0xbfb8aa3b, v62
	v_exp_f32_e32 v2, v2
	v_mul_f32_e32 v1, v61, v1
	v_mul_f32_e32 v1, v77, v1
	v_cvt_pk_bf16_f32 v1, v1, s0
	v_add_f32_e32 v2, 1.0, v2
	global_store_short v[124:125], v1, off offset:1600 nt
	v_mul_f32_e32 v1, 0xbfb8aa3b, v63
	v_rcp_f32_e32 v2, v2
	v_exp_f32_e32 v1, v1
	v_mul_f32_e32 v2, v62, v2
	v_add_f32_e32 v1, 1.0, v1
	v_mul_f32_e32 v2, v78, v2
	v_rcp_f32_e32 v1, v1
	v_cvt_pk_bf16_f32 v2, v2, s0
	global_store_short v[128:129], v2, off offset:3136 nt
	v_mul_f32_e32 v2, 0xbfb8aa3b, v16
	v_exp_f32_e32 v2, v2
	v_mul_f32_e32 v1, v63, v1
	v_mul_f32_e32 v1, v79, v1
; DI float sigmoidf_(float x) { return __builtin_amdgcn_rcpf(1.0f + __builtin_amdgcn_exp2f(-1.4426950408889634f * x)); }
; DI int cu(int r) { return (r & 3) + 8 * (r >> 2); }
;     template <int NI> DI void operator()(const f32x16 (&acc)[2][NI], int row0, int col0, int lane) const {
;     ...
;         for (int pr = 0; pr < NI / 2; ++pr)
; #pragma unroll
;             for (int mi = 0; mi < 2; ++mi)
; #pragma unroll
;                 for (int r = 0; r < 16; ++r) { const float g = acc[mi][2 * pr][r], u = acc[mi][2 * pr + 1][r]; __builtin_nontemporal_store(f2bf(g * sigmoidf_(g) * u), &(base + (32 * mi + cu(r)) * FFH + 32 * pr)[lo]); }
	v_cvt_pk_bf16_f32 v1, v1, s0
	v_add_f32_e32 v2, 1.0, v2
	global_store_short v[126:127], v1, off offset:576 nt
	v_mul_f32_e32 v1, 0xbfb8aa3b, v17
	v_rcp_f32_e32 v2, v2
	v_exp_f32_e32 v1, v1
	v_mul_f32_e32 v2, v16, v2
	v_add_f32_e32 v1, 1.0, v1
	v_mul_f32_e32 v2, v32, v2
	v_rcp_f32_e32 v1, v1
	v_cvt_pk_bf16_f32 v2, v2, s0
	global_store_short v[130:131], v2, off offset:64 nt
	v_mul_f32_e32 v2, 0xbfb8aa3b, v18
	v_exp_f32_e32 v2, v2
	v_mul_f32_e32 v1, v17, v1
	v_mul_f32_e32 v1, v33, v1
	v_cvt_pk_bf16_f32 v1, v1, s0
	v_add_f32_e32 v2, 1.0, v2
	global_store_short v[80:81], v1, off offset:1600 nt
	v_mul_f32_e32 v1, 0xbfb8aa3b, v19
	v_rcp_f32_e32 v2, v2
	v_exp_f32_e32 v1, v1
	v_mul_f32_e32 v2, v18, v2
	v_add_f32_e32 v1, 1.0, v1
	v_mul_f32_e32 v2, v34, v2
	v_rcp_f32_e32 v1, v1
	v_cvt_pk_bf16_f32 v2, v2, s0
	global_store_short v[96:97], v2, off offset:3136 nt
	v_mul_f32_e32 v2, 0xbfb8aa3b, v20
	v_exp_f32_e32 v2, v2
	v_mul_f32_e32 v1, v19, v1
	v_mul_f32_e32 v1, v35, v1
	v_cvt_pk_bf16_f32 v1, v1, s0
	v_add_f32_e32 v2, 1.0, v2
	global_store_short v[82:83], v1, off offset:576 nt
	v_mul_f32_e32 v1, 0xbfb8aa3b, v21
	v_rcp_f32_e32 v2, v2
	v_exp_f32_e32 v1, v1
	v_mul_f32_e32 v2, v20, v2
	v_add_f32_e32 v1, 1.0, v1
	v_mul_f32_e32 v2, v36, v2
	v_rcp_f32_e32 v1, v1
	v_cvt_pk_bf16_f32 v2, v2, s0
	global_store_short v[98:99], v2, off offset:64 nt
	v_mul_f32_e32 v2, 0xbfb8aa3b, v22
	v_exp_f32_e32 v2, v2
	v_mul_f32_e32 v1, v21, v1
	v_mul_f32_e32 v1, v37, v1
	v_cvt_pk_bf16_f32 v1, v1, s0
	v_add_f32_e32 v2, 1.0, v2
	global_store_short v[84:85], v1, off offset:1600 nt
	v_mul_f32_e32 v1, 0xbfb8aa3b, v23
	v_rcp_f32_e32 v2, v2
	v_exp_f32_e32 v1, v1
	v_mul_f32_e32 v2, v22, v2
	v_add_f32_e32 v1, 1.0, v1
	v_mul_f32_e32 v2, v38, v2
	v_rcp_f32_e32 v1, v1
	v_cvt_pk_bf16_f32 v2, v2, s0
	global_store_short v[100:101], v2, off offset:3136 nt
	v_mul_f32_e32 v2, 0xbfb8aa3b, v24
	v_exp_f32_e32 v2, v2
	v_mul_f32_e32 v1, v23, v1
	v_mul_f32_e32 v1, v39, v1
	v_cvt_pk_bf16_f32 v1, v1, s0
	v_add_f32_e32 v2, 1.0, v2
	global_store_short v[86:87], v1, off offset:576 nt
	v_mul_f32_e32 v1, 0xbfb8aa3b, v25
	v_rcp_f32_e32 v2, v2
	v_exp_f32_e32 v1, v1
	v_mul_f32_e32 v2, v24, v2
	v_add_f32_e32 v1, 1.0, v1
	v_mul_f32_e32 v2, v40, v2
	v_rcp_f32_e32 v1, v1
	v_cvt_pk_bf16_f32 v2, v2, s0
	global_store_short v[102:103], v2, off offset:64 nt
	v_mul_f32_e32 v2, 0xbfb8aa3b, v26
	v_exp_f32_e32 v2, v2
	v_mul_f32_e32 v1, v25, v1
	v_mul_f32_e32 v1, v41, v1
	v_cvt_pk_bf16_f32 v1, v1, s0
	v_add_f32_e32 v2, 1.0, v2
	global_store_short v[88:89], v1, off offset:1600 nt
	v_mul_f32_e32 v1, 0xbfb8aa3b, v27
	v_rcp_f32_e32 v2, v2
	v_exp_f32_e32 v1, v1
	v_mul_f32_e32 v2, v26, v2
	v_add_f32_e32 v1, 1.0, v1
	v_mul_f32_e32 v2, v42, v2
	v_rcp_f32_e32 v1, v1
	v_cvt_pk_bf16_f32 v2, v2, s0
	global_store_short v[104:105], v2, off offset:3136 nt
	v_mul_f32_e32 v2, 0xbfb8aa3b, v28
	v_exp_f32_e32 v2, v2
	v_mul_f32_e32 v1, v27, v1
	v_mul_f32_e32 v1, v43, v1
	v_cvt_pk_bf16_f32 v1, v1, s0
	v_add_f32_e32 v2, 1.0, v2
	global_store_short v[90:91], v1, off offset:576 nt
	v_mul_f32_e32 v1, 0xbfb8aa3b, v29
	v_rcp_f32_e32 v2, v2
	v_exp_f32_e32 v1, v1
	v_mul_f32_e32 v2, v28, v2
	v_add_f32_e32 v1, 1.0, v1
	v_mul_f32_e32 v2, v44, v2
	v_rcp_f32_e32 v1, v1
	v_cvt_pk_bf16_f32 v2, v2, s0
	global_store_short v[106:107], v2, off offset:64 nt
	v_add_f32_e32 v2, 1.0, v3
	v_mul_f32_e32 v3, 0xbfb8aa3b, v31
	v_rcp_f32_e32 v2, v2
	v_exp_f32_e32 v3, v3
	v_mul_f32_e32 v1, v29, v1
	v_mul_f32_e32 v1, v45, v1
	v_cvt_pk_bf16_f32 v1, v1, s0
	global_store_short v[92:93], v1, off offset:1600 nt
	v_mul_f32_e32 v1, v30, v2
	v_add_f32_e32 v2, 1.0, v3
	v_rcp_f32_e32 v2, v2
	v_mul_f32_e32 v1, v46, v1
	v_cvt_pk_bf16_f32 v1, v1, s0
	global_store_short v[108:109], v1, off offset:3136 nt
	v_mul_f32_e32 v1, v31, v2
	v_mul_f32_e32 v1, v47, v1
	v_cvt_pk_bf16_f32 v1, v1, s0
	global_store_short v[94:95], v1, off offset:576 nt
	s_cbranch_scc0 .LBB0_1337

; DI unsigned swz(int row, int chunk) { return (unsigned)row * 128u + (unsigned)((chunk ^ ((row >> 1) & 7)) << 4); }
; #define MFMA32(a, b, c) __builtin_amdgcn_mfma_f32_32x32x16_bf16((a), (b), (c), 0, 0, 0)
;     ...
;             for (int i = 0; i < 4; ++i) *(u32x4*)(lds + swz(lr + 32 * i, lc)) = ra[i];
; #pragma unroll
;             for (int i = 0; i < 8; ++i) *(u32x4*)(lds + 16384 + swz(lr + 32 * i, lc)) = rb[i];
;             __syncthreads();
;             if (kt + 1 < nk) {
; #pragma unroll
;                 for (int i = 0; i < 4; ++i) ra[i] = *(const u32x4*)((Au + (size_t)(32 * i) * lda + (kt + 1) * 64) + voA);
; #pragma unroll
;                 for (int i = 0; i < 8; ++i) rb[i] = *(const u32x4*)((Bu + (size_t)(32 * i) * ldb + (kt + 1) * 64) + voB);
;             }
;             __builtin_amdgcn_s_setprio(1);
; #pragma unroll 2
;             for (int ks = 0; ks < 4; ++ks) {
;                 bf16x8 af[2], bfr[4];
;                 const unsigned xo = (c0 ^ (unsigned)(2 * ks)) << 4;
; #pragma unroll
;                 for (int i = 0; i < 2; ++i) af[i] = *(const bf16x8*)(lds + (roA + xo) + i * 4096);
; #pragma unroll
;                 for (int j = 0; j < 4; ++j) bfr[j] = *(const bf16x8*)(lds + (roB + xo) + j * 4096);
; #pragma unroll
;                 for (int i = 0; i < 2; ++i)
; #pragma unroll
;                     for (int j = 0; j < 4; ++j) acc[i][j] = MFMA32(af[i], bfr[j], acc[i][j]);
;             }
;             __builtin_amdgcn_s_setprio(0);
.LBB0_1384:
	s_mov_b32 s0, s59
	s_add_i32 s59, s59, 1
	s_cmp_lt_u32 s0, 43
	s_waitcnt vmcnt(0)
	ds_write_b128 v193, v[130:133]
	ds_write_b128 v193, v[138:141] offset:4096
	ds_write_b128 v193, v[170:173] offset:8192
	ds_write_b128 v193, v[134:137] offset:12288
	ds_write_b128 v193, v[174:177] offset:16384
	ds_write_b128 v193, v[166:169] offset:20480
	ds_write_b128 v193, v[162:165] offset:24576
	ds_write_b128 v193, v[158:161] offset:28672
	ds_write_b128 v193, v[154:157] offset:32768
	ds_write_b128 v193, v[150:153] offset:36864
	ds_write_b128 v193, v[146:149] offset:40960
	ds_write_b128 v193, v[142:145] offset:45056
	s_waitcnt lgkmcnt(0)
	s_barrier
	s_cbranch_scc0 .LBB0_1386
	s_lshl_b32 s60, s59, 7
	s_mov_b32 s61, 0
	s_setprio 1
	v_xor_b32_e32 v1, 0, v187
	v_add_u32_e32 v202, v188, v1
	v_add_u32_e32 v1, v189, v1
	ds_read_b128 v[194:197], v202
	ds_read_b128 v[198:201], v1 offset:16384
	ds_read_b128 v[202:205], v202 offset:4096
	ds_read_b128 v[206:209], v1 offset:20480
	ds_read_b128 v[210:213], v1 offset:24576
	ds_read_b128 v[218:221], v1 offset:28672
	s_waitcnt lgkmcnt(4)
	v_mfma_f32_32x32x16_bf16 v[114:129], v[194:197], v[198:201], v[114:129]
	v_lshl_add_u64 v[222:223], v[182:183], 0, s[60:61]
	global_load_dwordx4 v[130:133], v[222:223], off
	s_add_u32 s60, s60, 0x2c000
	s_mov_b32 s18, 32
	v_xor_b32_e32 v1, s18, v187
	s_waitcnt lgkmcnt(2)
	v_mfma_f32_32x32x16_bf16 v[82:97], v[194:197], v[206:209], v[82:97]
	v_lshl_add_u64 v[224:225], v[182:183], 0, s[60:61]
	global_load_dwordx4 v[138:141], v[224:225], off
	s_add_u32 s60, s60, 0x2c000
	s_waitcnt lgkmcnt(1)
	v_mfma_f32_32x32x16_bf16 v[50:65], v[194:197], v[210:213], v[50:65]
	v_lshl_add_u64 v[226:227], v[182:183], 0, s[60:61]
	global_load_dwordx4 v[170:173], v[226:227], off
	s_add_u32 s60, s60, 0x2c000
	s_waitcnt lgkmcnt(0)
	v_mfma_f32_32x32x16_bf16 v[18:33], v[194:197], v[218:221], v[18:33]
	v_lshl_add_u64 v[222:223], v[182:183], 0, s[60:61]
	global_load_dwordx4 v[134:137], v[222:223], off
	s_sub_u32 s60, s60, 0x84000
	v_mfma_f32_32x32x16_bf16 v[98:113], v[202:205], v[198:201], v[98:113]
	v_lshl_add_u64 v[224:225], v[184:185], 0, s[60:61]
	global_load_dwordx4 v[174:177], v[224:225], off
	s_add_u32 s60, s60, 0x2c000
	v_mfma_f32_32x32x16_bf16 v[66:81], v[202:205], v[206:209], v[66:81]
	v_lshl_add_u64 v[226:227], v[184:185], 0, s[60:61]
	global_load_dwordx4 v[166:169], v[226:227], off
	s_add_u32 s60, s60, 0x2c000
	v_add_u32_e32 v206, v188, v1
	v_add_u32_e32 v1, v189, v1
	v_mfma_f32_32x32x16_bf16 v[34:49], v[202:205], v[210:213], v[34:49]
	v_lshl_add_u64 v[222:223], v[184:185], 0, s[60:61]
	global_load_dwordx4 v[162:165], v[222:223], off
	s_add_u32 s60, s60, 0x2c000
	v_mfma_f32_32x32x16_bf16 v[2:17], v[202:205], v[218:221], v[2:17]
	v_lshl_add_u64 v[224:225], v[184:185], 0, s[60:61]
	global_load_dwordx4 v[158:161], v[224:225], off
	s_add_u32 s60, s60, 0x2c000
	ds_read_b128 v[194:197], v206
	ds_read_b128 v[198:201], v1 offset:16384
	ds_read_b128 v[202:205], v206 offset:4096
	ds_read_b128 v[206:209], v1 offset:20480
	ds_read_b128 v[210:213], v1 offset:24576
	ds_read_b128 v[218:221], v1 offset:28672
	s_waitcnt lgkmcnt(4)
	v_mfma_f32_32x32x16_bf16 v[114:129], v[194:197], v[198:201], v[114:129]
	v_lshl_add_u64 v[226:227], v[184:185], 0, s[60:61]
	global_load_dwordx4 v[154:157], v[226:227], off
	s_add_u32 s60, s60, 0x2c000
	s_waitcnt lgkmcnt(2)
	v_mfma_f32_32x32x16_bf16 v[82:97], v[194:197], v[206:209], v[82:97]
	v_lshl_add_u64 v[222:223], v[184:185], 0, s[60:61]
	global_load_dwordx4 v[150:153], v[222:223], off
	s_add_u32 s60, s60, 0x2c000
	s_waitcnt lgkmcnt(1)
	v_mfma_f32_32x32x16_bf16 v[50:65], v[194:197], v[210:213], v[50:65]
	v_lshl_add_u64 v[224:225], v[184:185], 0, s[60:61]
	global_load_dwordx4 v[146:149], v[224:225], off
	s_add_u32 s60, s60, 0x2c000
	s_waitcnt lgkmcnt(0)
	v_mfma_f32_32x32x16_bf16 v[18:33], v[194:197], v[218:221], v[18:33]
	v_lshl_add_u64 v[226:227], v[184:185], 0, s[60:61]
	global_load_dwordx4 v[142:145], v[226:227], off
	v_mfma_f32_32x32x16_bf16 v[98:113], v[202:205], v[198:201], v[98:113]
	v_mfma_f32_32x32x16_bf16 v[66:81], v[202:205], v[206:209], v[66:81]
	v_mfma_f32_32x32x16_bf16 v[34:49], v[202:205], v[210:213], v[34:49]
	v_mfma_f32_32x32x16_bf16 v[2:17], v[202:205], v[218:221], v[2:17]
	v_xor_b32_e32 v1, 64, v187
	v_add_u32_e32 v202, v188, v1
	v_add_u32_e32 v1, v189, v1
	ds_read_b128 v[194:197], v202
	ds_read_b128 v[198:201], v1 offset:16384
	ds_read_b128 v[202:205], v202 offset:4096
	ds_read_b128 v[206:209], v1 offset:20480
	ds_read_b128 v[210:213], v1 offset:24576
	ds_read_b128 v[218:221], v1 offset:28672
	s_waitcnt lgkmcnt(4)
	v_mfma_f32_32x32x16_bf16 v[114:129], v[194:197], v[198:201], v[114:129]
	s_mov_b32 s18, 96
	v_xor_b32_e32 v1, s18, v187
	s_waitcnt lgkmcnt(2)
	v_mfma_f32_32x32x16_bf16 v[82:97], v[194:197], v[206:209], v[82:97]
	s_waitcnt lgkmcnt(1)
	v_mfma_f32_32x32x16_bf16 v[50:65], v[194:197], v[210:213], v[50:65]
	s_waitcnt lgkmcnt(0)
	v_mfma_f32_32x32x16_bf16 v[18:33], v[194:197], v[218:221], v[18:33]
	v_mfma_f32_32x32x16_bf16 v[98:113], v[202:205], v[198:201], v[98:113]
	v_mfma_f32_32x32x16_bf16 v[66:81], v[202:205], v[206:209], v[66:81]
	v_add_u32_e32 v206, v188, v1
	v_add_u32_e32 v1, v189, v1
	v_mfma_f32_32x32x16_bf16 v[34:49], v[202:205], v[210:213], v[34:49]
	v_mfma_f32_32x32x16_bf16 v[2:17], v[202:205], v[218:221], v[2:17]
	ds_read_b128 v[194:197], v206
	ds_read_b128 v[198:201], v1 offset:16384
	ds_read_b128 v[202:205], v206 offset:4096
	ds_read_b128 v[206:209], v1 offset:20480
	ds_read_b128 v[210:213], v1 offset:24576
	ds_read_b128 v[218:221], v1 offset:28672
	s_waitcnt lgkmcnt(4)
	v_mfma_f32_32x32x16_bf16 v[114:129], v[194:197], v[198:201], v[114:129]
	s_waitcnt lgkmcnt(2)
	v_mfma_f32_32x32x16_bf16 v[82:97], v[194:197], v[206:209], v[82:97]
	s_waitcnt lgkmcnt(1)
	v_mfma_f32_32x32x16_bf16 v[50:65], v[194:197], v[210:213], v[50:65]
	s_waitcnt lgkmcnt(0)
	v_mfma_f32_32x32x16_bf16 v[18:33], v[194:197], v[218:221], v[18:33]
	v_mfma_f32_32x32x16_bf16 v[98:113], v[202:205], v[198:201], v[98:113]
	v_mfma_f32_32x32x16_bf16 v[66:81], v[202:205], v[206:209], v[66:81]
	v_mfma_f32_32x32x16_bf16 v[34:49], v[202:205], v[210:213], v[34:49]
	v_mfma_f32_32x32x16_bf16 v[2:17], v[202:205], v[218:221], v[2:17]
	s_branch .Lkint_done_1387

; DI int cu(int r) { return (r & 3) + 8 * (r >> 2); }
;     ...
;             __builtin_amdgcn_s_setprio(0);
;             __syncthreads();
;     template <int NI> DI void operator()(const f32x16 (&acc)[2][NI], int row0, int col0, int lane) const {
;         const bool lat = row0 < NLAT;
;         const float* src = (lat ? srcL + (size_t)row0 * DM : srcC + (size_t)(row0 - NLAT) * DM) + col0;
;         float* dst = (lat ? dstL + (size_t)row0 * DM : dstC + (size_t)(row0 - NLAT) * DM) + col0;
;         const float* g = mod + ((lat ? (row0 >> 13) : 8) * 6 + gate_idx) * 1024 + col0;
;         const unsigned l31 = lane & 31, lo = (unsigned)(4 * (lane >> 5) * DM) + l31;
; #pragma unroll
;         for (int ni = 0; ni < NI; ++ni) {
;             const float gv = (g + 32 * ni)[l31];
;             float sv[32];
; #pragma unroll
;             for (int q = 0; q < 32; ++q) sv[q] = __builtin_nontemporal_load(&(src + (32 * (q >> 4) + cu(q & 15)) * DM + 32 * ni)[lo]);
; #pragma unroll
;             for (int q = 0; q < 32; ++q) (dst + (32 * (q >> 4) + cu(q & 15)) * DM + 32 * ni)[lo] = sv[q] + gv * acc[q >> 4][ni][q & 15];
;             asm volatile("" ::: "memory");
;         }
.Lkint_done_1387:
	s_setprio 0
	s_cmp_eq_u32 s59, 44
	s_barrier
	s_cbranch_scc0 .LBB0_1384
	s_waitcnt vmcnt(8)
	v_add_u32_e32 v136, s57, v190
	v_add_u32_e32 v131, 0xffff0000, v136
	v_ashrrev_i32_e32 v132, 31, v136
	v_cmp_gt_i32_e32 vcc, s10, v136
	v_mov_b32_e32 v134, s49
	v_or_b32_e32 v130, s58, v191
	v_cndmask_b32_e32 v133, 0, v132, vcc
	v_cndmask_b32_e32 v132, v131, v136, vcc
	v_mov_b32_e32 v131, s27
	v_cndmask_b32_e32 v135, v131, v134, vcc
	v_mov_b32_e32 v131, s26
	v_mov_b32_e32 v134, s48
	v_cndmask_b32_e32 v134, v131, v134, vcc
	v_lshlrev_b64 v[132:133], 12, v[132:133]
	v_lshl_add_u64 v[132:133], v[134:135], 0, v[132:133]
	v_min_i32_e32 v134, 0x10000, v136
	v_ashrrev_i32_e32 v134, 13, v134
	v_mul_i32_i24_e32 v134, 0x1800, v134
	v_ashrrev_i32_e32 v131, 31, v130
	v_ashrrev_i32_e32 v135, 31, v134
	v_mov_b32_e32 v1, v186
	v_lshlrev_b64 v[130:131], 2, v[130:131]
	v_lshl_add_u64 v[134:135], v[134:135], 2, s[28:29]
	v_lshl_add_u64 v[132:133], v[132:133], 0, v[130:131]
	v_lshl_add_u64 v[130:131], v[134:135], 0, v[130:131]
	v_and_b32_e32 v135, 31, v1
	v_lshlrev_b32_e32 v1, 7, v1
	v_lshlrev_b32_e32 v136, 2, v135
	v_mov_b32_e32 v137, v0
	v_and_or_b32 v134, v1, s11, v135
	v_lshl_add_u64 v[136:137], v[130:131], 0, v[136:137]
	v_mov_b32_e32 v135, v0
	v_lshl_add_u64 v[130:131], v[134:135], 2, v[132:133]
	v_add_co_u32_e32 v132, vcc, s12, v136
	s_waitcnt vmcnt(0)
	v_lshl_add_u64 v[144:145], v[136:137], 0, s[2:3]
	v_addc_co_u32_e32 v133, vcc, 0, v137, vcc
	global_load_dword v1, v[132:133], off
	global_load_dword v184, v[130:131], off nt
	v_add_co_u32_e32 v132, vcc, s13, v130
	s_add_i32 s85, s85, s81
	s_nop 0
	v_addc_co_u32_e32 v133, vcc, 0, v131, vcc
	v_add_co_u32_e32 v134, vcc, s14, v130
	s_cmpk_gt_i32 s85, 0xff
	s_nop 0
	v_addc_co_u32_e32 v135, vcc, 0, v131, vcc
	v_add_co_u32_e32 v136, vcc, s15, v130
	s_waitcnt vmcnt(0)
	v_fmac_f32_e32 v184, v114, v1
	v_addc_co_u32_e32 v137, vcc, 0, v131, vcc
	v_add_co_u32_e32 v138, vcc, s17, v130
	s_nop 1
	v_addc_co_u32_e32 v139, vcc, 0, v131, vcc
	v_add_co_u32_e32 v140, vcc, s23, v130
	s_nop 1
	v_addc_co_u32_e32 v141, vcc, 0, v131, vcc
	v_add_co_u32_e32 v142, vcc, s24, v130
	s_nop 1
	v_addc_co_u32_e32 v143, vcc, 0, v131, vcc
	v_add_co_u32_e32 v154, vcc, s16, v130
	global_load_dword v185, v[134:135], off offset:-4096 nt
	global_load_dword v194, v[134:135], off nt
	global_load_dword v195, v[138:139], off offset:-4096 nt
	global_load_dword v196, v[138:139], off nt
	global_load_dword v197, v[140:141], off offset:-4096 nt
	global_load_dword v198, v[140:141], off nt
	global_load_dword v199, v[142:143], off offset:-4096 nt
	global_load_dword v200, v[136:137], off nt
	v_addc_co_u32_e32 v155, vcc, 0, v131, vcc
	v_add_co_u32_e32 v146, vcc, s30, v130
	s_waitcnt vmcnt(7)
	v_fmac_f32_e32 v185, v115, v1
	v_addc_co_u32_e32 v147, vcc, 0, v131, vcc
	v_add_co_u32_e32 v148, vcc, s34, v130
	s_waitcnt vmcnt(6)
	v_fmac_f32_e32 v194, v116, v1
	v_addc_co_u32_e32 v149, vcc, 0, v131, vcc
	v_add_co_u32_e32 v150, vcc, s36, v130
	s_waitcnt vmcnt(0)
	v_fmac_f32_e32 v200, v117, v1
	v_addc_co_u32_e32 v151, vcc, 0, v131, vcc
	v_add_co_u32_e32 v152, vcc, s38, v130
	v_fmac_f32_e32 v195, v118, v1
	s_nop 0
	v_addc_co_u32_e32 v153, vcc, 0, v131, vcc
	global_load_dword v201, v[142:143], off nt
	global_load_dword v202, v[146:147], off offset:-4096 nt
	global_load_dword v203, v[146:147], off nt
	global_load_dword v204, v[148:149], off offset:-4096 nt
	global_load_dword v205, v[148:149], off nt
	global_load_dword v206, v[150:151], off offset:-4096 nt
	global_load_dword v207, v[150:151], off nt
	global_load_dword v208, v[152:153], off offset:-4096 nt
	v_add_co_u32_e32 v156, vcc, s40, v130
	v_fmac_f32_e32 v196, v119, v1
	s_nop 0
	v_addc_co_u32_e32 v157, vcc, 0, v131, vcc
	v_add_co_u32_e32 v158, vcc, s42, v130
	v_fmac_f32_e32 v197, v120, v1
	s_nop 0
	v_addc_co_u32_e32 v159, vcc, 0, v131, vcc
	v_add_co_u32_e32 v160, vcc, s44, v130
	v_fmac_f32_e32 v198, v121, v1
	s_nop 0
	v_addc_co_u32_e32 v161, vcc, 0, v131, vcc
	v_add_co_u32_e32 v162, vcc, s46, v130
	v_fmac_f32_e32 v199, v122, v1
	s_nop 0
	v_addc_co_u32_e32 v163, vcc, 0, v131, vcc
	global_load_dword v209, v[152:153], off nt
	global_load_dword v210, v[156:157], off offset:-4096 nt
	global_load_dword v211, v[156:157], off nt
	global_load_dword v212, v[158:159], off offset:-4096 nt
	global_load_dword v213, v[158:159], off nt
	global_load_dword v214, v[160:161], off offset:-4096 nt
	global_load_dword v215, v[160:161], off nt
	global_load_dword v218, v[162:163], off offset:-4096 nt
	v_add_co_u32_e32 v164, vcc, s52, v130
	s_waitcnt vmcnt(15)
	v_fmac_f32_e32 v201, v123, v1
	v_addc_co_u32_e32 v165, vcc, 0, v131, vcc
	v_add_co_u32_e32 v166, vcc, s54, v130
	global_load_dword v219, v[162:163], off nt
	global_load_dword v220, v[164:165], off offset:-4096 nt
	global_load_dword v221, v[164:165], off nt
	v_addc_co_u32_e32 v167, vcc, 0, v131, vcc
	v_add_co_u32_e32 v168, vcc, s56, v130
	s_waitcnt vmcnt(11)
	v_fmac_f32_e32 v208, v98, v1
	v_addc_co_u32_e32 v169, vcc, 0, v131, vcc
	global_load_dword v222, v[166:167], off offset:-4096 nt
	global_load_dword v223, v[166:167], off nt
	global_load_dword v224, v[168:169], off offset:-4096 nt
	global_load_dword v225, v[168:169], off nt
	v_add_co_u32_e32 v182, vcc, s22, v130
	v_fmac_f32_e32 v202, v124, v1
	s_nop 0
	v_addc_co_u32_e32 v183, vcc, 0, v131, vcc
	v_add_co_u32_e32 v176, vcc, s10, v130
	s_waitcnt vmcnt(14)
	v_fmac_f32_e32 v209, v99, v1
	v_addc_co_u32_e32 v177, vcc, 0, v131, vcc
	v_add_co_u32_e32 v174, vcc, s25, v130
	s_waitcnt vmcnt(13)
	v_fmac_f32_e32 v210, v100, v1
	v_addc_co_u32_e32 v175, vcc, 0, v131, vcc
	v_add_co_u32_e32 v172, vcc, s31, v130
	s_waitcnt vmcnt(12)
; DI int cu(int r) { return (r & 3) + 8 * (r >> 2); }
;     template <int NI> DI void operator()(const f32x16 (&acc)[2][NI], int row0, int col0, int lane) const {
;     ...
;         for (int ni = 0; ni < NI; ++ni) {
;             const float gv = (g + 32 * ni)[l31];
;             float sv[32];
; #pragma unroll
;             for (int q = 0; q < 32; ++q) sv[q] = __builtin_nontemporal_load(&(src + (32 * (q >> 4) + cu(q & 15)) * DM + 32 * ni)[lo]);
; #pragma unroll
;             for (int q = 0; q < 32; ++q) (dst + (32 * (q >> 4) + cu(q & 15)) * DM + 32 * ni)[lo] = sv[q] + gv * acc[q >> 4][ni][q & 15];
;             asm volatile("" ::: "memory");
;         }
	v_fmac_f32_e32 v211, v101, v1
	v_addc_co_u32_e32 v173, vcc, 0, v131, vcc
	v_add_co_u32_e32 v170, vcc, s35, v130
	s_waitcnt vmcnt(11)
	v_fmac_f32_e32 v212, v102, v1
	v_addc_co_u32_e32 v171, vcc, 0, v131, vcc
	v_add_co_u32_e32 v98, vcc, s37, v130
	s_waitcnt vmcnt(10)
	v_fmac_f32_e32 v213, v103, v1
	v_addc_co_u32_e32 v99, vcc, 0, v131, vcc
	v_add_co_u32_e32 v100, vcc, s39, v130
	s_waitcnt vmcnt(9)
	v_fmac_f32_e32 v214, v104, v1
	v_addc_co_u32_e32 v101, vcc, 0, v131, vcc
	v_add_co_u32_e32 v102, vcc, s41, v130
	s_waitcnt vmcnt(8)
	v_fmac_f32_e32 v215, v105, v1
	v_addc_co_u32_e32 v103, vcc, 0, v131, vcc
	v_add_co_u32_e32 v104, vcc, s43, v130
	s_waitcnt vmcnt(7)
	v_fmac_f32_e32 v218, v106, v1
	v_addc_co_u32_e32 v105, vcc, 0, v131, vcc
	v_add_co_u32_e32 v106, vcc, s45, v130
	v_fmac_f32_e32 v203, v125, v1
	v_fmac_f32_e32 v204, v126, v1
	v_fmac_f32_e32 v205, v127, v1
	v_fmac_f32_e32 v206, v128, v1
	v_fmac_f32_e32 v207, v129, v1
	global_store_dword v[130:131], v184, off
	global_store_dword v[134:135], v185, off offset:-4096
	global_store_dword v[134:135], v194, off
	global_store_dword v[136:137], v200, off
	global_store_dword v[138:139], v195, off offset:-4096
	global_store_dword v[138:139], v196, off
	global_store_dword v[140:141], v197, off offset:-4096
	global_store_dword v[140:141], v198, off
	global_store_dword v[142:143], v199, off offset:-4096
	global_store_dword v[142:143], v201, off
	global_store_dword v[146:147], v202, off offset:-4096
	global_store_dword v[146:147], v203, off
	global_store_dword v[148:149], v204, off offset:-4096
	global_store_dword v[148:149], v205, off
	global_store_dword v[150:151], v206, off offset:-4096
	global_store_dword v[150:151], v207, off
	global_store_dword v[152:153], v208, off offset:-4096
	s_waitcnt vmcnt(23)
	v_fmac_f32_e32 v219, v107, v1
	v_addc_co_u32_e32 v107, vcc, 0, v131, vcc
	s_waitcnt vmcnt(22)
	v_fmac_f32_e32 v220, v108, v1
	v_add_co_u32_e32 v108, vcc, s47, v130
	s_waitcnt vmcnt(21)
	v_fmac_f32_e32 v221, v109, v1
	v_addc_co_u32_e32 v109, vcc, 0, v131, vcc
	s_waitcnt vmcnt(20)
	v_fmac_f32_e32 v222, v110, v1
	v_add_co_u32_e32 v110, vcc, s53, v130
	s_waitcnt vmcnt(19)
	v_fmac_f32_e32 v223, v111, v1
	s_waitcnt vmcnt(18)
	v_fmac_f32_e32 v224, v112, v1
	s_waitcnt vmcnt(17)
	v_fmac_f32_e32 v225, v113, v1
	v_addc_co_u32_e32 v111, vcc, 0, v131, vcc
	global_store_dword v[152:153], v209, off
	global_store_dword v[156:157], v210, off offset:-4096
	global_store_dword v[156:157], v211, off
	global_store_dword v[158:159], v212, off offset:-4096
	global_store_dword v[158:159], v213, off
	global_store_dword v[160:161], v214, off offset:-4096
	global_store_dword v[160:161], v215, off
	global_store_dword v[162:163], v218, off offset:-4096
	global_store_dword v[162:163], v219, off
	global_store_dword v[164:165], v220, off offset:-4096
	global_store_dword v[164:165], v221, off
	global_store_dword v[166:167], v222, off offset:-4096
	global_store_dword v[166:167], v223, off
	global_store_dword v[168:169], v224, off offset:-4096
	global_store_dword v[168:169], v225, off
	v_add_co_u32_e32 v112, vcc, s55, v130
	global_load_dword v1, v[144:145], off offset:128
	global_load_dword v114, v[130:131], off offset:128 nt
	global_load_dword v115, v[132:133], off offset:128 nt
	v_addc_co_u32_e32 v113, vcc, 0, v131, vcc
	global_load_dword v116, v[134:135], off offset:128 nt
	global_load_dword v117, v[136:137], off offset:128 nt
	global_load_dword v118, v[154:155], off offset:128 nt
	global_load_dword v119, v[138:139], off offset:128 nt
	global_load_dword v120, v[182:183], off offset:128 nt
	global_load_dword v121, v[176:177], off offset:128 nt
	global_load_dword v122, v[140:141], off offset:128 nt
	global_load_dword v123, v[142:143], off offset:128 nt
	global_load_dword v124, v[174:175], off offset:128 nt
	global_load_dword v125, v[172:173], off offset:128 nt
	global_load_dword v126, v[146:147], off offset:128 nt
	global_load_dword v127, v[148:149], off offset:128 nt
	global_load_dword v128, v[170:171], off offset:128 nt
	global_load_dword v129, v[150:151], off offset:128 nt
	global_load_dword v184, v[98:99], off offset:128 nt
	global_load_dword v185, v[152:153], off offset:128 nt
	global_load_dword v194, v[100:101], off offset:128 nt
	global_load_dword v195, v[102:103], off offset:128 nt
	global_load_dword v196, v[156:157], off offset:128 nt
	global_load_dword v197, v[158:159], off offset:128 nt
	global_load_dword v198, v[104:105], off offset:128 nt
	global_load_dword v199, v[106:107], off offset:128 nt
	global_load_dword v200, v[160:161], off offset:128 nt
	global_load_dword v201, v[162:163], off offset:128 nt
	global_load_dword v202, v[108:109], off offset:128 nt
	global_load_dword v203, v[110:111], off offset:128 nt
	global_load_dword v204, v[164:165], off offset:128 nt
	global_load_dword v205, v[166:167], off offset:128 nt
	global_load_dword v206, v[112:113], off offset:128 nt
	global_load_dword v207, v[168:169], off offset:128 nt
	s_waitcnt vmcnt(31)
	v_fmac_f32_e32 v114, v82, v1
	s_waitcnt vmcnt(30)
	v_fmac_f32_e32 v115, v83, v1
	s_waitcnt vmcnt(29)
	v_fmac_f32_e32 v116, v84, v1
	s_waitcnt vmcnt(28)
	v_fmac_f32_e32 v117, v85, v1
	s_waitcnt vmcnt(27)
	v_fmac_f32_e32 v118, v86, v1
	s_waitcnt vmcnt(26)
	v_fmac_f32_e32 v119, v87, v1
	s_waitcnt vmcnt(25)
	v_fmac_f32_e32 v120, v88, v1
	s_waitcnt vmcnt(23)
	v_fmac_f32_e32 v122, v89, v1
	v_fmac_f32_e32 v121, v90, v1
	s_waitcnt vmcnt(22)
	v_fmac_f32_e32 v123, v91, v1
	s_waitcnt vmcnt(21)
	v_fmac_f32_e32 v124, v92, v1
	s_waitcnt vmcnt(19)
	v_fmac_f32_e32 v126, v93, v1
	v_fmac_f32_e32 v125, v94, v1
	s_waitcnt vmcnt(18)
	v_fmac_f32_e32 v127, v95, v1
	s_waitcnt vmcnt(17)
; DI int cu(int r) { return (r & 3) + 8 * (r >> 2); }
;     template <int NI> DI void operator()(const f32x16 (&acc)[2][NI], int row0, int col0, int lane) const {
;     ...
;         const unsigned l31 = lane & 31, lo = (unsigned)(4 * (lane >> 5) * DM) + l31;
; #pragma unroll
;         for (int ni = 0; ni < NI; ++ni) {
;             const float gv = (g + 32 * ni)[l31];
;             float sv[32];
; #pragma unroll
;             for (int q = 0; q < 32; ++q) sv[q] = __builtin_nontemporal_load(&(src + (32 * (q >> 4) + cu(q & 15)) * DM + 32 * ni)[lo]);
; #pragma unroll
;             for (int q = 0; q < 32; ++q) (dst + (32 * (q >> 4) + cu(q & 15)) * DM + 32 * ni)[lo] = sv[q] + gv * acc[q >> 4][ni][q & 15];
;             asm volatile("" ::: "memory");
;         }
	v_fmac_f32_e32 v128, v96, v1
	s_waitcnt vmcnt(16)
	v_fmac_f32_e32 v129, v97, v1
	s_waitcnt vmcnt(15)
	v_fmac_f32_e32 v184, v66, v1
	s_waitcnt vmcnt(14)
	v_fmac_f32_e32 v185, v67, v1
	s_waitcnt vmcnt(13)
	v_fmac_f32_e32 v194, v68, v1
	s_waitcnt vmcnt(11)
	v_fmac_f32_e32 v196, v69, v1
	v_fmac_f32_e32 v195, v70, v1
	s_waitcnt vmcnt(10)
	v_fmac_f32_e32 v197, v71, v1
	s_waitcnt vmcnt(9)
	v_fmac_f32_e32 v198, v72, v1
	s_waitcnt vmcnt(7)
	v_fmac_f32_e32 v200, v73, v1
	v_fmac_f32_e32 v199, v74, v1
	s_waitcnt vmcnt(6)
	v_fmac_f32_e32 v201, v75, v1
	s_waitcnt vmcnt(5)
	v_fmac_f32_e32 v202, v76, v1
	s_waitcnt vmcnt(3)
	v_fmac_f32_e32 v204, v77, v1
	v_fmac_f32_e32 v203, v78, v1
	s_waitcnt vmcnt(2)
	v_fmac_f32_e32 v205, v79, v1
	s_waitcnt vmcnt(1)
	v_fmac_f32_e32 v206, v80, v1
	s_waitcnt vmcnt(0)
	v_fmac_f32_e32 v207, v81, v1
	global_store_dword v[130:131], v114, off offset:128
	global_store_dword v[132:133], v115, off offset:128
	global_store_dword v[134:135], v116, off offset:128
	global_store_dword v[136:137], v117, off offset:128
	global_store_dword v[154:155], v118, off offset:128
	global_store_dword v[138:139], v119, off offset:128
	global_store_dword v[182:183], v120, off offset:128
	global_store_dword v[140:141], v122, off offset:128
	global_store_dword v[176:177], v121, off offset:128
	global_store_dword v[142:143], v123, off offset:128
	global_store_dword v[174:175], v124, off offset:128
	global_store_dword v[146:147], v126, off offset:128
	global_store_dword v[172:173], v125, off offset:128
	global_store_dword v[148:149], v127, off offset:128
	global_store_dword v[170:171], v128, off offset:128
	global_store_dword v[150:151], v129, off offset:128
	global_store_dword v[98:99], v184, off offset:128
	global_store_dword v[152:153], v185, off offset:128
	global_store_dword v[100:101], v194, off offset:128
	global_store_dword v[156:157], v196, off offset:128
	global_store_dword v[102:103], v195, off offset:128
	global_store_dword v[158:159], v197, off offset:128
	global_store_dword v[104:105], v198, off offset:128
	global_store_dword v[160:161], v200, off offset:128
	global_store_dword v[106:107], v199, off offset:128
	global_store_dword v[162:163], v201, off offset:128
	global_store_dword v[108:109], v202, off offset:128
	global_store_dword v[164:165], v204, off offset:128
	global_store_dword v[110:111], v203, off offset:128
	global_store_dword v[166:167], v205, off offset:128
	global_store_dword v[112:113], v206, off offset:128
	global_store_dword v[168:169], v207, off offset:128
	global_load_dword v1, v[144:145], off offset:256
	global_load_dword v66, v[130:131], off offset:256 nt
	global_load_dword v67, v[132:133], off offset:256 nt
	global_load_dword v68, v[134:135], off offset:256 nt
	global_load_dword v69, v[136:137], off offset:256 nt
	global_load_dword v70, v[154:155], off offset:256 nt
	global_load_dword v71, v[138:139], off offset:256 nt
	global_load_dword v72, v[182:183], off offset:256 nt
	global_load_dword v73, v[140:141], off offset:256 nt
	global_load_dword v74, v[176:177], off offset:256 nt
	global_load_dword v75, v[142:143], off offset:256 nt
	global_load_dword v76, v[174:175], off offset:256 nt
	global_load_dword v77, v[146:147], off offset:256 nt
	global_load_dword v78, v[172:173], off offset:256 nt
	global_load_dword v79, v[148:149], off offset:256 nt
	global_load_dword v80, v[170:171], off offset:256 nt
	global_load_dword v81, v[150:151], off offset:256 nt
	global_load_dword v82, v[98:99], off offset:256 nt
	global_load_dword v83, v[152:153], off offset:256 nt
	global_load_dword v84, v[100:101], off offset:256 nt
	global_load_dword v85, v[156:157], off offset:256 nt
	global_load_dword v86, v[102:103], off offset:256 nt
	global_load_dword v87, v[158:159], off offset:256 nt
	global_load_dword v88, v[104:105], off offset:256 nt
	global_load_dword v89, v[160:161], off offset:256 nt
	global_load_dword v90, v[106:107], off offset:256 nt
	global_load_dword v91, v[162:163], off offset:256 nt
	global_load_dword v92, v[108:109], off offset:256 nt
	global_load_dword v93, v[164:165], off offset:256 nt
	global_load_dword v94, v[110:111], off offset:256 nt
	global_load_dword v95, v[166:167], off offset:256 nt
	global_load_dword v96, v[112:113], off offset:256 nt
	global_load_dword v97, v[168:169], off offset:256 nt
	s_waitcnt vmcnt(31)
	v_fmac_f32_e32 v66, v50, v1
	s_waitcnt vmcnt(30)
	v_fmac_f32_e32 v67, v51, v1
	s_waitcnt vmcnt(29)
	v_fmac_f32_e32 v68, v52, v1
	s_waitcnt vmcnt(28)
	v_fmac_f32_e32 v69, v53, v1
	s_waitcnt vmcnt(27)
	v_fmac_f32_e32 v70, v54, v1
	s_waitcnt vmcnt(26)
	v_fmac_f32_e32 v71, v55, v1
	s_waitcnt vmcnt(25)
	v_fmac_f32_e32 v72, v56, v1
	s_waitcnt vmcnt(24)
	v_fmac_f32_e32 v73, v57, v1
	s_waitcnt vmcnt(23)
	v_fmac_f32_e32 v74, v58, v1
	s_waitcnt vmcnt(22)
	v_fmac_f32_e32 v75, v59, v1
	s_waitcnt vmcnt(21)
	v_fmac_f32_e32 v76, v60, v1
	s_waitcnt vmcnt(20)
	v_fmac_f32_e32 v77, v61, v1
	s_waitcnt vmcnt(19)
	v_fmac_f32_e32 v78, v62, v1
	s_waitcnt vmcnt(18)
	v_fmac_f32_e32 v79, v63, v1
	s_waitcnt vmcnt(17)
	v_fmac_f32_e32 v80, v64, v1
	s_waitcnt vmcnt(16)
	v_fmac_f32_e32 v81, v65, v1
	s_waitcnt vmcnt(15)
	v_fmac_f32_e32 v82, v34, v1
	s_waitcnt vmcnt(14)
	v_fmac_f32_e32 v83, v35, v1
	s_waitcnt vmcnt(13)
	v_fmac_f32_e32 v84, v36, v1
	s_waitcnt vmcnt(12)
	v_fmac_f32_e32 v85, v37, v1
	s_waitcnt vmcnt(11)
	v_fmac_f32_e32 v86, v38, v1
	s_waitcnt vmcnt(10)
	v_fmac_f32_e32 v87, v39, v1
	s_waitcnt vmcnt(9)
	v_fmac_f32_e32 v88, v40, v1
	s_waitcnt vmcnt(8)
	v_fmac_f32_e32 v89, v41, v1
	s_waitcnt vmcnt(7)
	v_fmac_f32_e32 v90, v42, v1
	s_waitcnt vmcnt(6)
	v_fmac_f32_e32 v91, v43, v1
	s_waitcnt vmcnt(5)
	v_fmac_f32_e32 v92, v44, v1
	s_waitcnt vmcnt(4)
; DI int cu(int r) { return (r & 3) + 8 * (r >> 2); }
;     template <int NI> DI void operator()(const f32x16 (&acc)[2][NI], int row0, int col0, int lane) const {
;     ...
;         const unsigned l31 = lane & 31, lo = (unsigned)(4 * (lane >> 5) * DM) + l31;
; #pragma unroll
;         for (int ni = 0; ni < NI; ++ni) {
;             const float gv = (g + 32 * ni)[l31];
;             float sv[32];
; #pragma unroll
;             for (int q = 0; q < 32; ++q) sv[q] = __builtin_nontemporal_load(&(src + (32 * (q >> 4) + cu(q & 15)) * DM + 32 * ni)[lo]);
; #pragma unroll
;             for (int q = 0; q < 32; ++q) (dst + (32 * (q >> 4) + cu(q & 15)) * DM + 32 * ni)[lo] = sv[q] + gv * acc[q >> 4][ni][q & 15];
;             asm volatile("" ::: "memory");
;         }
	v_fmac_f32_e32 v93, v45, v1
	s_waitcnt vmcnt(3)
	v_fmac_f32_e32 v94, v46, v1
	s_waitcnt vmcnt(2)
	v_fmac_f32_e32 v95, v47, v1
	s_waitcnt vmcnt(1)
	v_fmac_f32_e32 v96, v48, v1
	s_waitcnt vmcnt(0)
	v_fmac_f32_e32 v97, v49, v1
	global_store_dword v[130:131], v66, off offset:256
	global_store_dword v[132:133], v67, off offset:256
	global_store_dword v[134:135], v68, off offset:256
	global_store_dword v[136:137], v69, off offset:256
	global_store_dword v[154:155], v70, off offset:256
	global_store_dword v[138:139], v71, off offset:256
	global_store_dword v[182:183], v72, off offset:256
	global_store_dword v[140:141], v73, off offset:256
	global_store_dword v[176:177], v74, off offset:256
	global_store_dword v[142:143], v75, off offset:256
	global_store_dword v[174:175], v76, off offset:256
	global_store_dword v[146:147], v77, off offset:256
	global_store_dword v[172:173], v78, off offset:256
	global_store_dword v[148:149], v79, off offset:256
	global_store_dword v[170:171], v80, off offset:256
	global_store_dword v[150:151], v81, off offset:256
	global_store_dword v[98:99], v82, off offset:256
	global_store_dword v[152:153], v83, off offset:256
	global_store_dword v[100:101], v84, off offset:256
	global_store_dword v[156:157], v85, off offset:256
	global_store_dword v[102:103], v86, off offset:256
	global_store_dword v[158:159], v87, off offset:256
	global_store_dword v[104:105], v88, off offset:256
	global_store_dword v[160:161], v89, off offset:256
	global_store_dword v[106:107], v90, off offset:256
	global_store_dword v[162:163], v91, off offset:256
	global_store_dword v[108:109], v92, off offset:256
	global_store_dword v[164:165], v93, off offset:256
	global_store_dword v[110:111], v94, off offset:256
	global_store_dword v[166:167], v95, off offset:256
	global_store_dword v[112:113], v96, off offset:256
	global_store_dword v[168:169], v97, off offset:256
	global_load_dword v1, v[144:145], off offset:384
	global_load_dword v34, v[130:131], off offset:384 nt
	global_load_dword v35, v[132:133], off offset:384 nt
	global_load_dword v36, v[134:135], off offset:384 nt
	global_load_dword v37, v[136:137], off offset:384 nt
	global_load_dword v38, v[154:155], off offset:384 nt
	global_load_dword v39, v[138:139], off offset:384 nt
	global_load_dword v40, v[182:183], off offset:384 nt
	global_load_dword v41, v[140:141], off offset:384 nt
	global_load_dword v42, v[176:177], off offset:384 nt
	global_load_dword v43, v[142:143], off offset:384 nt
	global_load_dword v44, v[174:175], off offset:384 nt
	global_load_dword v45, v[146:147], off offset:384 nt
	global_load_dword v46, v[172:173], off offset:384 nt
	global_load_dword v47, v[148:149], off offset:384 nt
	global_load_dword v48, v[170:171], off offset:384 nt
	global_load_dword v49, v[150:151], off offset:384 nt
	global_load_dword v50, v[98:99], off offset:384 nt
	global_load_dword v51, v[152:153], off offset:384 nt
	global_load_dword v52, v[100:101], off offset:384 nt
	global_load_dword v53, v[156:157], off offset:384 nt
	global_load_dword v54, v[102:103], off offset:384 nt
	global_load_dword v55, v[158:159], off offset:384 nt
	global_load_dword v56, v[104:105], off offset:384 nt
	global_load_dword v57, v[160:161], off offset:384 nt
	global_load_dword v58, v[106:107], off offset:384 nt
	global_load_dword v59, v[162:163], off offset:384 nt
	global_load_dword v60, v[108:109], off offset:384 nt
	global_load_dword v61, v[164:165], off offset:384 nt
	global_load_dword v62, v[110:111], off offset:384 nt
	global_load_dword v63, v[166:167], off offset:384 nt
	global_load_dword v64, v[112:113], off offset:384 nt
	global_load_dword v65, v[168:169], off offset:384 nt
	s_waitcnt vmcnt(31)
	v_fmac_f32_e32 v34, v18, v1
	s_waitcnt vmcnt(30)
	v_fmac_f32_e32 v35, v19, v1
	s_waitcnt vmcnt(29)
	v_fmac_f32_e32 v36, v20, v1
	s_waitcnt vmcnt(28)
	v_fmac_f32_e32 v37, v21, v1
	s_waitcnt vmcnt(27)
	v_fmac_f32_e32 v38, v22, v1
	s_waitcnt vmcnt(26)
	v_fmac_f32_e32 v39, v23, v1
	s_waitcnt vmcnt(25)
	v_fmac_f32_e32 v40, v24, v1
	s_waitcnt vmcnt(24)
	v_fmac_f32_e32 v41, v25, v1
	s_waitcnt vmcnt(23)
	v_fmac_f32_e32 v42, v26, v1
	s_waitcnt vmcnt(22)
	v_fmac_f32_e32 v43, v27, v1
	s_waitcnt vmcnt(21)
	v_fmac_f32_e32 v44, v28, v1
	s_waitcnt vmcnt(20)
	v_fmac_f32_e32 v45, v29, v1
	s_waitcnt vmcnt(19)
	v_fmac_f32_e32 v46, v30, v1
	s_waitcnt vmcnt(18)
	v_fmac_f32_e32 v47, v31, v1
	s_waitcnt vmcnt(17)
	v_fmac_f32_e32 v48, v32, v1
	s_waitcnt vmcnt(16)
	v_fmac_f32_e32 v49, v33, v1
	s_waitcnt vmcnt(15)
	v_fmac_f32_e32 v50, v2, v1
	s_waitcnt vmcnt(14)
	v_fmac_f32_e32 v51, v3, v1
	s_waitcnt vmcnt(13)
	v_fmac_f32_e32 v52, v4, v1
	s_waitcnt vmcnt(12)
	v_fmac_f32_e32 v53, v5, v1
	s_waitcnt vmcnt(11)
	v_fmac_f32_e32 v54, v6, v1
	s_waitcnt vmcnt(10)
	v_fmac_f32_e32 v55, v7, v1
	s_waitcnt vmcnt(9)
	v_fmac_f32_e32 v56, v8, v1
	s_waitcnt vmcnt(8)
	v_fmac_f32_e32 v57, v9, v1
	s_waitcnt vmcnt(7)
	v_fmac_f32_e32 v58, v10, v1
	s_waitcnt vmcnt(6)
	v_fmac_f32_e32 v59, v11, v1
	s_waitcnt vmcnt(5)
	v_fmac_f32_e32 v60, v12, v1
	s_waitcnt vmcnt(4)
	v_fmac_f32_e32 v61, v13, v1
	s_waitcnt vmcnt(3)
	v_fmac_f32_e32 v62, v14, v1
	s_waitcnt vmcnt(2)
	v_fmac_f32_e32 v63, v15, v1
	s_waitcnt vmcnt(1)
	v_fmac_f32_e32 v64, v16, v1
	s_waitcnt vmcnt(0)
	v_fmac_f32_e32 v65, v17, v1
	global_store_dword v[130:131], v34, off offset:384
	global_store_dword v[132:133], v35, off offset:384
	global_store_dword v[134:135], v36, off offset:384
	global_store_dword v[136:137], v37, off offset:384
	global_store_dword v[154:155], v38, off offset:384
	global_store_dword v[138:139], v39, off offset:384
	global_store_dword v[182:183], v40, off offset:384
	global_store_dword v[140:141], v41, off offset:384
	global_store_dword v[176:177], v42, off offset:384
	global_store_dword v[142:143], v43, off offset:384
	global_store_dword v[174:175], v44, off offset:384
	global_store_dword v[146:147], v45, off offset:384
	global_store_dword v[172:173], v46, off offset:384
	global_store_dword v[148:149], v47, off offset:384
	global_store_dword v[170:171], v48, off offset:384
	global_store_dword v[150:151], v49, off offset:384
	global_store_dword v[98:99], v50, off offset:384
	global_store_dword v[152:153], v51, off offset:384
	global_store_dword v[100:101], v52, off offset:384
	global_store_dword v[156:157], v53, off offset:384
	global_store_dword v[102:103], v54, off offset:384
	global_store_dword v[158:159], v55, off offset:384
	global_store_dword v[104:105], v56, off offset:384
	global_store_dword v[160:161], v57, off offset:384
	global_store_dword v[106:107], v58, off offset:384
	global_store_dword v[162:163], v59, off offset:384
	global_store_dword v[108:109], v60, off offset:384
	global_store_dword v[164:165], v61, off offset:384
	global_store_dword v[110:111], v62, off offset:384
	global_store_dword v[166:167], v63, off offset:384
	global_store_dword v[112:113], v64, off offset:384
	global_store_dword v[168:169], v65, off offset:384
	s_cbranch_scc0 .LBB0_1383
